# v86 + K-loops: vmcnt(8)+lgkmcnt(0) wait pairs merged into one s_waitcnt; mid-segment s_setprio 0/1 flip removed
# speedup vs baseline: 1.0020x; 1.0020x over previous
; #define PG8_STAGE(bufoff, gbase, voff) do { _Pragma("unroll") for (int _i = 0; _i < 2; ++_i) \
;         __builtin_amdgcn_global_load_lds((const unsigned*)((const char*)(gbase) + (voff)[_i]), (PG8_LAS unsigned*)(lds + (bufoff) + ldsw + _i * 8192), 16, 0, 0); } while (0)
; #define PG8_LDA(dst, b, h) do { _Pragma("unroll") for (int m = 0; m < 4; ++m) _Pragma("unroll") for (int k = 0; k < 2; ++k) dst[m][k] = *(const PG8_LAS bf16x8*)(lds + PG8_SA(b, h) + aoff + m * 2048 + k * 1024); } while (0)
; #define PG8_LDB(dst, b, h) do { _Pragma("unroll") for (int n = 0; n < 2; ++n) _Pragma("unroll") for (int k = 0; k < 2; ++k) dst[n][k] = *(const PG8_LAS bf16x8*)(lds + PG8_SB(b, h) + boff + n * 2048 + k * 1024); } while (0)
; #define PG8_MMA(ai, bj, At, Bt) do { __builtin_amdgcn_s_setprio(1); _Pragma("unroll") for (int m = 0; m < 4; ++m) _Pragma("unroll") for (int n = 0; n < 2; ++n) _Pragma("unroll") for (int k = 0; k < 2; ++k) \
;         acc[ai][bj][m][n] = __builtin_amdgcn_mfma_f32_16x16x32_bf16(Bt[n][k], At[m][k], acc[ai][bj][m][n], 0, 0, 0); __builtin_amdgcn_s_setprio(0); } while (0)
; #define PG8_WAIT_V(n) asm volatile("s_waitcnt vmcnt(" #n ")" ::: "memory")
; #define PG8_WAIT_L(n) asm volatile("s_waitcnt lgkmcnt(" #n ")" ::: "memory")
; #define PG8_BAR __builtin_amdgcn_s_barrier()
; #define PG8_SCHED __builtin_amdgcn_sched_barrier(0)
;     ...
;             const bool last = (t == nt - 2);
;             const char* a1 = cA + (size_t)(t + 1) * kstep;
;             const char* a2 = last ? nA : cA + (size_t)(t + 2) * kstep; const char* b2 = last ? nB : cB + (size_t)(t + 2) * kstep;
;             const char* a3 = a2 + kstep; const char* b3 = b2 + kstep;
;             if (last && has_next) S.a_ready(nxt);
;             if (t == 0) E.pre_issue(pre, cur, tid, ui); else if (t == 2) E.pre_finish(pre, tid, ui);
;             if constexpr (SP2) {
;             PG8_LDB(B0, 0, 0); PG8_LDB(B1, 0, 1); PG8_SCHED; PG8_LDA(At, 0, 0); PG8_STAGE(PG8_SA(1, 1), a1 + hstep, voffA);
;             PG8_WAIT_V(8); PG8_WAIT_L(0); PG8_BAR; PG8_MMA(0, 0, At, B0); PG8_MMA(0, 1, At, B1); PG8_BAR; PG8_SCHED;
;             PG8_LDA(At, 0, 1); PG8_STAGE(PG8_SB(0, 0), b2, voffB); PG8_STAGE(PG8_SB(0, 1), b2 + hstep, voffB); PG8_STAGE(PG8_SA(0, 0), a2, voffA);
;             PG8_WAIT_V(8); PG8_WAIT_L(0); PG8_BAR; PG8_MMA(1, 0, At, B0); PG8_MMA(1, 1, At, B1); PG8_BAR; PG8_SCHED;
.LBB0_198:
	s_add_u32 s48, s60, 0xfff80080
	s_addc_u32 s49, s61, -1
	s_add_i32 s87, 0, 0x10000
	s_cmp_eq_u32 s86, 28
	s_cselect_b32 s69, s25, s49
	s_cselect_b32 s68, s81, s48
	s_cselect_b32 s63, s15, s85
	s_cselect_b32 s62, s83, s84
	s_add_i32 s48, 0, 0x14000
	ds_read_b128 v[142:145], v251
	ds_read_b128 v[146:149], v251 offset:1024
	ds_read_b128 v[150:153], v251 offset:2048
	ds_read_b128 v[158:161], v251 offset:3072
	ds_read_b128 v[162:165], v251 offset:16384
	ds_read_b128 v[166:169], v251 offset:17408
	ds_read_b128 v[170:173], v251 offset:18432
	ds_read_b128 v[174:177], v251 offset:19456
	v_lshl_add_u64 v[198:199], s[60:61], 0, v[138:139]
	s_add_i32 m0, s20, 0xc000
	ds_read_b128 v[178:181], v156
	ds_read_b128 v[182:185], v156 offset:1024
	ds_read_b128 v[186:189], v156 offset:2048
	ds_read_b128 v[190:193], v156 offset:3072
	ds_read_b128 v[194:197], v156 offset:4096
	ds_read_b128 v[210:213], v156 offset:5120
	ds_read_b128 v[214:217], v156 offset:6144
	ds_read_b128 v[218:221], v156 offset:7168
	global_load_lds_dwordx4 v[198:199], off
	v_lshl_add_u64 v[198:199], s[60:61], 0, v[140:141]
	s_add_i32 m0, s20, 0xe000
	s_nop 0
	global_load_lds_dwordx4 v[198:199], off
	s_waitcnt vmcnt(8) lgkmcnt(0)
	s_setprio 1
	s_barrier
	v_mfma_f32_16x16x32_bf16 v[128:131], v[142:145], v[178:181], v[128:131]
	v_mfma_f32_16x16x32_bf16 v[124:127], v[150:153], v[178:181], v[124:127]
	v_mfma_f32_16x16x32_bf16 v[112:115], v[142:145], v[186:189], v[112:115]
	v_mfma_f32_16x16x32_bf16 v[108:111], v[150:153], v[186:189], v[108:111]
	v_mfma_f32_16x16x32_bf16 v[96:99], v[142:145], v[194:197], v[96:99]
	v_mfma_f32_16x16x32_bf16 v[92:95], v[150:153], v[194:197], v[92:95]
	v_mfma_f32_16x16x32_bf16 v[80:83], v[142:145], v[214:217], v[80:83]
	v_mfma_f32_16x16x32_bf16 v[76:79], v[150:153], v[214:217], v[76:79]
	v_mfma_f32_16x16x32_bf16 v[128:131], v[146:149], v[182:185], v[128:131]
	v_mfma_f32_16x16x32_bf16 v[124:127], v[158:161], v[182:185], v[124:127]
	v_mfma_f32_16x16x32_bf16 v[112:115], v[146:149], v[190:193], v[112:115]
	v_mfma_f32_16x16x32_bf16 v[108:111], v[158:161], v[190:193], v[108:111]
	v_mfma_f32_16x16x32_bf16 v[96:99], v[146:149], v[210:213], v[96:99]
	v_mfma_f32_16x16x32_bf16 v[92:95], v[158:161], v[210:213], v[92:95]
	v_mfma_f32_16x16x32_bf16 v[80:83], v[146:149], v[218:221], v[80:83]
	v_mfma_f32_16x16x32_bf16 v[76:79], v[158:161], v[218:221], v[76:79]
	v_mfma_f32_16x16x32_bf16 v[120:123], v[162:165], v[178:181], v[120:123]
	v_mfma_f32_16x16x32_bf16 v[116:119], v[170:173], v[178:181], v[116:119]
	v_mfma_f32_16x16x32_bf16 v[104:107], v[162:165], v[186:189], v[104:107]
	v_mfma_f32_16x16x32_bf16 v[100:103], v[170:173], v[186:189], v[100:103]
	v_mfma_f32_16x16x32_bf16 v[88:91], v[162:165], v[194:197], v[88:91]
	v_mfma_f32_16x16x32_bf16 v[84:87], v[170:173], v[194:197], v[84:87]
	v_mfma_f32_16x16x32_bf16 v[72:75], v[162:165], v[214:217], v[72:75]
	v_mfma_f32_16x16x32_bf16 v[68:71], v[170:173], v[214:217], v[68:71]
	v_mfma_f32_16x16x32_bf16 v[120:123], v[166:169], v[182:185], v[120:123]
	v_mfma_f32_16x16x32_bf16 v[116:119], v[174:177], v[182:185], v[116:119]
	v_mfma_f32_16x16x32_bf16 v[104:107], v[166:169], v[190:193], v[104:107]
	v_mfma_f32_16x16x32_bf16 v[100:103], v[174:177], v[190:193], v[100:103]
	v_mfma_f32_16x16x32_bf16 v[88:91], v[166:169], v[210:213], v[88:91]
	v_mfma_f32_16x16x32_bf16 v[84:87], v[174:177], v[210:213], v[84:87]
	v_mfma_f32_16x16x32_bf16 v[72:75], v[166:169], v[218:221], v[72:75]
	v_mfma_f32_16x16x32_bf16 v[68:71], v[174:177], v[218:221], v[68:71]
	s_barrier
	s_setprio 0
	s_add_i32 s49, s87, s1
	v_lshl_add_u64 v[198:199], s[62:63], 0, v[200:201]
	s_mov_b32 m0, s49
	ds_read_b128 v[178:181], v156 offset:16384
	ds_read_b128 v[182:185], v156 offset:17408
	ds_read_b128 v[186:189], v156 offset:18432
	ds_read_b128 v[190:193], v156 offset:19456
	ds_read_b128 v[194:197], v156 offset:20480
	ds_read_b128 v[210:213], v156 offset:21504
	ds_read_b128 v[214:217], v156 offset:22528
	ds_read_b128 v[218:221], v156 offset:23552
	global_load_lds_dwordx4 v[198:199], off
	s_add_i32 m0, s49, 0x2000
	s_add_u32 s88, s62, 0x80000
	v_lshl_add_u64 v[206:207], s[62:63], 0, v[132:133]
	s_addc_u32 s89, s63, 0
	s_add_i32 s48, s48, s1
	global_load_lds_dwordx4 v[206:207], off
	v_lshl_add_u64 v[208:209], s[88:89], 0, v[200:201]
	s_mov_b32 m0, s48
	v_lshl_add_u64 v[222:223], s[68:69], 0, v[134:135]
	global_load_lds_dwordx4 v[208:209], off
	v_lshl_add_u64 v[208:209], s[88:89], 0, v[132:133]
	s_add_i32 m0, s48, 0x2000
	s_nop 0
	global_load_lds_dwordx4 v[208:209], off
	v_lshl_add_u64 v[208:209], s[68:69], 0, v[136:137]
	s_mov_b32 m0, s20
	s_nop 0
	global_load_lds_dwordx4 v[208:209], off
	s_mov_b32 m0, s21
	s_nop 0
	global_load_lds_dwordx4 v[222:223], off
	s_waitcnt vmcnt(8) lgkmcnt(0)
	s_setprio 1
	s_barrier
; #define PG8_STAGE(bufoff, gbase, voff) do { _Pragma("unroll") for (int _i = 0; _i < 2; ++_i) \
;         __builtin_amdgcn_global_load_lds((const unsigned*)((const char*)(gbase) + (voff)[_i]), (PG8_LAS unsigned*)(lds + (bufoff) + ldsw + _i * 8192), 16, 0, 0); } while (0)
; #define PG8_LDA(dst, b, h) do { _Pragma("unroll") for (int m = 0; m < 4; ++m) _Pragma("unroll") for (int k = 0; k < 2; ++k) dst[m][k] = *(const PG8_LAS bf16x8*)(lds + PG8_SA(b, h) + aoff + m * 2048 + k * 1024); } while (0)
; #define PG8_LDB(dst, b, h) do { _Pragma("unroll") for (int n = 0; n < 2; ++n) _Pragma("unroll") for (int k = 0; k < 2; ++k) dst[n][k] = *(const PG8_LAS bf16x8*)(lds + PG8_SB(b, h) + boff + n * 2048 + k * 1024); } while (0)
; #define PG8_MMA(ai, bj, At, Bt) do { __builtin_amdgcn_s_setprio(1); _Pragma("unroll") for (int m = 0; m < 4; ++m) _Pragma("unroll") for (int n = 0; n < 2; ++n) _Pragma("unroll") for (int k = 0; k < 2; ++k) \
;         acc[ai][bj][m][n] = __builtin_amdgcn_mfma_f32_16x16x32_bf16(Bt[n][k], At[m][k], acc[ai][bj][m][n], 0, 0, 0); __builtin_amdgcn_s_setprio(0); } while (0)
; #define PG8_WAIT_V(n) asm volatile("s_waitcnt vmcnt(" #n ")" ::: "memory")
; #define PG8_WAIT_L(n) asm volatile("s_waitcnt lgkmcnt(" #n ")" ::: "memory")
; #define PG8_BAR __builtin_amdgcn_s_barrier()
; #define PG8_SCHED __builtin_amdgcn_sched_barrier(0)
;     ...
;             PG8_WAIT_V(8); PG8_WAIT_L(0); PG8_BAR; PG8_MMA(1, 0, At, B0); PG8_MMA(1, 1, At, B1); PG8_BAR; PG8_SCHED;
;             PG8_LDB(B0, 1, 0); PG8_LDB(B1, 1, 1); PG8_SCHED; PG8_LDA(At, 1, 0); PG8_STAGE(PG8_SA(0, 1), a2 + hstep, voffA);
;             PG8_WAIT_V(8); PG8_WAIT_L(0); PG8_BAR; PG8_MMA(0, 0, At, B0); PG8_MMA(0, 1, At, B1); PG8_BAR; PG8_SCHED;
	v_mfma_f32_16x16x32_bf16 v[64:67], v[142:145], v[178:181], v[64:67]
	v_mfma_f32_16x16x32_bf16 v[60:63], v[150:153], v[178:181], v[60:63]
	v_mfma_f32_16x16x32_bf16 v[48:51], v[142:145], v[186:189], v[48:51]
	v_mfma_f32_16x16x32_bf16 v[44:47], v[150:153], v[186:189], v[44:47]
	v_mfma_f32_16x16x32_bf16 v[32:35], v[142:145], v[194:197], v[32:35]
	v_mfma_f32_16x16x32_bf16 v[28:31], v[150:153], v[194:197], v[28:31]
	v_mfma_f32_16x16x32_bf16 v[16:19], v[142:145], v[214:217], v[16:19]
	v_mfma_f32_16x16x32_bf16 v[12:15], v[150:153], v[214:217], v[12:15]
	v_mfma_f32_16x16x32_bf16 v[64:67], v[146:149], v[182:185], v[64:67]
	v_mfma_f32_16x16x32_bf16 v[60:63], v[158:161], v[182:185], v[60:63]
	v_mfma_f32_16x16x32_bf16 v[48:51], v[146:149], v[190:193], v[48:51]
	v_mfma_f32_16x16x32_bf16 v[44:47], v[158:161], v[190:193], v[44:47]
	v_mfma_f32_16x16x32_bf16 v[32:35], v[146:149], v[210:213], v[32:35]
	v_mfma_f32_16x16x32_bf16 v[28:31], v[158:161], v[210:213], v[28:31]
	v_mfma_f32_16x16x32_bf16 v[16:19], v[146:149], v[218:221], v[16:19]
	v_mfma_f32_16x16x32_bf16 v[12:15], v[158:161], v[218:221], v[12:15]
	v_mfma_f32_16x16x32_bf16 v[56:59], v[162:165], v[178:181], v[56:59]
	v_mfma_f32_16x16x32_bf16 v[52:55], v[170:173], v[178:181], v[52:55]
	v_mfma_f32_16x16x32_bf16 v[40:43], v[162:165], v[186:189], v[40:43]
	v_mfma_f32_16x16x32_bf16 v[36:39], v[170:173], v[186:189], v[36:39]
	v_mfma_f32_16x16x32_bf16 v[24:27], v[162:165], v[194:197], v[24:27]
	v_mfma_f32_16x16x32_bf16 v[20:23], v[170:173], v[194:197], v[20:23]
	v_mfma_f32_16x16x32_bf16 v[8:11], v[162:165], v[214:217], v[8:11]
	v_mfma_f32_16x16x32_bf16 v[4:7], v[170:173], v[214:217], v[4:7]
	v_mfma_f32_16x16x32_bf16 v[56:59], v[166:169], v[182:185], v[56:59]
	v_mfma_f32_16x16x32_bf16 v[52:55], v[174:177], v[182:185], v[52:55]
	v_mfma_f32_16x16x32_bf16 v[40:43], v[166:169], v[190:193], v[40:43]
	v_mfma_f32_16x16x32_bf16 v[36:39], v[174:177], v[190:193], v[36:39]
	v_mfma_f32_16x16x32_bf16 v[24:27], v[166:169], v[210:213], v[24:27]
	v_mfma_f32_16x16x32_bf16 v[20:23], v[174:177], v[210:213], v[20:23]
	v_mfma_f32_16x16x32_bf16 v[8:11], v[166:169], v[218:221], v[8:11]
	v_mfma_f32_16x16x32_bf16 v[4:7], v[174:177], v[218:221], v[4:7]
	s_barrier
	s_setprio 0
	s_add_i32 s48, 0, 0x18000
	s_add_i32 s49, 0, 0x1c000
	ds_read_b128 v[142:145], v251 offset:32768
	ds_read_b128 v[146:149], v251 offset:33792
	ds_read_b128 v[150:153], v251 offset:34816
	ds_read_b128 v[158:161], v251 offset:35840
	ds_read_b128 v[162:165], v251 offset:49152
	ds_read_b128 v[166:169], v251 offset:50176
	ds_read_b128 v[170:173], v251 offset:51200
	ds_read_b128 v[174:177], v251 offset:52224
	s_add_u32 s68, s68, 0x80000
	s_addc_u32 s69, s69, 0
	s_mov_b32 m0, s23
	v_lshl_add_u64 v[224:225], s[68:69], 0, v[136:137]
	ds_read_b128 v[178:181], v156 offset:32768
	ds_read_b128 v[182:185], v156 offset:33792
	ds_read_b128 v[186:189], v156 offset:34816
	ds_read_b128 v[190:193], v156 offset:35840
	ds_read_b128 v[194:197], v156 offset:36864
	ds_read_b128 v[210:213], v156 offset:37888
	ds_read_b128 v[214:217], v156 offset:38912
	ds_read_b128 v[218:221], v156 offset:39936
	global_load_lds_dwordx4 v[224:225], off
	v_lshl_add_u64 v[224:225], s[68:69], 0, v[134:135]
	s_mov_b32 m0, s42
	s_nop 0
	global_load_lds_dwordx4 v[224:225], off
	s_waitcnt vmcnt(8) lgkmcnt(0)
	s_setprio 1
	s_barrier
	v_mfma_f32_16x16x32_bf16 v[128:131], v[142:145], v[178:181], v[128:131]
	v_mfma_f32_16x16x32_bf16 v[124:127], v[150:153], v[178:181], v[124:127]
	v_mfma_f32_16x16x32_bf16 v[112:115], v[142:145], v[186:189], v[112:115]
	v_mfma_f32_16x16x32_bf16 v[108:111], v[150:153], v[186:189], v[108:111]
	v_mfma_f32_16x16x32_bf16 v[96:99], v[142:145], v[194:197], v[96:99]
	v_mfma_f32_16x16x32_bf16 v[92:95], v[150:153], v[194:197], v[92:95]
	v_mfma_f32_16x16x32_bf16 v[80:83], v[142:145], v[214:217], v[80:83]
	v_mfma_f32_16x16x32_bf16 v[76:79], v[150:153], v[214:217], v[76:79]
	v_mfma_f32_16x16x32_bf16 v[128:131], v[146:149], v[182:185], v[128:131]
	v_mfma_f32_16x16x32_bf16 v[124:127], v[158:161], v[182:185], v[124:127]
	v_mfma_f32_16x16x32_bf16 v[112:115], v[146:149], v[190:193], v[112:115]
	v_mfma_f32_16x16x32_bf16 v[108:111], v[158:161], v[190:193], v[108:111]
	v_mfma_f32_16x16x32_bf16 v[96:99], v[146:149], v[210:213], v[96:99]
	v_mfma_f32_16x16x32_bf16 v[92:95], v[158:161], v[210:213], v[92:95]
	v_mfma_f32_16x16x32_bf16 v[80:83], v[146:149], v[218:221], v[80:83]
	v_mfma_f32_16x16x32_bf16 v[76:79], v[158:161], v[218:221], v[76:79]
	v_mfma_f32_16x16x32_bf16 v[120:123], v[162:165], v[178:181], v[120:123]
	v_mfma_f32_16x16x32_bf16 v[116:119], v[170:173], v[178:181], v[116:119]
	v_mfma_f32_16x16x32_bf16 v[104:107], v[162:165], v[186:189], v[104:107]
	v_mfma_f32_16x16x32_bf16 v[100:103], v[170:173], v[186:189], v[100:103]
	v_mfma_f32_16x16x32_bf16 v[88:91], v[162:165], v[194:197], v[88:91]
	v_mfma_f32_16x16x32_bf16 v[84:87], v[170:173], v[194:197], v[84:87]
	v_mfma_f32_16x16x32_bf16 v[72:75], v[162:165], v[214:217], v[72:75]
	v_mfma_f32_16x16x32_bf16 v[68:71], v[170:173], v[214:217], v[68:71]
	v_mfma_f32_16x16x32_bf16 v[120:123], v[166:169], v[182:185], v[120:123]
	v_mfma_f32_16x16x32_bf16 v[116:119], v[174:177], v[182:185], v[116:119]
	v_mfma_f32_16x16x32_bf16 v[104:107], v[166:169], v[190:193], v[104:107]
	v_mfma_f32_16x16x32_bf16 v[100:103], v[174:177], v[190:193], v[100:103]
	v_mfma_f32_16x16x32_bf16 v[88:91], v[166:169], v[210:213], v[88:91]
	v_mfma_f32_16x16x32_bf16 v[84:87], v[174:177], v[210:213], v[84:87]
	v_mfma_f32_16x16x32_bf16 v[72:75], v[166:169], v[218:221], v[72:75]
	v_mfma_f32_16x16x32_bf16 v[68:71], v[174:177], v[218:221], v[68:71]
	s_barrier
; #define PG8_STAGE(bufoff, gbase, voff) do { _Pragma("unroll") for (int _i = 0; _i < 2; ++_i) \
;         __builtin_amdgcn_global_load_lds((const unsigned*)((const char*)(gbase) + (voff)[_i]), (PG8_LAS unsigned*)(lds + (bufoff) + ldsw + _i * 8192), 16, 0, 0); } while (0)
; #define PG8_LDA(dst, b, h) do { _Pragma("unroll") for (int m = 0; m < 4; ++m) _Pragma("unroll") for (int k = 0; k < 2; ++k) dst[m][k] = *(const PG8_LAS bf16x8*)(lds + PG8_SA(b, h) + aoff + m * 2048 + k * 1024); } while (0)
; #define PG8_MMA(ai, bj, At, Bt) do { __builtin_amdgcn_s_setprio(1); _Pragma("unroll") for (int m = 0; m < 4; ++m) _Pragma("unroll") for (int n = 0; n < 2; ++n) _Pragma("unroll") for (int k = 0; k < 2; ++k) \
;         acc[ai][bj][m][n] = __builtin_amdgcn_mfma_f32_16x16x32_bf16(Bt[n][k], At[m][k], acc[ai][bj][m][n], 0, 0, 0); __builtin_amdgcn_s_setprio(0); } while (0)
; #define PG8_WAIT_V(n) asm volatile("s_waitcnt vmcnt(" #n ")" ::: "memory")
; #define PG8_WAIT_L(n) asm volatile("s_waitcnt lgkmcnt(" #n ")" ::: "memory")
; #define PG8_BAR __builtin_amdgcn_s_barrier()
; #define PG8_SCHED __builtin_amdgcn_sched_barrier(0)
;     ...
;             PG8_LDA(At, 1, 1); PG8_STAGE(PG8_SB(1, 0), b3, voffB); PG8_STAGE(PG8_SB(1, 1), b3 + hstep, voffB); PG8_STAGE(PG8_SA(1, 0), a3, voffA);
;             PG8_WAIT_V(8); PG8_WAIT_L(0); PG8_BAR; PG8_MMA(1, 0, At, B0); PG8_MMA(1, 1, At, B1); PG8_BAR; PG8_SCHED;
	s_setprio 0
	s_add_i32 s48, s48, s1
	v_lshl_add_u64 v[198:199], v[198:199], 0, s[66:67]
	s_mov_b32 m0, s48
	ds_read_b128 v[178:181], v156 offset:49152
	ds_read_b128 v[182:185], v156 offset:50176
	ds_read_b128 v[186:189], v156 offset:51200
	ds_read_b128 v[190:193], v156 offset:52224
	ds_read_b128 v[194:197], v156 offset:53248
	ds_read_b128 v[210:213], v156 offset:54272
	ds_read_b128 v[214:217], v156 offset:55296
	ds_read_b128 v[218:221], v156 offset:56320
	global_load_lds_dwordx4 v[198:199], off
	s_add_i32 m0, s48, 0x2000
	s_add_u32 s62, s62, 0x80080
	v_lshl_add_u64 v[198:199], v[206:207], 0, s[66:67]
	s_addc_u32 s63, s63, 0
	s_add_i32 s48, s49, s1
	global_load_lds_dwordx4 v[198:199], off
	v_lshl_add_u64 v[198:199], s[62:63], 0, v[200:201]
	s_mov_b32 m0, s48
	s_nop 0
	global_load_lds_dwordx4 v[198:199], off
	v_lshl_add_u64 v[198:199], s[62:63], 0, v[132:133]
	s_add_i32 m0, s48, 0x2000
	s_nop 0
	global_load_lds_dwordx4 v[198:199], off
	v_lshl_add_u64 v[198:199], v[208:209], 0, s[66:67]
	s_mov_b32 m0, s55
	s_nop 0
	global_load_lds_dwordx4 v[198:199], off
	v_lshl_add_u64 v[198:199], v[222:223], 0, s[66:67]
	s_mov_b32 m0, s56
	s_nop 0
	global_load_lds_dwordx4 v[198:199], off
	s_waitcnt vmcnt(8) lgkmcnt(0)
	s_setprio 1
	s_barrier
	v_mfma_f32_16x16x32_bf16 v[64:67], v[142:145], v[178:181], v[64:67]
	v_mfma_f32_16x16x32_bf16 v[60:63], v[150:153], v[178:181], v[60:63]
	v_mfma_f32_16x16x32_bf16 v[48:51], v[142:145], v[186:189], v[48:51]
	v_mfma_f32_16x16x32_bf16 v[44:47], v[150:153], v[186:189], v[44:47]
	v_mfma_f32_16x16x32_bf16 v[32:35], v[142:145], v[194:197], v[32:35]
	v_mfma_f32_16x16x32_bf16 v[28:31], v[150:153], v[194:197], v[28:31]
	v_mfma_f32_16x16x32_bf16 v[16:19], v[142:145], v[214:217], v[16:19]
	v_mfma_f32_16x16x32_bf16 v[12:15], v[150:153], v[214:217], v[12:15]
	v_mfma_f32_16x16x32_bf16 v[64:67], v[146:149], v[182:185], v[64:67]
	v_mfma_f32_16x16x32_bf16 v[60:63], v[158:161], v[182:185], v[60:63]
	v_mfma_f32_16x16x32_bf16 v[48:51], v[146:149], v[190:193], v[48:51]
	v_mfma_f32_16x16x32_bf16 v[44:47], v[158:161], v[190:193], v[44:47]
	v_mfma_f32_16x16x32_bf16 v[32:35], v[146:149], v[210:213], v[32:35]
	v_mfma_f32_16x16x32_bf16 v[28:31], v[158:161], v[210:213], v[28:31]
	v_mfma_f32_16x16x32_bf16 v[16:19], v[146:149], v[218:221], v[16:19]
	v_mfma_f32_16x16x32_bf16 v[12:15], v[158:161], v[218:221], v[12:15]
	v_mfma_f32_16x16x32_bf16 v[56:59], v[162:165], v[178:181], v[56:59]
	v_mfma_f32_16x16x32_bf16 v[52:55], v[170:173], v[178:181], v[52:55]
	v_mfma_f32_16x16x32_bf16 v[40:43], v[162:165], v[186:189], v[40:43]
	v_mfma_f32_16x16x32_bf16 v[36:39], v[170:173], v[186:189], v[36:39]
	v_mfma_f32_16x16x32_bf16 v[24:27], v[162:165], v[194:197], v[24:27]
	v_mfma_f32_16x16x32_bf16 v[20:23], v[170:173], v[194:197], v[20:23]
	v_mfma_f32_16x16x32_bf16 v[8:11], v[162:165], v[214:217], v[8:11]
	v_mfma_f32_16x16x32_bf16 v[4:7], v[170:173], v[214:217], v[4:7]
	v_mfma_f32_16x16x32_bf16 v[56:59], v[166:169], v[182:185], v[56:59]
	v_mfma_f32_16x16x32_bf16 v[52:55], v[174:177], v[182:185], v[52:55]
	v_mfma_f32_16x16x32_bf16 v[40:43], v[166:169], v[190:193], v[40:43]
	v_mfma_f32_16x16x32_bf16 v[36:39], v[174:177], v[190:193], v[36:39]
	v_mfma_f32_16x16x32_bf16 v[24:27], v[166:169], v[210:213], v[24:27]
	v_mfma_f32_16x16x32_bf16 v[20:23], v[174:177], v[210:213], v[20:23]
	v_mfma_f32_16x16x32_bf16 v[8:11], v[166:169], v[218:221], v[8:11]
	v_mfma_f32_16x16x32_bf16 v[4:7], v[174:177], v[218:221], v[4:7]
	s_barrier
	s_setprio 0
	s_add_i32 s86, s86, 2
	s_add_u32 s60, s60, 0x100
	s_addc_u32 s61, s61, 0
	s_add_u32 s84, s84, 0x100
	s_addc_u32 s85, s85, 0
	s_cmp_gt_u32 s86, 29
	s_cbranch_scc0 .LBB0_198
	s_and_b64 vcc, exec, s[12:13]
	s_cbranch_vccz .LBB0_201
	s_barrier

; #define PG8_STAGE(bufoff, gbase, voff) do { _Pragma("unroll") for (int _i = 0; _i < 2; ++_i) \
;         __builtin_amdgcn_global_load_lds((const unsigned*)((const char*)(gbase) + (voff)[_i]), (PG8_LAS unsigned*)(lds + (bufoff) + ldsw + _i * 8192), 16, 0, 0); } while (0)
; #define PG8_LDA(dst, b, h) do { _Pragma("unroll") for (int m = 0; m < 4; ++m) _Pragma("unroll") for (int k = 0; k < 2; ++k) dst[m][k] = *(const PG8_LAS bf16x8*)(lds + PG8_SA(b, h) + aoff + m * 2048 + k * 1024); } while (0)
; #define PG8_LDB(dst, b, h) do { _Pragma("unroll") for (int n = 0; n < 2; ++n) _Pragma("unroll") for (int k = 0; k < 2; ++k) dst[n][k] = *(const PG8_LAS bf16x8*)(lds + PG8_SB(b, h) + boff + n * 2048 + k * 1024); } while (0)
; #define PG8_MMA(ai, bj, At, Bt) do { __builtin_amdgcn_s_setprio(1); _Pragma("unroll") for (int m = 0; m < 4; ++m) _Pragma("unroll") for (int n = 0; n < 2; ++n) _Pragma("unroll") for (int k = 0; k < 2; ++k) \
;         acc[ai][bj][m][n] = __builtin_amdgcn_mfma_f32_16x16x32_bf16(Bt[n][k], At[m][k], acc[ai][bj][m][n], 0, 0, 0); __builtin_amdgcn_s_setprio(0); } while (0)
; #define PG8_WAIT_V(n) asm volatile("s_waitcnt vmcnt(" #n ")" ::: "memory")
; #define PG8_WAIT_L(n) asm volatile("s_waitcnt lgkmcnt(" #n ")" ::: "memory")
; #define PG8_BAR __builtin_amdgcn_s_barrier()
; #define PG8_SCHED __builtin_amdgcn_sched_barrier(0)
;     ...
;             const bool last = (t == nt - 2);
;             const char* a1 = cA + (size_t)(t + 1) * kstep;
;             const char* a2 = last ? nA : cA + (size_t)(t + 2) * kstep; const char* b2 = last ? nB : cB + (size_t)(t + 2) * kstep;
;             const char* a3 = a2 + kstep; const char* b3 = b2 + kstep;
;             if (last && has_next) S.a_ready(nxt);
;             if (t == 0) E.pre_issue(pre, cur, tid, ui); else if (t == 2) E.pre_finish(pre, tid, ui);
;             if constexpr (SP2) {
;             PG8_LDB(B0, 0, 0); PG8_LDB(B1, 0, 1); PG8_SCHED; PG8_LDA(At, 0, 0); PG8_STAGE(PG8_SA(1, 1), a1 + hstep, voffA);
;             PG8_WAIT_V(8); PG8_WAIT_L(0); PG8_BAR; PG8_MMA(0, 0, At, B0); PG8_MMA(0, 1, At, B1); PG8_BAR; PG8_SCHED;
;             PG8_LDA(At, 0, 1); PG8_STAGE(PG8_SB(0, 0), b2, voffB); PG8_STAGE(PG8_SB(0, 1), b2 + hstep, voffB); PG8_STAGE(PG8_SA(0, 0), a2, voffA);
;             PG8_WAIT_V(8); PG8_WAIT_L(0); PG8_BAR; PG8_MMA(1, 0, At, B0); PG8_MMA(1, 1, At, B1); PG8_BAR; PG8_SCHED;
.LBB0_279:
	s_add_u32 s10, s56, s6
	s_addc_u32 s11, s73, s7
	s_add_u32 s10, s10, 0x1d800100
	s_addc_u32 s11, s11, 0
	s_add_u32 s48, s0, s6
	s_addc_u32 s49, s50, s7
	s_add_i32 s52, 0, 0x10000
	s_cmpk_eq_i32 s6, 0xf00
	s_cselect_b32 s13, s55, s11
	s_cselect_b32 s12, s54, s10
	s_cselect_b32 s11, s5, s49
	s_cselect_b32 s10, s4, s48
	s_add_i32 s48, 0, 0x14000
	ds_read_b128 v[146:149], v251
	ds_read_b128 v[150:153], v251 offset:1024
	ds_read_b128 v[154:157], v251 offset:2048
	ds_read_b128 v[158:161], v251 offset:3072
	ds_read_b128 v[162:165], v251 offset:16384
	ds_read_b128 v[166:169], v251 offset:17408
	ds_read_b128 v[170:173], v251 offset:18432
	ds_read_b128 v[174:177], v251 offset:19456
	v_lshl_add_u64 v[198:199], v[138:139], 0, s[6:7]
	s_add_i32 m0, s15, 0xc000
	ds_read_b128 v[178:181], v144
	ds_read_b128 v[182:185], v144 offset:1024
	ds_read_b128 v[186:189], v144 offset:2048
	ds_read_b128 v[190:193], v144 offset:3072
	ds_read_b128 v[194:197], v144 offset:4096
	ds_read_b128 v[210:213], v144 offset:5120
	ds_read_b128 v[214:217], v144 offset:6144
	ds_read_b128 v[218:221], v144 offset:7168
	global_load_lds_dwordx4 v[198:199], off
	v_lshl_add_u64 v[198:199], v[140:141], 0, s[6:7]
	s_add_i32 m0, s15, 0xe000
	s_nop 0
	global_load_lds_dwordx4 v[198:199], off
	s_waitcnt vmcnt(8) lgkmcnt(0)
	s_setprio 1
	s_barrier
	v_mfma_f32_16x16x32_bf16 v[128:131], v[146:149], v[178:181], v[128:131]
	v_mfma_f32_16x16x32_bf16 v[124:127], v[154:157], v[178:181], v[124:127]
	v_mfma_f32_16x16x32_bf16 v[112:115], v[146:149], v[186:189], v[112:115]
	v_mfma_f32_16x16x32_bf16 v[108:111], v[154:157], v[186:189], v[108:111]
	v_mfma_f32_16x16x32_bf16 v[96:99], v[146:149], v[194:197], v[96:99]
	v_mfma_f32_16x16x32_bf16 v[92:95], v[154:157], v[194:197], v[92:95]
	v_mfma_f32_16x16x32_bf16 v[80:83], v[146:149], v[214:217], v[80:83]
	v_mfma_f32_16x16x32_bf16 v[76:79], v[154:157], v[214:217], v[76:79]
	v_mfma_f32_16x16x32_bf16 v[128:131], v[150:153], v[182:185], v[128:131]
	v_mfma_f32_16x16x32_bf16 v[124:127], v[158:161], v[182:185], v[124:127]
	v_mfma_f32_16x16x32_bf16 v[112:115], v[150:153], v[190:193], v[112:115]
	v_mfma_f32_16x16x32_bf16 v[108:111], v[158:161], v[190:193], v[108:111]
	v_mfma_f32_16x16x32_bf16 v[96:99], v[150:153], v[210:213], v[96:99]
	v_mfma_f32_16x16x32_bf16 v[92:95], v[158:161], v[210:213], v[92:95]
	v_mfma_f32_16x16x32_bf16 v[80:83], v[150:153], v[218:221], v[80:83]
	v_mfma_f32_16x16x32_bf16 v[76:79], v[158:161], v[218:221], v[76:79]
	v_mfma_f32_16x16x32_bf16 v[120:123], v[162:165], v[178:181], v[120:123]
	v_mfma_f32_16x16x32_bf16 v[116:119], v[170:173], v[178:181], v[116:119]
	v_mfma_f32_16x16x32_bf16 v[104:107], v[162:165], v[186:189], v[104:107]
	v_mfma_f32_16x16x32_bf16 v[100:103], v[170:173], v[186:189], v[100:103]
	v_mfma_f32_16x16x32_bf16 v[88:91], v[162:165], v[194:197], v[88:91]
	v_mfma_f32_16x16x32_bf16 v[84:87], v[170:173], v[194:197], v[84:87]
	v_mfma_f32_16x16x32_bf16 v[72:75], v[162:165], v[214:217], v[72:75]
	v_mfma_f32_16x16x32_bf16 v[68:71], v[170:173], v[214:217], v[68:71]
	v_mfma_f32_16x16x32_bf16 v[120:123], v[166:169], v[182:185], v[120:123]
	v_mfma_f32_16x16x32_bf16 v[116:119], v[174:177], v[182:185], v[116:119]
	v_mfma_f32_16x16x32_bf16 v[104:107], v[166:169], v[190:193], v[104:107]
	v_mfma_f32_16x16x32_bf16 v[100:103], v[174:177], v[190:193], v[100:103]
	v_mfma_f32_16x16x32_bf16 v[88:91], v[166:169], v[210:213], v[88:91]
	v_mfma_f32_16x16x32_bf16 v[84:87], v[174:177], v[210:213], v[84:87]
	v_mfma_f32_16x16x32_bf16 v[72:75], v[166:169], v[218:221], v[72:75]
	v_mfma_f32_16x16x32_bf16 v[68:71], v[174:177], v[218:221], v[68:71]
	s_barrier
	s_setprio 0
	s_add_i32 s49, s52, s14
	v_lshl_add_u64 v[198:199], s[10:11], 0, v[200:201]
	s_mov_b32 m0, s49
	ds_read_b128 v[178:181], v144 offset:16384
	ds_read_b128 v[182:185], v144 offset:17408
	ds_read_b128 v[186:189], v144 offset:18432
	ds_read_b128 v[190:193], v144 offset:19456
	ds_read_b128 v[194:197], v144 offset:20480
	ds_read_b128 v[210:213], v144 offset:21504
	ds_read_b128 v[214:217], v144 offset:22528
	ds_read_b128 v[218:221], v144 offset:23552
	global_load_lds_dwordx4 v[198:199], off
	s_add_i32 m0, s49, 0x2000
	s_add_u32 s52, s10, 0x80000
	v_lshl_add_u64 v[206:207], s[10:11], 0, v[136:137]
	s_addc_u32 s53, s11, 0
	s_add_i32 s48, s48, s14
	global_load_lds_dwordx4 v[206:207], off
	v_lshl_add_u64 v[208:209], s[52:53], 0, v[200:201]
	s_mov_b32 m0, s48
	v_lshl_add_u64 v[222:223], s[12:13], 0, v[134:135]
	global_load_lds_dwordx4 v[208:209], off
	v_lshl_add_u64 v[208:209], s[52:53], 0, v[136:137]
	s_add_i32 m0, s48, 0x2000
	s_nop 0
	global_load_lds_dwordx4 v[208:209], off
	v_lshl_add_u64 v[208:209], s[12:13], 0, v[132:133]
	s_mov_b32 m0, s15
	s_nop 0
	global_load_lds_dwordx4 v[208:209], off
	s_mov_b32 m0, s20
	s_nop 0
	global_load_lds_dwordx4 v[222:223], off
	s_waitcnt vmcnt(8) lgkmcnt(0)
	s_setprio 1
	s_barrier
; #define PG8_STAGE(bufoff, gbase, voff) do { _Pragma("unroll") for (int _i = 0; _i < 2; ++_i) \
;         __builtin_amdgcn_global_load_lds((const unsigned*)((const char*)(gbase) + (voff)[_i]), (PG8_LAS unsigned*)(lds + (bufoff) + ldsw + _i * 8192), 16, 0, 0); } while (0)
; #define PG8_LDA(dst, b, h) do { _Pragma("unroll") for (int m = 0; m < 4; ++m) _Pragma("unroll") for (int k = 0; k < 2; ++k) dst[m][k] = *(const PG8_LAS bf16x8*)(lds + PG8_SA(b, h) + aoff + m * 2048 + k * 1024); } while (0)
; #define PG8_LDB(dst, b, h) do { _Pragma("unroll") for (int n = 0; n < 2; ++n) _Pragma("unroll") for (int k = 0; k < 2; ++k) dst[n][k] = *(const PG8_LAS bf16x8*)(lds + PG8_SB(b, h) + boff + n * 2048 + k * 1024); } while (0)
; #define PG8_MMA(ai, bj, At, Bt) do { __builtin_amdgcn_s_setprio(1); _Pragma("unroll") for (int m = 0; m < 4; ++m) _Pragma("unroll") for (int n = 0; n < 2; ++n) _Pragma("unroll") for (int k = 0; k < 2; ++k) \
;         acc[ai][bj][m][n] = __builtin_amdgcn_mfma_f32_16x16x32_bf16(Bt[n][k], At[m][k], acc[ai][bj][m][n], 0, 0, 0); __builtin_amdgcn_s_setprio(0); } while (0)
; #define PG8_WAIT_V(n) asm volatile("s_waitcnt vmcnt(" #n ")" ::: "memory")
; #define PG8_WAIT_L(n) asm volatile("s_waitcnt lgkmcnt(" #n ")" ::: "memory")
; #define PG8_BAR __builtin_amdgcn_s_barrier()
; #define PG8_SCHED __builtin_amdgcn_sched_barrier(0)
;     ...
;             PG8_WAIT_V(8); PG8_WAIT_L(0); PG8_BAR; PG8_MMA(1, 0, At, B0); PG8_MMA(1, 1, At, B1); PG8_BAR; PG8_SCHED;
;             PG8_LDB(B0, 1, 0); PG8_LDB(B1, 1, 1); PG8_SCHED; PG8_LDA(At, 1, 0); PG8_STAGE(PG8_SA(0, 1), a2 + hstep, voffA);
;             PG8_WAIT_V(8); PG8_WAIT_L(0); PG8_BAR; PG8_MMA(0, 0, At, B0); PG8_MMA(0, 1, At, B1); PG8_BAR; PG8_SCHED;
	v_mfma_f32_16x16x32_bf16 v[64:67], v[146:149], v[178:181], v[64:67]
	v_mfma_f32_16x16x32_bf16 v[60:63], v[154:157], v[178:181], v[60:63]
	v_mfma_f32_16x16x32_bf16 v[48:51], v[146:149], v[186:189], v[48:51]
	v_mfma_f32_16x16x32_bf16 v[44:47], v[154:157], v[186:189], v[44:47]
	v_mfma_f32_16x16x32_bf16 v[32:35], v[146:149], v[194:197], v[32:35]
	v_mfma_f32_16x16x32_bf16 v[28:31], v[154:157], v[194:197], v[28:31]
	v_mfma_f32_16x16x32_bf16 v[16:19], v[146:149], v[214:217], v[16:19]
	v_mfma_f32_16x16x32_bf16 v[12:15], v[154:157], v[214:217], v[12:15]
	v_mfma_f32_16x16x32_bf16 v[64:67], v[150:153], v[182:185], v[64:67]
	v_mfma_f32_16x16x32_bf16 v[60:63], v[158:161], v[182:185], v[60:63]
	v_mfma_f32_16x16x32_bf16 v[48:51], v[150:153], v[190:193], v[48:51]
	v_mfma_f32_16x16x32_bf16 v[44:47], v[158:161], v[190:193], v[44:47]
	v_mfma_f32_16x16x32_bf16 v[32:35], v[150:153], v[210:213], v[32:35]
	v_mfma_f32_16x16x32_bf16 v[28:31], v[158:161], v[210:213], v[28:31]
	v_mfma_f32_16x16x32_bf16 v[16:19], v[150:153], v[218:221], v[16:19]
	v_mfma_f32_16x16x32_bf16 v[12:15], v[158:161], v[218:221], v[12:15]
	v_mfma_f32_16x16x32_bf16 v[56:59], v[162:165], v[178:181], v[56:59]
	v_mfma_f32_16x16x32_bf16 v[52:55], v[170:173], v[178:181], v[52:55]
	v_mfma_f32_16x16x32_bf16 v[40:43], v[162:165], v[186:189], v[40:43]
	v_mfma_f32_16x16x32_bf16 v[36:39], v[170:173], v[186:189], v[36:39]
	v_mfma_f32_16x16x32_bf16 v[24:27], v[162:165], v[194:197], v[24:27]
	v_mfma_f32_16x16x32_bf16 v[20:23], v[170:173], v[194:197], v[20:23]
	v_mfma_f32_16x16x32_bf16 v[8:11], v[162:165], v[214:217], v[8:11]
	v_mfma_f32_16x16x32_bf16 v[4:7], v[170:173], v[214:217], v[4:7]
	v_mfma_f32_16x16x32_bf16 v[56:59], v[166:169], v[182:185], v[56:59]
	v_mfma_f32_16x16x32_bf16 v[52:55], v[174:177], v[182:185], v[52:55]
	v_mfma_f32_16x16x32_bf16 v[40:43], v[166:169], v[190:193], v[40:43]
	v_mfma_f32_16x16x32_bf16 v[36:39], v[174:177], v[190:193], v[36:39]
	v_mfma_f32_16x16x32_bf16 v[24:27], v[166:169], v[210:213], v[24:27]
	v_mfma_f32_16x16x32_bf16 v[20:23], v[174:177], v[210:213], v[20:23]
	v_mfma_f32_16x16x32_bf16 v[8:11], v[166:169], v[218:221], v[8:11]
	v_mfma_f32_16x16x32_bf16 v[4:7], v[174:177], v[218:221], v[4:7]
	s_barrier
	s_setprio 0
	s_add_i32 s48, 0, 0x18000
	s_add_i32 s49, 0, 0x1c000
	ds_read_b128 v[146:149], v251 offset:32768
	ds_read_b128 v[150:153], v251 offset:33792
	ds_read_b128 v[154:157], v251 offset:34816
	ds_read_b128 v[158:161], v251 offset:35840
	ds_read_b128 v[162:165], v251 offset:49152
	ds_read_b128 v[166:169], v251 offset:50176
	ds_read_b128 v[170:173], v251 offset:51200
	ds_read_b128 v[174:177], v251 offset:52224
	s_add_u32 s12, s12, 0x80000
	s_addc_u32 s13, s13, 0
	s_mov_b32 m0, s21
	v_lshl_add_u64 v[224:225], s[12:13], 0, v[132:133]
	ds_read_b128 v[178:181], v144 offset:32768
	ds_read_b128 v[182:185], v144 offset:33792
	ds_read_b128 v[186:189], v144 offset:34816
	ds_read_b128 v[190:193], v144 offset:35840
	ds_read_b128 v[194:197], v144 offset:36864
	ds_read_b128 v[210:213], v144 offset:37888
	ds_read_b128 v[214:217], v144 offset:38912
	ds_read_b128 v[218:221], v144 offset:39936
	global_load_lds_dwordx4 v[224:225], off
	v_lshl_add_u64 v[224:225], s[12:13], 0, v[134:135]
	s_mov_b32 m0, s23
	s_nop 0
	global_load_lds_dwordx4 v[224:225], off
	s_waitcnt vmcnt(8) lgkmcnt(0)
	s_setprio 1
	s_barrier
	v_mfma_f32_16x16x32_bf16 v[128:131], v[146:149], v[178:181], v[128:131]
	v_mfma_f32_16x16x32_bf16 v[124:127], v[154:157], v[178:181], v[124:127]
	v_mfma_f32_16x16x32_bf16 v[112:115], v[146:149], v[186:189], v[112:115]
	v_mfma_f32_16x16x32_bf16 v[108:111], v[154:157], v[186:189], v[108:111]
	v_mfma_f32_16x16x32_bf16 v[96:99], v[146:149], v[194:197], v[96:99]
	v_mfma_f32_16x16x32_bf16 v[92:95], v[154:157], v[194:197], v[92:95]
	v_mfma_f32_16x16x32_bf16 v[80:83], v[146:149], v[214:217], v[80:83]
	v_mfma_f32_16x16x32_bf16 v[76:79], v[154:157], v[214:217], v[76:79]
	v_mfma_f32_16x16x32_bf16 v[128:131], v[150:153], v[182:185], v[128:131]
	v_mfma_f32_16x16x32_bf16 v[124:127], v[158:161], v[182:185], v[124:127]
	v_mfma_f32_16x16x32_bf16 v[112:115], v[150:153], v[190:193], v[112:115]
	v_mfma_f32_16x16x32_bf16 v[108:111], v[158:161], v[190:193], v[108:111]
	v_mfma_f32_16x16x32_bf16 v[96:99], v[150:153], v[210:213], v[96:99]
	v_mfma_f32_16x16x32_bf16 v[92:95], v[158:161], v[210:213], v[92:95]
	v_mfma_f32_16x16x32_bf16 v[80:83], v[150:153], v[218:221], v[80:83]
	v_mfma_f32_16x16x32_bf16 v[76:79], v[158:161], v[218:221], v[76:79]
	v_mfma_f32_16x16x32_bf16 v[120:123], v[162:165], v[178:181], v[120:123]
	v_mfma_f32_16x16x32_bf16 v[116:119], v[170:173], v[178:181], v[116:119]
	v_mfma_f32_16x16x32_bf16 v[104:107], v[162:165], v[186:189], v[104:107]
	v_mfma_f32_16x16x32_bf16 v[100:103], v[170:173], v[186:189], v[100:103]
	v_mfma_f32_16x16x32_bf16 v[88:91], v[162:165], v[194:197], v[88:91]
	v_mfma_f32_16x16x32_bf16 v[84:87], v[170:173], v[194:197], v[84:87]
	v_mfma_f32_16x16x32_bf16 v[72:75], v[162:165], v[214:217], v[72:75]
	v_mfma_f32_16x16x32_bf16 v[68:71], v[170:173], v[214:217], v[68:71]
	v_mfma_f32_16x16x32_bf16 v[120:123], v[166:169], v[182:185], v[120:123]
	v_mfma_f32_16x16x32_bf16 v[116:119], v[174:177], v[182:185], v[116:119]
	v_mfma_f32_16x16x32_bf16 v[104:107], v[166:169], v[190:193], v[104:107]
	v_mfma_f32_16x16x32_bf16 v[100:103], v[174:177], v[190:193], v[100:103]
	v_mfma_f32_16x16x32_bf16 v[88:91], v[166:169], v[210:213], v[88:91]
	v_mfma_f32_16x16x32_bf16 v[84:87], v[174:177], v[210:213], v[84:87]
	v_mfma_f32_16x16x32_bf16 v[72:75], v[166:169], v[218:221], v[72:75]
	v_mfma_f32_16x16x32_bf16 v[68:71], v[174:177], v[218:221], v[68:71]
	s_barrier
; #define PG8_STAGE(bufoff, gbase, voff) do { _Pragma("unroll") for (int _i = 0; _i < 2; ++_i) \
;         __builtin_amdgcn_global_load_lds((const unsigned*)((const char*)(gbase) + (voff)[_i]), (PG8_LAS unsigned*)(lds + (bufoff) + ldsw + _i * 8192), 16, 0, 0); } while (0)
; #define PG8_LDA(dst, b, h) do { _Pragma("unroll") for (int m = 0; m < 4; ++m) _Pragma("unroll") for (int k = 0; k < 2; ++k) dst[m][k] = *(const PG8_LAS bf16x8*)(lds + PG8_SA(b, h) + aoff + m * 2048 + k * 1024); } while (0)
; #define PG8_MMA(ai, bj, At, Bt) do { __builtin_amdgcn_s_setprio(1); _Pragma("unroll") for (int m = 0; m < 4; ++m) _Pragma("unroll") for (int n = 0; n < 2; ++n) _Pragma("unroll") for (int k = 0; k < 2; ++k) \
;         acc[ai][bj][m][n] = __builtin_amdgcn_mfma_f32_16x16x32_bf16(Bt[n][k], At[m][k], acc[ai][bj][m][n], 0, 0, 0); __builtin_amdgcn_s_setprio(0); } while (0)
; #define PG8_WAIT_V(n) asm volatile("s_waitcnt vmcnt(" #n ")" ::: "memory")
; #define PG8_WAIT_L(n) asm volatile("s_waitcnt lgkmcnt(" #n ")" ::: "memory")
; #define PG8_BAR __builtin_amdgcn_s_barrier()
; #define PG8_SCHED __builtin_amdgcn_sched_barrier(0)
;     ...
;             PG8_LDA(At, 1, 1); PG8_STAGE(PG8_SB(1, 0), b3, voffB); PG8_STAGE(PG8_SB(1, 1), b3 + hstep, voffB); PG8_STAGE(PG8_SA(1, 0), a3, voffA);
;             PG8_WAIT_V(8); PG8_WAIT_L(0); PG8_BAR; PG8_MMA(1, 0, At, B0); PG8_MMA(1, 1, At, B1); PG8_BAR; PG8_SCHED;
	s_setprio 0
	s_add_i32 s12, s48, s14
	v_lshl_add_u64 v[198:199], v[198:199], 0, s[66:67]
	s_mov_b32 m0, s12
	ds_read_b128 v[178:181], v144 offset:49152
	ds_read_b128 v[182:185], v144 offset:50176
	ds_read_b128 v[186:189], v144 offset:51200
	ds_read_b128 v[190:193], v144 offset:52224
	ds_read_b128 v[194:197], v144 offset:53248
	ds_read_b128 v[210:213], v144 offset:54272
	ds_read_b128 v[214:217], v144 offset:55296
	ds_read_b128 v[218:221], v144 offset:56320
	global_load_lds_dwordx4 v[198:199], off
	s_add_i32 m0, s12, 0x2000
	s_add_u32 s10, s10, 0x80080
	v_lshl_add_u64 v[198:199], v[206:207], 0, s[66:67]
	s_addc_u32 s11, s11, 0
	s_add_i32 s12, s49, s14
	global_load_lds_dwordx4 v[198:199], off
	v_lshl_add_u64 v[198:199], s[10:11], 0, v[200:201]
	s_mov_b32 m0, s12
	s_nop 0
	global_load_lds_dwordx4 v[198:199], off
	v_lshl_add_u64 v[198:199], s[10:11], 0, v[136:137]
	s_add_i32 m0, s12, 0x2000
	s_nop 0
	global_load_lds_dwordx4 v[198:199], off
	v_lshl_add_u64 v[198:199], v[208:209], 0, s[66:67]
	s_mov_b32 m0, s42
	s_nop 0
	global_load_lds_dwordx4 v[198:199], off
	v_lshl_add_u64 v[198:199], v[222:223], 0, s[66:67]
	s_mov_b32 m0, s44
	s_nop 0
	global_load_lds_dwordx4 v[198:199], off
	s_waitcnt vmcnt(8) lgkmcnt(0)
	s_setprio 1
	s_barrier
	v_mfma_f32_16x16x32_bf16 v[64:67], v[146:149], v[178:181], v[64:67]
	v_mfma_f32_16x16x32_bf16 v[60:63], v[154:157], v[178:181], v[60:63]
	v_mfma_f32_16x16x32_bf16 v[48:51], v[146:149], v[186:189], v[48:51]
	v_mfma_f32_16x16x32_bf16 v[44:47], v[154:157], v[186:189], v[44:47]
	v_mfma_f32_16x16x32_bf16 v[32:35], v[146:149], v[194:197], v[32:35]
	v_mfma_f32_16x16x32_bf16 v[28:31], v[154:157], v[194:197], v[28:31]
	v_mfma_f32_16x16x32_bf16 v[16:19], v[146:149], v[214:217], v[16:19]
	v_mfma_f32_16x16x32_bf16 v[12:15], v[154:157], v[214:217], v[12:15]
	v_mfma_f32_16x16x32_bf16 v[64:67], v[150:153], v[182:185], v[64:67]
	v_mfma_f32_16x16x32_bf16 v[60:63], v[158:161], v[182:185], v[60:63]
	v_mfma_f32_16x16x32_bf16 v[48:51], v[150:153], v[190:193], v[48:51]
	v_mfma_f32_16x16x32_bf16 v[44:47], v[158:161], v[190:193], v[44:47]
	v_mfma_f32_16x16x32_bf16 v[32:35], v[150:153], v[210:213], v[32:35]
	v_mfma_f32_16x16x32_bf16 v[28:31], v[158:161], v[210:213], v[28:31]
	v_mfma_f32_16x16x32_bf16 v[16:19], v[150:153], v[218:221], v[16:19]
	v_mfma_f32_16x16x32_bf16 v[12:15], v[158:161], v[218:221], v[12:15]
	v_mfma_f32_16x16x32_bf16 v[56:59], v[162:165], v[178:181], v[56:59]
	v_mfma_f32_16x16x32_bf16 v[52:55], v[170:173], v[178:181], v[52:55]
	v_mfma_f32_16x16x32_bf16 v[40:43], v[162:165], v[186:189], v[40:43]
	v_mfma_f32_16x16x32_bf16 v[36:39], v[170:173], v[186:189], v[36:39]
	v_mfma_f32_16x16x32_bf16 v[24:27], v[162:165], v[194:197], v[24:27]
	v_mfma_f32_16x16x32_bf16 v[20:23], v[170:173], v[194:197], v[20:23]
	v_mfma_f32_16x16x32_bf16 v[8:11], v[162:165], v[214:217], v[8:11]
	v_mfma_f32_16x16x32_bf16 v[4:7], v[170:173], v[214:217], v[4:7]
	v_mfma_f32_16x16x32_bf16 v[56:59], v[166:169], v[182:185], v[56:59]
	v_mfma_f32_16x16x32_bf16 v[52:55], v[174:177], v[182:185], v[52:55]
	v_mfma_f32_16x16x32_bf16 v[40:43], v[166:169], v[190:193], v[40:43]
	v_mfma_f32_16x16x32_bf16 v[36:39], v[174:177], v[190:193], v[36:39]
	v_mfma_f32_16x16x32_bf16 v[24:27], v[166:169], v[210:213], v[24:27]
	v_mfma_f32_16x16x32_bf16 v[20:23], v[174:177], v[210:213], v[20:23]
	v_mfma_f32_16x16x32_bf16 v[8:11], v[166:169], v[218:221], v[8:11]
	v_mfma_f32_16x16x32_bf16 v[4:7], v[174:177], v[218:221], v[4:7]
	s_barrier
	s_setprio 0
	s_add_i32 s51, s51, 2
	s_add_u32 s6, s6, 0x100
	s_addc_u32 s7, s7, 0
	s_cmp_gt_u32 s51, 29
	s_cbranch_scc0 .LBB0_279
	s_cmpk_lt_u32 s1, 0x100
	s_cbranch_scc0 .LBB0_282
	s_barrier

; #define PG8_STAGE(bufoff, gbase, voff) do { _Pragma("unroll") for (int _i = 0; _i < 2; ++_i) \
;         __builtin_amdgcn_global_load_lds((const unsigned*)((const char*)(gbase) + (voff)[_i]), (PG8_LAS unsigned*)(lds + (bufoff) + ldsw + _i * 8192), 16, 0, 0); } while (0)
; #define PG8_LDA(dst, b, h) do { _Pragma("unroll") for (int m = 0; m < 4; ++m) _Pragma("unroll") for (int k = 0; k < 2; ++k) dst[m][k] = *(const PG8_LAS bf16x8*)(lds + PG8_SA(b, h) + aoff + m * 2048 + k * 1024); } while (0)
; #define PG8_LDB(dst, b, h) do { _Pragma("unroll") for (int n = 0; n < 2; ++n) _Pragma("unroll") for (int k = 0; k < 2; ++k) dst[n][k] = *(const PG8_LAS bf16x8*)(lds + PG8_SB(b, h) + boff + n * 2048 + k * 1024); } while (0)
; #define PG8_MMA(ai, bj, At, Bt) do { __builtin_amdgcn_s_setprio(1); _Pragma("unroll") for (int m = 0; m < 4; ++m) _Pragma("unroll") for (int n = 0; n < 2; ++n) _Pragma("unroll") for (int k = 0; k < 2; ++k) \
;         acc[ai][bj][m][n] = __builtin_amdgcn_mfma_f32_16x16x32_bf16(Bt[n][k], At[m][k], acc[ai][bj][m][n], 0, 0, 0); __builtin_amdgcn_s_setprio(0); } while (0)
; #define PG8_WAIT_V(n) asm volatile("s_waitcnt vmcnt(" #n ")" ::: "memory")
; #define PG8_WAIT_L(n) asm volatile("s_waitcnt lgkmcnt(" #n ")" ::: "memory")
; #define PG8_BAR __builtin_amdgcn_s_barrier()
; #define PG8_SCHED __builtin_amdgcn_sched_barrier(0)
;     ...
;             const bool last = (t == nt - 2);
;             const char* a1 = cA + (size_t)(t + 1) * kstep;
;             const char* a2 = last ? nA : cA + (size_t)(t + 2) * kstep; const char* b2 = last ? nB : cB + (size_t)(t + 2) * kstep;
;             const char* a3 = a2 + kstep; const char* b3 = b2 + kstep;
;             if (last && has_next) S.a_ready(nxt);
;             if (t == 0) E.pre_issue(pre, cur, tid, ui); else if (t == 2) E.pre_finish(pre, tid, ui);
;             if constexpr (SP2) {
;             PG8_LDB(B0, 0, 0); PG8_LDB(B1, 0, 1); PG8_SCHED; PG8_LDA(At, 0, 0); PG8_STAGE(PG8_SA(1, 1), a1 + hstep, voffA);
;             PG8_WAIT_V(8); PG8_WAIT_L(0); PG8_BAR; PG8_MMA(0, 0, At, B0); PG8_MMA(0, 1, At, B1); PG8_BAR; PG8_SCHED;
;             PG8_LDA(At, 0, 1); PG8_STAGE(PG8_SB(0, 0), b2, voffB); PG8_STAGE(PG8_SB(0, 1), b2 + hstep, voffB); PG8_STAGE(PG8_SA(0, 0), a2, voffA);
;             PG8_WAIT_V(8); PG8_WAIT_L(0); PG8_BAR; PG8_MMA(1, 0, At, B0); PG8_MMA(1, 1, At, B1); PG8_BAR; PG8_SCHED;
.LBB0_290:
	s_add_u32 s48, s24, 0xfffe0080
	s_addc_u32 s49, s25, -1
	s_add_i32 s84, 0, 0x10000
	s_cmp_eq_u32 s83, 4
	s_cselect_b32 s61, s68, s49
	s_cselect_b32 s60, s69, s48
	s_cselect_b32 s51, s70, s81
	s_cselect_b32 s50, s71, s73
	s_add_i32 s48, 0, 0x14000
	ds_read_b128 v[142:145], v251
	ds_read_b128 v[152:155], v251 offset:1024
	ds_read_b128 v[156:159], v251 offset:2048
	ds_read_b128 v[160:163], v251 offset:3072
	ds_read_b128 v[164:167], v251 offset:16384
	ds_read_b128 v[168:171], v251 offset:17408
	ds_read_b128 v[172:175], v251 offset:18432
	ds_read_b128 v[176:179], v251 offset:19456
	v_lshl_add_u64 v[146:147], s[24:25], 0, v[140:141]
	s_add_i32 m0, s23, 0xc000
	ds_read_b128 v[180:183], v150
	ds_read_b128 v[184:187], v150 offset:1024
	ds_read_b128 v[188:191], v150 offset:2048
	ds_read_b128 v[192:195], v150 offset:3072
	ds_read_b128 v[196:199], v150 offset:4096
	ds_read_b128 v[210:213], v150 offset:5120
	ds_read_b128 v[214:217], v150 offset:6144
	ds_read_b128 v[218:221], v150 offset:7168
	global_load_lds_dwordx4 v[146:147], off
	v_lshl_add_u64 v[146:147], s[24:25], 0, v[138:139]
	s_add_i32 m0, s23, 0xe000
	s_nop 0
	global_load_lds_dwordx4 v[146:147], off
	s_waitcnt vmcnt(8) lgkmcnt(0)
	s_setprio 1
	s_barrier
	v_mfma_f32_16x16x32_bf16 v[128:131], v[142:145], v[180:183], v[128:131]
	v_mfma_f32_16x16x32_bf16 v[124:127], v[156:159], v[180:183], v[124:127]
	v_mfma_f32_16x16x32_bf16 v[112:115], v[142:145], v[188:191], v[112:115]
	v_mfma_f32_16x16x32_bf16 v[108:111], v[156:159], v[188:191], v[108:111]
	v_mfma_f32_16x16x32_bf16 v[96:99], v[142:145], v[196:199], v[96:99]
	v_mfma_f32_16x16x32_bf16 v[92:95], v[156:159], v[196:199], v[92:95]
	v_mfma_f32_16x16x32_bf16 v[80:83], v[142:145], v[214:217], v[80:83]
	v_mfma_f32_16x16x32_bf16 v[76:79], v[156:159], v[214:217], v[76:79]
	v_mfma_f32_16x16x32_bf16 v[128:131], v[152:155], v[184:187], v[128:131]
	v_mfma_f32_16x16x32_bf16 v[124:127], v[160:163], v[184:187], v[124:127]
	v_mfma_f32_16x16x32_bf16 v[112:115], v[152:155], v[192:195], v[112:115]
	v_mfma_f32_16x16x32_bf16 v[108:111], v[160:163], v[192:195], v[108:111]
	v_mfma_f32_16x16x32_bf16 v[96:99], v[152:155], v[210:213], v[96:99]
	v_mfma_f32_16x16x32_bf16 v[92:95], v[160:163], v[210:213], v[92:95]
	v_mfma_f32_16x16x32_bf16 v[80:83], v[152:155], v[218:221], v[80:83]
	v_mfma_f32_16x16x32_bf16 v[76:79], v[160:163], v[218:221], v[76:79]
	v_mfma_f32_16x16x32_bf16 v[120:123], v[164:167], v[180:183], v[120:123]
	v_mfma_f32_16x16x32_bf16 v[116:119], v[172:175], v[180:183], v[116:119]
	v_mfma_f32_16x16x32_bf16 v[104:107], v[164:167], v[188:191], v[104:107]
	v_mfma_f32_16x16x32_bf16 v[100:103], v[172:175], v[188:191], v[100:103]
	v_mfma_f32_16x16x32_bf16 v[88:91], v[164:167], v[196:199], v[88:91]
	v_mfma_f32_16x16x32_bf16 v[84:87], v[172:175], v[196:199], v[84:87]
	v_mfma_f32_16x16x32_bf16 v[72:75], v[164:167], v[214:217], v[72:75]
	v_mfma_f32_16x16x32_bf16 v[68:71], v[172:175], v[214:217], v[68:71]
	v_mfma_f32_16x16x32_bf16 v[120:123], v[168:171], v[184:187], v[120:123]
	v_mfma_f32_16x16x32_bf16 v[116:119], v[176:179], v[184:187], v[116:119]
	v_mfma_f32_16x16x32_bf16 v[104:107], v[168:171], v[192:195], v[104:107]
	v_mfma_f32_16x16x32_bf16 v[100:103], v[176:179], v[192:195], v[100:103]
	v_mfma_f32_16x16x32_bf16 v[88:91], v[168:171], v[210:213], v[88:91]
	v_mfma_f32_16x16x32_bf16 v[84:87], v[176:179], v[210:213], v[84:87]
	v_mfma_f32_16x16x32_bf16 v[72:75], v[168:171], v[218:221], v[72:75]
	v_mfma_f32_16x16x32_bf16 v[68:71], v[176:179], v[218:221], v[68:71]
	s_barrier
	s_setprio 0
	s_add_i32 s49, s84, s21
	v_lshl_add_u64 v[146:147], s[50:51], 0, v[200:201]
	s_mov_b32 m0, s49
	ds_read_b128 v[180:183], v150 offset:16384
	ds_read_b128 v[184:187], v150 offset:17408
	ds_read_b128 v[188:191], v150 offset:18432
	ds_read_b128 v[192:195], v150 offset:19456
	ds_read_b128 v[196:199], v150 offset:20480
	ds_read_b128 v[210:213], v150 offset:21504
	ds_read_b128 v[214:217], v150 offset:22528
	ds_read_b128 v[218:221], v150 offset:23552
	global_load_lds_dwordx4 v[146:147], off
	s_add_i32 m0, s49, 0x2000
	s_add_u32 s84, s50, 0x20000
	v_lshl_add_u64 v[206:207], s[50:51], 0, v[132:133]
	s_addc_u32 s85, s51, 0
	s_add_i32 s48, s48, s21
	global_load_lds_dwordx4 v[206:207], off
	v_lshl_add_u64 v[208:209], s[84:85], 0, v[200:201]
	s_mov_b32 m0, s48
	v_lshl_add_u64 v[222:223], s[60:61], 0, v[134:135]
	global_load_lds_dwordx4 v[208:209], off
	v_lshl_add_u64 v[208:209], s[84:85], 0, v[132:133]
	s_add_i32 m0, s48, 0x2000
	s_nop 0
	global_load_lds_dwordx4 v[208:209], off
	v_lshl_add_u64 v[208:209], s[60:61], 0, v[136:137]
	s_mov_b32 m0, s23
	s_nop 0
	global_load_lds_dwordx4 v[208:209], off
	s_mov_b32 m0, s42
	s_nop 0
	global_load_lds_dwordx4 v[222:223], off
	s_waitcnt vmcnt(8) lgkmcnt(0)
	s_setprio 1
	s_barrier
; #define PG8_STAGE(bufoff, gbase, voff) do { _Pragma("unroll") for (int _i = 0; _i < 2; ++_i) \
;         __builtin_amdgcn_global_load_lds((const unsigned*)((const char*)(gbase) + (voff)[_i]), (PG8_LAS unsigned*)(lds + (bufoff) + ldsw + _i * 8192), 16, 0, 0); } while (0)
; #define PG8_LDA(dst, b, h) do { _Pragma("unroll") for (int m = 0; m < 4; ++m) _Pragma("unroll") for (int k = 0; k < 2; ++k) dst[m][k] = *(const PG8_LAS bf16x8*)(lds + PG8_SA(b, h) + aoff + m * 2048 + k * 1024); } while (0)
; #define PG8_LDB(dst, b, h) do { _Pragma("unroll") for (int n = 0; n < 2; ++n) _Pragma("unroll") for (int k = 0; k < 2; ++k) dst[n][k] = *(const PG8_LAS bf16x8*)(lds + PG8_SB(b, h) + boff + n * 2048 + k * 1024); } while (0)
; #define PG8_MMA(ai, bj, At, Bt) do { __builtin_amdgcn_s_setprio(1); _Pragma("unroll") for (int m = 0; m < 4; ++m) _Pragma("unroll") for (int n = 0; n < 2; ++n) _Pragma("unroll") for (int k = 0; k < 2; ++k) \
;         acc[ai][bj][m][n] = __builtin_amdgcn_mfma_f32_16x16x32_bf16(Bt[n][k], At[m][k], acc[ai][bj][m][n], 0, 0, 0); __builtin_amdgcn_s_setprio(0); } while (0)
; #define PG8_WAIT_V(n) asm volatile("s_waitcnt vmcnt(" #n ")" ::: "memory")
; #define PG8_WAIT_L(n) asm volatile("s_waitcnt lgkmcnt(" #n ")" ::: "memory")
; #define PG8_BAR __builtin_amdgcn_s_barrier()
; #define PG8_SCHED __builtin_amdgcn_sched_barrier(0)
;     ...
;             PG8_WAIT_V(8); PG8_WAIT_L(0); PG8_BAR; PG8_MMA(0, 0, At, B0); PG8_MMA(0, 1, At, B1); PG8_BAR; PG8_SCHED;
;             PG8_LDA(At, 0, 1); PG8_STAGE(PG8_SB(0, 0), b2, voffB); PG8_STAGE(PG8_SB(0, 1), b2 + hstep, voffB); PG8_STAGE(PG8_SA(0, 0), a2, voffA);
;             PG8_WAIT_V(8); PG8_WAIT_L(0); PG8_BAR; PG8_MMA(1, 0, At, B0); PG8_MMA(1, 1, At, B1); PG8_BAR; PG8_SCHED;
;             PG8_LDB(B0, 1, 0); PG8_LDB(B1, 1, 1); PG8_SCHED; PG8_LDA(At, 1, 0); PG8_STAGE(PG8_SA(0, 1), a2 + hstep, voffA);
;             PG8_WAIT_V(8); PG8_WAIT_L(0); PG8_BAR; PG8_MMA(0, 0, At, B0); PG8_MMA(0, 1, At, B1); PG8_BAR; PG8_SCHED;
;             PG8_LDA(At, 1, 1); PG8_STAGE(PG8_SB(1, 0), b3, voffB); PG8_STAGE(PG8_SB(1, 1), b3 + hstep, voffB); PG8_STAGE(PG8_SA(1, 0), a3, voffA);
;             PG8_WAIT_V(8); PG8_WAIT_L(0); PG8_BAR; PG8_MMA(1, 0, At, B0); PG8_MMA(1, 1, At, B1); PG8_BAR; PG8_SCHED;
	v_mfma_f32_16x16x32_bf16 v[64:67], v[142:145], v[180:183], v[64:67]
	v_mfma_f32_16x16x32_bf16 v[60:63], v[156:159], v[180:183], v[60:63]
	v_mfma_f32_16x16x32_bf16 v[48:51], v[142:145], v[188:191], v[48:51]
	v_mfma_f32_16x16x32_bf16 v[44:47], v[156:159], v[188:191], v[44:47]
	v_mfma_f32_16x16x32_bf16 v[32:35], v[142:145], v[196:199], v[32:35]
	v_mfma_f32_16x16x32_bf16 v[28:31], v[156:159], v[196:199], v[28:31]
	v_mfma_f32_16x16x32_bf16 v[16:19], v[142:145], v[214:217], v[16:19]
	v_mfma_f32_16x16x32_bf16 v[12:15], v[156:159], v[214:217], v[12:15]
	v_mfma_f32_16x16x32_bf16 v[64:67], v[152:155], v[184:187], v[64:67]
	v_mfma_f32_16x16x32_bf16 v[60:63], v[160:163], v[184:187], v[60:63]
	v_mfma_f32_16x16x32_bf16 v[48:51], v[152:155], v[192:195], v[48:51]
	v_mfma_f32_16x16x32_bf16 v[44:47], v[160:163], v[192:195], v[44:47]
	v_mfma_f32_16x16x32_bf16 v[32:35], v[152:155], v[210:213], v[32:35]
	v_mfma_f32_16x16x32_bf16 v[28:31], v[160:163], v[210:213], v[28:31]
	v_mfma_f32_16x16x32_bf16 v[16:19], v[152:155], v[218:221], v[16:19]
	v_mfma_f32_16x16x32_bf16 v[12:15], v[160:163], v[218:221], v[12:15]
	v_mfma_f32_16x16x32_bf16 v[56:59], v[164:167], v[180:183], v[56:59]
	v_mfma_f32_16x16x32_bf16 v[52:55], v[172:175], v[180:183], v[52:55]
	v_mfma_f32_16x16x32_bf16 v[40:43], v[164:167], v[188:191], v[40:43]
	v_mfma_f32_16x16x32_bf16 v[36:39], v[172:175], v[188:191], v[36:39]
	v_mfma_f32_16x16x32_bf16 v[24:27], v[164:167], v[196:199], v[24:27]
	v_mfma_f32_16x16x32_bf16 v[20:23], v[172:175], v[196:199], v[20:23]
	v_mfma_f32_16x16x32_bf16 v[8:11], v[164:167], v[214:217], v[8:11]
	v_mfma_f32_16x16x32_bf16 v[4:7], v[172:175], v[214:217], v[4:7]
	v_mfma_f32_16x16x32_bf16 v[56:59], v[168:171], v[184:187], v[56:59]
	v_mfma_f32_16x16x32_bf16 v[52:55], v[176:179], v[184:187], v[52:55]
	v_mfma_f32_16x16x32_bf16 v[40:43], v[168:171], v[192:195], v[40:43]
	v_mfma_f32_16x16x32_bf16 v[36:39], v[176:179], v[192:195], v[36:39]
	v_mfma_f32_16x16x32_bf16 v[24:27], v[168:171], v[210:213], v[24:27]
	v_mfma_f32_16x16x32_bf16 v[20:23], v[176:179], v[210:213], v[20:23]
	v_mfma_f32_16x16x32_bf16 v[8:11], v[168:171], v[218:221], v[8:11]
	v_mfma_f32_16x16x32_bf16 v[4:7], v[176:179], v[218:221], v[4:7]
	s_barrier
	s_setprio 0
	s_add_i32 s48, 0, 0x18000
	s_add_i32 s49, 0, 0x1c000
	ds_read_b128 v[142:145], v251 offset:32768
	ds_read_b128 v[152:155], v251 offset:33792
	ds_read_b128 v[156:159], v251 offset:34816
	ds_read_b128 v[160:163], v251 offset:35840
	ds_read_b128 v[164:167], v251 offset:49152
	ds_read_b128 v[168:171], v251 offset:50176
	ds_read_b128 v[172:175], v251 offset:51200
	ds_read_b128 v[176:179], v251 offset:52224
	s_add_u32 s60, s60, 0x20000
	s_addc_u32 s61, s61, 0
	s_mov_b32 m0, s44
	v_lshl_add_u64 v[224:225], s[60:61], 0, v[136:137]
	ds_read_b128 v[180:183], v150 offset:32768
	ds_read_b128 v[184:187], v150 offset:33792
	ds_read_b128 v[188:191], v150 offset:34816
	ds_read_b128 v[192:195], v150 offset:35840
	ds_read_b128 v[196:199], v150 offset:36864
	ds_read_b128 v[210:213], v150 offset:37888
	ds_read_b128 v[214:217], v150 offset:38912
	ds_read_b128 v[218:221], v150 offset:39936
	global_load_lds_dwordx4 v[224:225], off
	v_lshl_add_u64 v[224:225], s[60:61], 0, v[134:135]
	s_mov_b32 m0, s52
	s_nop 0
	global_load_lds_dwordx4 v[224:225], off
	s_waitcnt vmcnt(8) lgkmcnt(0)
	s_setprio 1
	s_barrier
	v_mfma_f32_16x16x32_bf16 v[128:131], v[142:145], v[180:183], v[128:131]
	v_mfma_f32_16x16x32_bf16 v[124:127], v[156:159], v[180:183], v[124:127]
	v_mfma_f32_16x16x32_bf16 v[112:115], v[142:145], v[188:191], v[112:115]
	v_mfma_f32_16x16x32_bf16 v[108:111], v[156:159], v[188:191], v[108:111]
	v_mfma_f32_16x16x32_bf16 v[96:99], v[142:145], v[196:199], v[96:99]
	v_mfma_f32_16x16x32_bf16 v[92:95], v[156:159], v[196:199], v[92:95]
	v_mfma_f32_16x16x32_bf16 v[80:83], v[142:145], v[214:217], v[80:83]
	v_mfma_f32_16x16x32_bf16 v[76:79], v[156:159], v[214:217], v[76:79]
	v_mfma_f32_16x16x32_bf16 v[128:131], v[152:155], v[184:187], v[128:131]
	v_mfma_f32_16x16x32_bf16 v[124:127], v[160:163], v[184:187], v[124:127]
	v_mfma_f32_16x16x32_bf16 v[112:115], v[152:155], v[192:195], v[112:115]
	v_mfma_f32_16x16x32_bf16 v[108:111], v[160:163], v[192:195], v[108:111]
	v_mfma_f32_16x16x32_bf16 v[96:99], v[152:155], v[210:213], v[96:99]
	v_mfma_f32_16x16x32_bf16 v[92:95], v[160:163], v[210:213], v[92:95]
	v_mfma_f32_16x16x32_bf16 v[80:83], v[152:155], v[218:221], v[80:83]
	v_mfma_f32_16x16x32_bf16 v[76:79], v[160:163], v[218:221], v[76:79]
	v_mfma_f32_16x16x32_bf16 v[120:123], v[164:167], v[180:183], v[120:123]
	v_mfma_f32_16x16x32_bf16 v[116:119], v[172:175], v[180:183], v[116:119]
	v_mfma_f32_16x16x32_bf16 v[104:107], v[164:167], v[188:191], v[104:107]
	v_mfma_f32_16x16x32_bf16 v[100:103], v[172:175], v[188:191], v[100:103]
	v_mfma_f32_16x16x32_bf16 v[88:91], v[164:167], v[196:199], v[88:91]
	v_mfma_f32_16x16x32_bf16 v[84:87], v[172:175], v[196:199], v[84:87]
	v_mfma_f32_16x16x32_bf16 v[72:75], v[164:167], v[214:217], v[72:75]
	v_mfma_f32_16x16x32_bf16 v[68:71], v[172:175], v[214:217], v[68:71]
	v_mfma_f32_16x16x32_bf16 v[120:123], v[168:171], v[184:187], v[120:123]
	v_mfma_f32_16x16x32_bf16 v[116:119], v[176:179], v[184:187], v[116:119]
	v_mfma_f32_16x16x32_bf16 v[104:107], v[168:171], v[192:195], v[104:107]
	v_mfma_f32_16x16x32_bf16 v[100:103], v[176:179], v[192:195], v[100:103]
	v_mfma_f32_16x16x32_bf16 v[88:91], v[168:171], v[210:213], v[88:91]
	v_mfma_f32_16x16x32_bf16 v[84:87], v[176:179], v[210:213], v[84:87]
	v_mfma_f32_16x16x32_bf16 v[72:75], v[168:171], v[218:221], v[72:75]
	v_mfma_f32_16x16x32_bf16 v[68:71], v[176:179], v[218:221], v[68:71]
	s_barrier
; #define PG8_STAGE(bufoff, gbase, voff) do { _Pragma("unroll") for (int _i = 0; _i < 2; ++_i) \
;         __builtin_amdgcn_global_load_lds((const unsigned*)((const char*)(gbase) + (voff)[_i]), (PG8_LAS unsigned*)(lds + (bufoff) + ldsw + _i * 8192), 16, 0, 0); } while (0)
; #define PG8_LDA(dst, b, h) do { _Pragma("unroll") for (int m = 0; m < 4; ++m) _Pragma("unroll") for (int k = 0; k < 2; ++k) dst[m][k] = *(const PG8_LAS bf16x8*)(lds + PG8_SA(b, h) + aoff + m * 2048 + k * 1024); } while (0)
; #define PG8_MMA(ai, bj, At, Bt) do { __builtin_amdgcn_s_setprio(1); _Pragma("unroll") for (int m = 0; m < 4; ++m) _Pragma("unroll") for (int n = 0; n < 2; ++n) _Pragma("unroll") for (int k = 0; k < 2; ++k) \
;         acc[ai][bj][m][n] = __builtin_amdgcn_mfma_f32_16x16x32_bf16(Bt[n][k], At[m][k], acc[ai][bj][m][n], 0, 0, 0); __builtin_amdgcn_s_setprio(0); } while (0)
; #define PG8_WAIT_V(n) asm volatile("s_waitcnt vmcnt(" #n ")" ::: "memory")
; #define PG8_WAIT_L(n) asm volatile("s_waitcnt lgkmcnt(" #n ")" ::: "memory")
; #define PG8_BAR __builtin_amdgcn_s_barrier()
; #define PG8_SCHED __builtin_amdgcn_sched_barrier(0)
;     __device__ __forceinline__ void operator()(const f32x4 (&acc)[2][2][4][2], const Unit& u, int wr, int wc, int fr_, int fq_, int ui) const {
;     ...
;         const int row0 = u.pm * BM + wr * 64 + fr, dim0 = wc * 32 + 8 * fq;
;         float r[2][4]; load_rs(r, rsl, wr, fr);
; #pragma unroll
;         for (int ai = 0; ai < 2; ++ai)
; #pragma unroll
;             for (int m = 0; m < 4; ++m) { const int row = row0 + ai * HALF + m * 16, b = row >> 12, s = row & 4095;
;     ...
;         for (int t = 0; t < nt; t += 2) {
;             const bool last = (t == nt - 2);
;             const char* a1 = cA + (size_t)(t + 1) * kstep;
;             const char* a2 = last ? nA : cA + (size_t)(t + 2) * kstep; const char* b2 = last ? nB : cB + (size_t)(t + 2) * kstep;
;             const char* a3 = a2 + kstep; const char* b3 = b2 + kstep;
;     ...
;             PG8_LDA(At, 1, 1); PG8_STAGE(PG8_SB(1, 0), b3, voffB); PG8_STAGE(PG8_SB(1, 1), b3 + hstep, voffB); PG8_STAGE(PG8_SA(1, 0), a3, voffA);
;             PG8_WAIT_V(8); PG8_WAIT_L(0); PG8_BAR; PG8_MMA(1, 0, At, B0); PG8_MMA(1, 1, At, B1); PG8_BAR; PG8_SCHED;
	s_setprio 0
	s_add_i32 s48, s48, s21
	v_lshl_add_u64 v[146:147], v[146:147], 0, s[66:67]
	s_mov_b32 m0, s48
	ds_read_b128 v[180:183], v150 offset:49152
	ds_read_b128 v[184:187], v150 offset:50176
	ds_read_b128 v[188:191], v150 offset:51200
	ds_read_b128 v[192:195], v150 offset:52224
	ds_read_b128 v[196:199], v150 offset:53248
	ds_read_b128 v[210:213], v150 offset:54272
	ds_read_b128 v[214:217], v150 offset:55296
	ds_read_b128 v[218:221], v150 offset:56320
	global_load_lds_dwordx4 v[146:147], off
	s_add_i32 m0, s48, 0x2000
	s_add_u32 s50, s50, 0x20080
	v_lshl_add_u64 v[146:147], v[206:207], 0, s[66:67]
	s_addc_u32 s51, s51, 0
	s_add_i32 s48, s49, s21
	global_load_lds_dwordx4 v[146:147], off
	v_lshl_add_u64 v[146:147], s[50:51], 0, v[200:201]
	s_mov_b32 m0, s48
	s_nop 0
	global_load_lds_dwordx4 v[146:147], off
	v_lshl_add_u64 v[146:147], s[50:51], 0, v[132:133]
	s_add_i32 m0, s48, 0x2000
	s_nop 0
	global_load_lds_dwordx4 v[146:147], off
	v_lshl_add_u64 v[146:147], v[208:209], 0, s[66:67]
	s_mov_b32 m0, s54
	s_nop 0
	global_load_lds_dwordx4 v[146:147], off
	v_lshl_add_u64 v[146:147], v[222:223], 0, s[66:67]
	s_mov_b32 m0, s55
	s_nop 0
	global_load_lds_dwordx4 v[146:147], off
	s_waitcnt vmcnt(8) lgkmcnt(0)
	s_setprio 1
	s_barrier
	v_mfma_f32_16x16x32_bf16 v[64:67], v[142:145], v[180:183], v[64:67]
	v_mfma_f32_16x16x32_bf16 v[60:63], v[156:159], v[180:183], v[60:63]
	v_mfma_f32_16x16x32_bf16 v[48:51], v[142:145], v[188:191], v[48:51]
	v_mfma_f32_16x16x32_bf16 v[44:47], v[156:159], v[188:191], v[44:47]
	v_mfma_f32_16x16x32_bf16 v[32:35], v[142:145], v[196:199], v[32:35]
	v_mfma_f32_16x16x32_bf16 v[28:31], v[156:159], v[196:199], v[28:31]
	v_mfma_f32_16x16x32_bf16 v[16:19], v[142:145], v[214:217], v[16:19]
	v_mfma_f32_16x16x32_bf16 v[12:15], v[156:159], v[214:217], v[12:15]
	v_mfma_f32_16x16x32_bf16 v[64:67], v[152:155], v[184:187], v[64:67]
	v_mfma_f32_16x16x32_bf16 v[60:63], v[160:163], v[184:187], v[60:63]
	v_mfma_f32_16x16x32_bf16 v[48:51], v[152:155], v[192:195], v[48:51]
	v_mfma_f32_16x16x32_bf16 v[44:47], v[160:163], v[192:195], v[44:47]
	v_mfma_f32_16x16x32_bf16 v[32:35], v[152:155], v[210:213], v[32:35]
	v_mfma_f32_16x16x32_bf16 v[28:31], v[160:163], v[210:213], v[28:31]
	v_mfma_f32_16x16x32_bf16 v[16:19], v[152:155], v[218:221], v[16:19]
	v_mfma_f32_16x16x32_bf16 v[12:15], v[160:163], v[218:221], v[12:15]
	v_mfma_f32_16x16x32_bf16 v[56:59], v[164:167], v[180:183], v[56:59]
	v_mfma_f32_16x16x32_bf16 v[52:55], v[172:175], v[180:183], v[52:55]
	v_mfma_f32_16x16x32_bf16 v[40:43], v[164:167], v[188:191], v[40:43]
	v_mfma_f32_16x16x32_bf16 v[36:39], v[172:175], v[188:191], v[36:39]
	v_mfma_f32_16x16x32_bf16 v[24:27], v[164:167], v[196:199], v[24:27]
	v_mfma_f32_16x16x32_bf16 v[20:23], v[172:175], v[196:199], v[20:23]
	v_mfma_f32_16x16x32_bf16 v[8:11], v[164:167], v[214:217], v[8:11]
	v_mfma_f32_16x16x32_bf16 v[4:7], v[172:175], v[214:217], v[4:7]
	v_mfma_f32_16x16x32_bf16 v[56:59], v[168:171], v[184:187], v[56:59]
	v_mfma_f32_16x16x32_bf16 v[52:55], v[176:179], v[184:187], v[52:55]
	v_mfma_f32_16x16x32_bf16 v[40:43], v[168:171], v[192:195], v[40:43]
	v_mfma_f32_16x16x32_bf16 v[36:39], v[176:179], v[192:195], v[36:39]
	v_mfma_f32_16x16x32_bf16 v[24:27], v[168:171], v[210:213], v[24:27]
	v_mfma_f32_16x16x32_bf16 v[20:23], v[176:179], v[210:213], v[20:23]
	v_mfma_f32_16x16x32_bf16 v[8:11], v[168:171], v[218:221], v[8:11]
	v_mfma_f32_16x16x32_bf16 v[4:7], v[176:179], v[218:221], v[4:7]
	s_barrier
	s_setprio 0
	s_add_i32 s83, s83, 2
	s_add_u32 s73, s73, 0x100
	s_addc_u32 s81, s81, 0
	s_add_u32 s24, s24, 0x100
	s_addc_u32 s25, s25, 0
	s_cmp_gt_u32 s83, 5
	s_cbranch_scc0 .LBB0_290
	v_mov_b32_e32 v142, v148
	v_mov_b32_e32 v143, v3
	v_readlane_b32 s84, v255, 29
	s_add_i32 s24, s63, s84
	v_add_u32_e32 v151, s56, v143
	v_ashrrev_i32_e32 v156, 12, v151
	s_ashr_i32 s25, s24, 31
	v_ashrrev_i32_e32 v157, 31, v156
	s_lshl_b64 s[24:25], s[24:25], 12
	v_lshlrev_b64 v[156:157], 16, v[156:157]
	v_lshl_add_u32 v143, v143, 2, s58
	v_lshl_add_u64 v[156:157], v[156:157], 0, s[24:25]
	v_lshl_add_u32 v142, v142, 3, s53
	ds_read2_b32 v[152:153], v143 offset1:16
	ds_read2_b32 v[154:155], v143 offset0:32 offset1:48
	ds_read2_b32 v[146:147], v143 offset0:128 offset1:144
	ds_read2_b32 v[144:145], v143 offset0:160 offset1:176
	v_and_or_b32 v156, v151, s17, v156
	v_ashrrev_i32_e32 v143, 31, v142
	v_lshlrev_b64 v[156:157], 7, v[156:157]
	v_lshl_add_u64 v[156:157], v[156:157], 0, v[142:143]
	s_waitcnt lgkmcnt(0)
; #define PG8_G __attribute__((address_space(1)))
; __device__ __forceinline__ u32x4 pack8bf(const f32x4 a, const f32x4 b) { u32x4 w; w.x = cvt_pk_bf16(a[0], a[1]); w.y = cvt_pk_bf16(a[2], a[3]); w.z = cvt_pk_bf16(b[0], b[1]); w.w = cvt_pk_bf16(b[2], b[3]); return w; }
;     __device__ __forceinline__ void operator()(const f32x4 (&acc)[2][2][4][2], const Unit& u, int wr, int wc, int fr_, int fq_, int ui) const {
;     ...
;         const int row0 = u.pm * BM + wr * 64 + fr, dim0 = wc * 32 + 8 * fq;
;         float r[2][4]; load_rs(r, rsl, wr, fr);
; #pragma unroll
;         for (int ai = 0; ai < 2; ++ai)
; #pragma unroll
;             for (int m = 0; m < 4; ++m) { const int row = row0 + ai * HALF + m * 16, b = row >> 12, s = row & 4095;
;                 const size_t o = (((size_t)b * 16 + u.pn) * 4096 + s) * 128 + dim0;
;                 *(PG8_G u32x4*)(KH + o) = pack8bf(acc[ai][0][m][0] * r[ai][m], acc[ai][0][m][1] * r[ai][m]); *(PG8_G u32x4*)(VH + o) = pack8bf(acc[ai][1][m][0] * r[ai][m], acc[ai][1][m][1] * r[ai][m]); }
	v_pk_mul_f32 v[128:129], v[128:129], v[152:153] op_sel_hi:[1,0]
	v_pk_mul_f32 v[130:131], v[130:131], v[152:153] op_sel_hi:[1,0]
	v_pk_mul_f32 v[158:159], v[126:127], v[152:153] op_sel_hi:[1,0]
	v_pk_mul_f32 v[126:127], v[124:125], v[152:153] op_sel_hi:[1,0]
	v_cvt_pk_bf16_f32 v124, v128, v129
	v_lshlrev_b64 v[128:129], 1, v[156:157]
	v_cvt_pk_bf16_f32 v125, v130, v131
	v_lshl_add_u64 v[130:131], s[12:13], 0, v[128:129]
	v_cvt_pk_bf16_f32 v126, v126, v127
	v_cvt_pk_bf16_f32 v127, v158, v159
	global_store_dwordx4 v[130:131], v[124:127], off
	v_pk_mul_f32 v[120:121], v[120:121], v[152:153] op_sel_hi:[1,0]
	v_pk_mul_f32 v[122:123], v[122:123], v[152:153] op_sel_hi:[1,0]
	v_pk_mul_f32 v[124:125], v[118:119], v[152:153] op_sel_hi:[1,0]
	v_pk_mul_f32 v[118:119], v[116:117], v[152:153] op_sel_hi:[1,0]
	v_cvt_pk_bf16_f32 v116, v120, v121
	v_cvt_pk_bf16_f32 v117, v122, v123
	v_lshl_add_u64 v[120:121], s[14:15], 0, v[128:129]
	v_cvt_pk_bf16_f32 v118, v118, v119
	v_cvt_pk_bf16_f32 v119, v124, v125
	global_store_dwordx4 v[120:121], v[116:119], off
	v_pk_mul_f32 v[96:97], v[96:97], v[154:155] op_sel_hi:[1,0]
	v_pk_mul_f32 v[98:99], v[98:99], v[154:155] op_sel_hi:[1,0]
	v_add_u32_e32 v118, 16, v151
	v_ashrrev_i32_e32 v116, 12, v118
	v_ashrrev_i32_e32 v117, 31, v116
	v_lshlrev_b64 v[116:117], 16, v[116:117]
	v_lshl_add_u64 v[116:117], v[116:117], 0, s[24:25]
	v_and_or_b32 v116, v118, s17, v116
	v_lshlrev_b64 v[116:117], 7, v[116:117]
	v_mov_b32_e32 v118, v153
	v_lshl_add_u64 v[116:117], v[116:117], 0, v[142:143]
	v_pk_mul_f32 v[112:113], v[112:113], v[118:119] op_sel_hi:[1,0]
	v_pk_mul_f32 v[114:115], v[114:115], v[118:119] op_sel_hi:[1,0]
	v_pk_mul_f32 v[120:121], v[110:111], v[118:119] op_sel_hi:[1,0]
	v_pk_mul_f32 v[110:111], v[108:109], v[118:119] op_sel_hi:[1,0]
	v_cvt_pk_bf16_f32 v108, v112, v113
	v_lshlrev_b64 v[112:113], 1, v[116:117]
	v_cvt_pk_bf16_f32 v109, v114, v115
	v_lshl_add_u64 v[114:115], s[12:13], 0, v[112:113]
	v_cvt_pk_bf16_f32 v110, v110, v111
	v_cvt_pk_bf16_f32 v111, v120, v121
	global_store_dwordx4 v[114:115], v[108:111], off
	v_pk_mul_f32 v[104:105], v[104:105], v[118:119] op_sel_hi:[1,0]
	v_pk_mul_f32 v[106:107], v[106:107], v[118:119] op_sel_hi:[1,0]
	v_pk_mul_f32 v[108:109], v[102:103], v[118:119] op_sel_hi:[1,0]
	v_pk_mul_f32 v[102:103], v[100:101], v[118:119] op_sel_hi:[1,0]
	v_cvt_pk_bf16_f32 v100, v104, v105
	v_cvt_pk_bf16_f32 v101, v106, v107
	v_lshl_add_u64 v[104:105], s[14:15], 0, v[112:113]
	v_cvt_pk_bf16_f32 v102, v102, v103
	v_cvt_pk_bf16_f32 v103, v108, v109
	global_store_dwordx4 v[104:105], v[100:103], off
	v_pk_mul_f32 v[88:89], v[88:89], v[154:155] op_sel_hi:[1,0]
	v_pk_mul_f32 v[90:91], v[90:91], v[154:155] op_sel_hi:[1,0]
	v_add_u32_e32 v102, 32, v151
	v_ashrrev_i32_e32 v100, 12, v102
	v_ashrrev_i32_e32 v101, 31, v100
	v_lshlrev_b64 v[100:101], 16, v[100:101]
	v_lshl_add_u64 v[100:101], v[100:101], 0, s[24:25]
	v_and_or_b32 v100, v102, s17, v100
	v_lshlrev_b64 v[100:101], 7, v[100:101]
	v_lshl_add_u64 v[100:101], v[100:101], 0, v[142:143]
	v_pk_mul_f32 v[102:103], v[94:95], v[154:155] op_sel_hi:[1,0]
	v_pk_mul_f32 v[94:95], v[92:93], v[154:155] op_sel_hi:[1,0]
	v_cvt_pk_bf16_f32 v92, v96, v97
	v_lshlrev_b64 v[96:97], 1, v[100:101]
	v_cvt_pk_bf16_f32 v93, v98, v99
	v_lshl_add_u64 v[98:99], s[12:13], 0, v[96:97]
	v_cvt_pk_bf16_f32 v94, v94, v95
	v_cvt_pk_bf16_f32 v95, v102, v103
	global_store_dwordx4 v[98:99], v[92:95], off
	v_pk_mul_f32 v[64:65], v[64:65], v[146:147] op_sel_hi:[1,0]
	v_pk_mul_f32 v[66:67], v[66:67], v[146:147] op_sel_hi:[1,0]
	v_pk_mul_f32 v[92:93], v[86:87], v[154:155] op_sel_hi:[1,0]
	v_pk_mul_f32 v[86:87], v[84:85], v[154:155] op_sel_hi:[1,0]
	v_cvt_pk_bf16_f32 v84, v88, v89
	v_cvt_pk_bf16_f32 v85, v90, v91
	v_lshl_add_u64 v[88:89], s[14:15], 0, v[96:97]
	v_cvt_pk_bf16_f32 v86, v86, v87
	v_cvt_pk_bf16_f32 v87, v92, v93
	global_store_dwordx4 v[88:89], v[84:87], off
	v_pk_mul_f32 v[56:57], v[56:57], v[146:147] op_sel_hi:[1,0]
	v_pk_mul_f32 v[58:59], v[58:59], v[146:147] op_sel_hi:[1,0]
	v_add_u32_e32 v86, 48, v151
	v_ashrrev_i32_e32 v84, 12, v86
	v_ashrrev_i32_e32 v85, 31, v84
	v_lshlrev_b64 v[84:85], 16, v[84:85]
	v_lshl_add_u64 v[84:85], v[84:85], 0, s[24:25]
	v_and_or_b32 v84, v86, s17, v84
	v_lshlrev_b64 v[84:85], 7, v[84:85]
	v_mov_b32_e32 v86, v155
	v_lshl_add_u64 v[84:85], v[84:85], 0, v[142:143]
	v_pk_mul_f32 v[80:81], v[80:81], v[86:87] op_sel_hi:[1,0]
	v_pk_mul_f32 v[82:83], v[82:83], v[86:87] op_sel_hi:[1,0]
	v_pk_mul_f32 v[88:89], v[78:79], v[86:87] op_sel_hi:[1,0]
	v_pk_mul_f32 v[78:79], v[76:77], v[86:87] op_sel_hi:[1,0]
	v_cvt_pk_bf16_f32 v76, v80, v81
	v_lshlrev_b64 v[80:81], 1, v[84:85]
	v_cvt_pk_bf16_f32 v77, v82, v83
	v_lshl_add_u64 v[82:83], s[12:13], 0, v[80:81]
	v_cvt_pk_bf16_f32 v78, v78, v79
	v_cvt_pk_bf16_f32 v79, v88, v89
	global_store_dwordx4 v[82:83], v[76:79], off
	v_pk_mul_f32 v[72:73], v[72:73], v[86:87] op_sel_hi:[1,0]
	v_pk_mul_f32 v[74:75], v[74:75], v[86:87] op_sel_hi:[1,0]
	v_pk_mul_f32 v[76:77], v[70:71], v[86:87] op_sel_hi:[1,0]
	v_pk_mul_f32 v[70:71], v[68:69], v[86:87] op_sel_hi:[1,0]
	v_cvt_pk_bf16_f32 v68, v72, v73
	v_cvt_pk_bf16_f32 v69, v74, v75
	v_lshl_add_u64 v[72:73], s[14:15], 0, v[80:81]
; #define PG8_G __attribute__((address_space(1)))
; __device__ __forceinline__ u32x4 pack8bf(const f32x4 a, const f32x4 b) { u32x4 w; w.x = cvt_pk_bf16(a[0], a[1]); w.y = cvt_pk_bf16(a[2], a[3]); w.z = cvt_pk_bf16(b[0], b[1]); w.w = cvt_pk_bf16(b[2], b[3]); return w; }
;     __device__ __forceinline__ bool next(int i, Unit& u) const { if (i >= n) return false; u.pm = pm; u.pn = pn0 + i; return true; }
;     __device__ __forceinline__ bool next(int i, Unit& u) const { if (i) return false; u.pm = pm; u.pn = pn; return true; }
;     __device__ __forceinline__ void operator()(const f32x4 (&acc)[2][2][4][2], const Unit& u, int wr, int wc, int fr_, int fq_, int ui) const {
;     ...
;         const int row0 = u.pm * BM + wr * 64 + fr, dim0 = wc * 32 + 8 * fq;
;         float r[2][4]; load_rs(r, rsl, wr, fr);
; #pragma unroll
;         for (int ai = 0; ai < 2; ++ai)
; #pragma unroll
;             for (int m = 0; m < 4; ++m) { const int row = row0 + ai * HALF + m * 16, b = row >> 12, s = row & 4095;
;                 const size_t o = (((size_t)b * 16 + u.pn) * 4096 + s) * 128 + dim0;
;                 *(PG8_G u32x4*)(KH + o) = pack8bf(acc[ai][0][m][0] * r[ai][m], acc[ai][0][m][1] * r[ai][m]); *(PG8_G u32x4*)(VH + o) = pack8bf(acc[ai][1][m][0] * r[ai][m], acc[ai][1][m][1] * r[ai][m]); }
;     ...
;     for (;;) {
;         const bool has_next = S.next(ui + 1, nxt);
	v_cvt_pk_bf16_f32 v70, v70, v71
	v_cvt_pk_bf16_f32 v71, v76, v77
	global_store_dwordx4 v[72:73], v[68:71], off
	v_pk_mul_f32 v[32:33], v[32:33], v[144:145] op_sel_hi:[1,0]
	v_pk_mul_f32 v[34:35], v[34:35], v[144:145] op_sel_hi:[1,0]
	v_add_u32_e32 v70, 0x80, v151
	v_ashrrev_i32_e32 v68, 12, v70
	v_ashrrev_i32_e32 v69, 31, v68
	v_lshlrev_b64 v[68:69], 16, v[68:69]
	v_lshl_add_u64 v[68:69], v[68:69], 0, s[24:25]
	v_and_or_b32 v68, v70, s17, v68
	v_lshlrev_b64 v[68:69], 7, v[68:69]
	v_lshl_add_u64 v[68:69], v[68:69], 0, v[142:143]
	v_pk_mul_f32 v[70:71], v[62:63], v[146:147] op_sel_hi:[1,0]
	v_pk_mul_f32 v[62:63], v[60:61], v[146:147] op_sel_hi:[1,0]
	v_cvt_pk_bf16_f32 v60, v64, v65
	v_lshlrev_b64 v[64:65], 1, v[68:69]
	v_cvt_pk_bf16_f32 v61, v66, v67
	v_lshl_add_u64 v[66:67], s[12:13], 0, v[64:65]
	v_cvt_pk_bf16_f32 v62, v62, v63
	v_cvt_pk_bf16_f32 v63, v70, v71
	global_store_dwordx4 v[66:67], v[60:63], off
	v_pk_mul_f32 v[24:25], v[24:25], v[144:145] op_sel_hi:[1,0]
	v_pk_mul_f32 v[26:27], v[26:27], v[144:145] op_sel_hi:[1,0]
	v_pk_mul_f32 v[60:61], v[54:55], v[146:147] op_sel_hi:[1,0]
	v_pk_mul_f32 v[54:55], v[52:53], v[146:147] op_sel_hi:[1,0]
	v_cvt_pk_bf16_f32 v52, v56, v57
	v_cvt_pk_bf16_f32 v53, v58, v59
	v_lshl_add_u64 v[56:57], s[14:15], 0, v[64:65]
	v_cvt_pk_bf16_f32 v54, v54, v55
	v_cvt_pk_bf16_f32 v55, v60, v61
	global_store_dwordx4 v[56:57], v[52:55], off
	s_cmp_eq_u32 s62, 8
	s_mov_b32 s63, s62
	v_add_u32_e32 v54, 0x90, v151
	v_ashrrev_i32_e32 v52, 12, v54
	v_ashrrev_i32_e32 v53, 31, v52
	v_lshlrev_b64 v[52:53], 16, v[52:53]
	v_lshl_add_u64 v[52:53], v[52:53], 0, s[24:25]
	v_and_or_b32 v52, v54, s17, v52
	v_lshlrev_b64 v[52:53], 7, v[52:53]
	v_mov_b32_e32 v54, v147
	v_lshl_add_u64 v[52:53], v[52:53], 0, v[142:143]
	v_pk_mul_f32 v[48:49], v[48:49], v[54:55] op_sel_hi:[1,0]
	v_pk_mul_f32 v[50:51], v[50:51], v[54:55] op_sel_hi:[1,0]
	v_pk_mul_f32 v[56:57], v[46:47], v[54:55] op_sel_hi:[1,0]
	v_pk_mul_f32 v[46:47], v[44:45], v[54:55] op_sel_hi:[1,0]
	v_cvt_pk_bf16_f32 v44, v48, v49
	v_lshlrev_b64 v[48:49], 1, v[52:53]
	v_cvt_pk_bf16_f32 v45, v50, v51
	v_lshl_add_u64 v[50:51], s[12:13], 0, v[48:49]
	v_cvt_pk_bf16_f32 v46, v46, v47
	v_cvt_pk_bf16_f32 v47, v56, v57
	global_store_dwordx4 v[50:51], v[44:47], off
	v_pk_mul_f32 v[40:41], v[40:41], v[54:55] op_sel_hi:[1,0]
	v_pk_mul_f32 v[42:43], v[42:43], v[54:55] op_sel_hi:[1,0]
	v_pk_mul_f32 v[44:45], v[38:39], v[54:55] op_sel_hi:[1,0]
	v_pk_mul_f32 v[38:39], v[36:37], v[54:55] op_sel_hi:[1,0]
	v_cvt_pk_bf16_f32 v36, v40, v41
	v_cvt_pk_bf16_f32 v37, v42, v43
	v_lshl_add_u64 v[40:41], s[14:15], 0, v[48:49]
	v_cvt_pk_bf16_f32 v38, v38, v39
	v_cvt_pk_bf16_f32 v39, v44, v45
	global_store_dwordx4 v[40:41], v[36:39], off
	v_readlane_b32 s85, v255, 30
	s_nop 0
	v_add_u32_e32 v38, 0xa0, v151
	v_ashrrev_i32_e32 v36, 12, v38
	v_ashrrev_i32_e32 v37, 31, v36
	v_lshlrev_b64 v[36:37], 16, v[36:37]
	v_lshl_add_u64 v[36:37], v[36:37], 0, s[24:25]
	v_and_or_b32 v36, v38, s17, v36
	v_lshlrev_b64 v[36:37], 7, v[36:37]
	v_lshl_add_u64 v[36:37], v[36:37], 0, v[142:143]
	v_pk_mul_f32 v[38:39], v[30:31], v[144:145] op_sel_hi:[1,0]
	v_pk_mul_f32 v[30:31], v[28:29], v[144:145] op_sel_hi:[1,0]
	v_cvt_pk_bf16_f32 v28, v32, v33
	v_lshlrev_b64 v[32:33], 1, v[36:37]
	v_cvt_pk_bf16_f32 v29, v34, v35
	v_lshl_add_u64 v[34:35], s[12:13], 0, v[32:33]
	v_cvt_pk_bf16_f32 v30, v30, v31
	v_cvt_pk_bf16_f32 v31, v38, v39
	global_store_dwordx4 v[34:35], v[28:31], off
	s_nop 1
	v_pk_mul_f32 v[28:29], v[22:23], v[144:145] op_sel_hi:[1,0]
	v_pk_mul_f32 v[22:23], v[20:21], v[144:145] op_sel_hi:[1,0]
	v_cvt_pk_bf16_f32 v20, v24, v25
	v_cvt_pk_bf16_f32 v21, v26, v27
	v_lshl_add_u64 v[24:25], s[14:15], 0, v[32:33]
	v_cvt_pk_bf16_f32 v22, v22, v23
	v_cvt_pk_bf16_f32 v23, v28, v29
	global_store_dwordx4 v[24:25], v[20:23], off
	s_nop 1
	v_add_u32_e32 v22, 0xb0, v151
	v_ashrrev_i32_e32 v20, 12, v22
	v_ashrrev_i32_e32 v21, 31, v20
	v_lshlrev_b64 v[20:21], 16, v[20:21]
	v_lshl_add_u64 v[20:21], v[20:21], 0, s[24:25]
	v_and_or_b32 v20, v22, s17, v20
	v_lshlrev_b64 v[20:21], 7, v[20:21]
	v_mov_b32_e32 v22, v145
	v_lshl_add_u64 v[20:21], v[20:21], 0, v[142:143]
	v_pk_mul_f32 v[16:17], v[16:17], v[22:23] op_sel_hi:[1,0]
	v_pk_mul_f32 v[18:19], v[18:19], v[22:23] op_sel_hi:[1,0]
	v_pk_mul_f32 v[24:25], v[14:15], v[22:23] op_sel_hi:[1,0]
	v_pk_mul_f32 v[14:15], v[12:13], v[22:23] op_sel_hi:[1,0]
	v_cvt_pk_bf16_f32 v12, v16, v17
	v_lshlrev_b64 v[16:17], 1, v[20:21]
	v_cvt_pk_bf16_f32 v13, v18, v19
	v_lshl_add_u64 v[18:19], s[12:13], 0, v[16:17]
	v_pk_mul_f32 v[8:9], v[8:9], v[22:23] op_sel_hi:[1,0]
	v_cvt_pk_bf16_f32 v14, v14, v15
	v_cvt_pk_bf16_f32 v15, v24, v25
	global_store_dwordx4 v[18:19], v[12:15], off
	v_pk_mul_f32 v[10:11], v[10:11], v[22:23] op_sel_hi:[1,0]
	s_nop 0
	v_pk_mul_f32 v[12:13], v[6:7], v[22:23] op_sel_hi:[1,0]
	v_pk_mul_f32 v[6:7], v[4:5], v[22:23] op_sel_hi:[1,0]
	v_cvt_pk_bf16_f32 v4, v8, v9
	v_lshl_add_u64 v[8:9], s[14:15], 0, v[16:17]
	v_cvt_pk_bf16_f32 v5, v10, v11
	v_cvt_pk_bf16_f32 v6, v6, v7
	v_cvt_pk_bf16_f32 v7, v12, v13
	global_store_dwordx4 v[8:9], v[4:7], off
	s_cbranch_scc0 .LBB0_289
	s_waitcnt vmcnt(0)
	s_cmpk_gt_u32 s20, 0xff
	s_cbranch_scc1 .LBB0_294
	s_barrier

; #define PG8_STAGE(bufoff, gbase, voff) do { _Pragma("unroll") for (int _i = 0; _i < 2; ++_i) \
;         __builtin_amdgcn_global_load_lds((const unsigned*)((const char*)(gbase) + (voff)[_i]), (PG8_LAS unsigned*)(lds + (bufoff) + ldsw + _i * 8192), 16, 0, 0); } while (0)
; #define PG8_LDA(dst, b, h) do { _Pragma("unroll") for (int m = 0; m < 4; ++m) _Pragma("unroll") for (int k = 0; k < 2; ++k) dst[m][k] = *(const PG8_LAS bf16x8*)(lds + PG8_SA(b, h) + aoff + m * 2048 + k * 1024); } while (0)
; #define PG8_LDB(dst, b, h) do { _Pragma("unroll") for (int n = 0; n < 2; ++n) _Pragma("unroll") for (int k = 0; k < 2; ++k) dst[n][k] = *(const PG8_LAS bf16x8*)(lds + PG8_SB(b, h) + boff + n * 2048 + k * 1024); } while (0)
; #define PG8_MMA(ai, bj, At, Bt) do { __builtin_amdgcn_s_setprio(1); _Pragma("unroll") for (int m = 0; m < 4; ++m) _Pragma("unroll") for (int n = 0; n < 2; ++n) _Pragma("unroll") for (int k = 0; k < 2; ++k) \
;         acc[ai][bj][m][n] = __builtin_amdgcn_mfma_f32_16x16x32_bf16(Bt[n][k], At[m][k], acc[ai][bj][m][n], 0, 0, 0); __builtin_amdgcn_s_setprio(0); } while (0)
; #define PG8_WAIT_V(n) asm volatile("s_waitcnt vmcnt(" #n ")" ::: "memory")
;     ...
;             const char* a1 = cA + (size_t)(t + 1) * kstep;
;             const char* a2 = last ? nA : cA + (size_t)(t + 2) * kstep; const char* b2 = last ? nB : cB + (size_t)(t + 2) * kstep;
;             const char* a3 = a2 + kstep; const char* b3 = b2 + kstep;
;             if (last && has_next) S.a_ready(nxt);
;             if (t == 0) E.pre_issue(pre, cur, tid, ui); else if (t == 2) E.pre_finish(pre, tid, ui);
;             if constexpr (SP2) {
;             PG8_LDB(B0, 0, 0); PG8_LDB(B1, 0, 1); PG8_SCHED; PG8_LDA(At, 0, 0); PG8_STAGE(PG8_SA(1, 1), a1 + hstep, voffA);
;             PG8_WAIT_V(8); PG8_WAIT_L(0); PG8_BAR; PG8_MMA(0, 0, At, B0); PG8_MMA(0, 1, At, B1); PG8_BAR; PG8_SCHED;
;             PG8_LDA(At, 0, 1); PG8_STAGE(PG8_SB(0, 0), b2, voffB); PG8_STAGE(PG8_SB(0, 1), b2 + hstep, voffB); PG8_STAGE(PG8_SA(0, 0), a2, voffA);
;             PG8_WAIT_V(8); PG8_WAIT_L(0); PG8_BAR; PG8_MMA(1, 0, At, B0); PG8_MMA(1, 1, At, B1); PG8_BAR; PG8_SCHED;
;             PG8_LDB(B0, 1, 0); PG8_LDB(B1, 1, 1); PG8_SCHED; PG8_LDA(At, 1, 0); PG8_STAGE(PG8_SA(0, 1), a2 + hstep, voffA);
;             PG8_WAIT_V(8); PG8_WAIT_L(0); PG8_BAR; PG8_MMA(0, 0, At, B0); PG8_MMA(0, 1, At, B1); PG8_BAR; PG8_SCHED;
.LBB0_301:
	s_add_u32 s24, s14, 0xfffe0080
	s_addc_u32 s25, s15, -1
	s_add_i32 s48, 0, 0x10000
	s_cmp_eq_u32 s54, 4
	s_cselect_b32 s51, s21, s25
	s_cselect_b32 s50, s23, s24
	s_cselect_b32 s25, s42, s53
	s_cselect_b32 s24, s44, s52
	s_add_i32 s49, 0, 0x14000
	ds_read_b128 v[132:135], v251
	ds_read_b128 v[146:149], v251 offset:1024
	ds_read_b128 v[150:153], v251 offset:2048
	ds_read_b128 v[154:157], v251 offset:3072
	ds_read_b128 v[158:161], v251 offset:16384
	ds_read_b128 v[162:165], v251 offset:17408
	ds_read_b128 v[166:169], v251 offset:18432
	ds_read_b128 v[176:179], v251 offset:19456
	v_lshl_add_u64 v[170:171], s[14:15], 0, v[144:145]
	s_add_i32 m0, s62, 0xc000
	ds_read_b128 v[180:183], v174
	ds_read_b128 v[184:187], v174 offset:1024
	ds_read_b128 v[188:191], v174 offset:2048
	ds_read_b128 v[192:195], v174 offset:3072
	ds_read_b128 v[196:199], v174 offset:4096
	ds_read_b128 v[210:213], v174 offset:5120
	ds_read_b128 v[214:217], v174 offset:6144
	ds_read_b128 v[218:221], v174 offset:7168
	global_load_lds_dwordx4 v[170:171], off
	v_lshl_add_u64 v[170:171], s[14:15], 0, v[142:143]
	s_add_i32 m0, s62, 0xe000
	s_nop 0
	global_load_lds_dwordx4 v[170:171], off
	s_waitcnt vmcnt(8) lgkmcnt(0)
	s_setprio 1
	s_barrier
	v_mfma_f32_16x16x32_bf16 v[128:131], v[132:135], v[180:183], v[128:131]
	v_mfma_f32_16x16x32_bf16 v[124:127], v[150:153], v[180:183], v[124:127]
	v_mfma_f32_16x16x32_bf16 v[116:119], v[132:135], v[188:191], v[116:119]
	v_mfma_f32_16x16x32_bf16 v[108:111], v[150:153], v[188:191], v[108:111]
	v_mfma_f32_16x16x32_bf16 v[100:103], v[132:135], v[196:199], v[100:103]
	v_mfma_f32_16x16x32_bf16 v[92:95], v[150:153], v[196:199], v[92:95]
	v_mfma_f32_16x16x32_bf16 v[84:87], v[132:135], v[214:217], v[84:87]
	v_mfma_f32_16x16x32_bf16 v[76:79], v[150:153], v[214:217], v[76:79]
	v_mfma_f32_16x16x32_bf16 v[128:131], v[146:149], v[184:187], v[128:131]
	v_mfma_f32_16x16x32_bf16 v[124:127], v[154:157], v[184:187], v[124:127]
	v_mfma_f32_16x16x32_bf16 v[116:119], v[146:149], v[192:195], v[116:119]
	v_mfma_f32_16x16x32_bf16 v[108:111], v[154:157], v[192:195], v[108:111]
	v_mfma_f32_16x16x32_bf16 v[100:103], v[146:149], v[210:213], v[100:103]
	v_mfma_f32_16x16x32_bf16 v[92:95], v[154:157], v[210:213], v[92:95]
	v_mfma_f32_16x16x32_bf16 v[84:87], v[146:149], v[218:221], v[84:87]
	v_mfma_f32_16x16x32_bf16 v[76:79], v[154:157], v[218:221], v[76:79]
	v_mfma_f32_16x16x32_bf16 v[120:123], v[158:161], v[180:183], v[120:123]
	v_mfma_f32_16x16x32_bf16 v[112:115], v[166:169], v[180:183], v[112:115]
	v_mfma_f32_16x16x32_bf16 v[104:107], v[158:161], v[188:191], v[104:107]
	v_mfma_f32_16x16x32_bf16 v[96:99], v[166:169], v[188:191], v[96:99]
	v_mfma_f32_16x16x32_bf16 v[88:91], v[158:161], v[196:199], v[88:91]
	v_mfma_f32_16x16x32_bf16 v[80:83], v[166:169], v[196:199], v[80:83]
	v_mfma_f32_16x16x32_bf16 v[72:75], v[158:161], v[214:217], v[72:75]
	v_mfma_f32_16x16x32_bf16 v[68:71], v[166:169], v[214:217], v[68:71]
	v_mfma_f32_16x16x32_bf16 v[120:123], v[162:165], v[184:187], v[120:123]
	v_mfma_f32_16x16x32_bf16 v[112:115], v[176:179], v[184:187], v[112:115]
	v_mfma_f32_16x16x32_bf16 v[104:107], v[162:165], v[192:195], v[104:107]
	v_mfma_f32_16x16x32_bf16 v[96:99], v[176:179], v[192:195], v[96:99]
	v_mfma_f32_16x16x32_bf16 v[88:91], v[162:165], v[210:213], v[88:91]
	v_mfma_f32_16x16x32_bf16 v[80:83], v[176:179], v[210:213], v[80:83]
	v_mfma_f32_16x16x32_bf16 v[72:75], v[162:165], v[218:221], v[72:75]
	v_mfma_f32_16x16x32_bf16 v[68:71], v[176:179], v[218:221], v[68:71]
	s_barrier
	s_setprio 0
	s_add_i32 s48, s48, s61
	v_lshl_add_u64 v[170:171], s[24:25], 0, v[200:201]
	s_mov_b32 m0, s48
	ds_read_b128 v[180:183], v174 offset:16384
	ds_read_b128 v[184:187], v174 offset:17408
	ds_read_b128 v[188:191], v174 offset:18432
	ds_read_b128 v[192:195], v174 offset:19456
	ds_read_b128 v[196:199], v174 offset:20480
	ds_read_b128 v[210:213], v174 offset:21504
	ds_read_b128 v[214:217], v174 offset:22528
	ds_read_b128 v[218:221], v174 offset:23552
	global_load_lds_dwordx4 v[170:171], off
	s_add_i32 m0, s48, 0x2000
	s_add_u32 s84, s24, 0x20000
	v_lshl_add_u64 v[206:207], s[24:25], 0, v[136:137]
	s_addc_u32 s85, s25, 0
	s_add_i32 s48, s49, s61
	global_load_lds_dwordx4 v[206:207], off
	v_lshl_add_u64 v[208:209], s[84:85], 0, v[200:201]
	s_mov_b32 m0, s48
	v_lshl_add_u64 v[222:223], s[50:51], 0, v[138:139]
	global_load_lds_dwordx4 v[208:209], off
	v_lshl_add_u64 v[208:209], s[84:85], 0, v[136:137]
	s_add_i32 m0, s48, 0x2000
	s_nop 0
	global_load_lds_dwordx4 v[208:209], off
	v_lshl_add_u64 v[208:209], s[50:51], 0, v[140:141]
	s_mov_b32 m0, s62
	s_nop 0
	global_load_lds_dwordx4 v[208:209], off
	s_mov_b32 m0, s63
	s_nop 0
	global_load_lds_dwordx4 v[222:223], off
	s_waitcnt vmcnt(8) lgkmcnt(0)
	s_setprio 1
	s_barrier
; #define PG8_STAGE(bufoff, gbase, voff) do { _Pragma("unroll") for (int _i = 0; _i < 2; ++_i) \
;         __builtin_amdgcn_global_load_lds((const unsigned*)((const char*)(gbase) + (voff)[_i]), (PG8_LAS unsigned*)(lds + (bufoff) + ldsw + _i * 8192), 16, 0, 0); } while (0)
; #define PG8_LDA(dst, b, h) do { _Pragma("unroll") for (int m = 0; m < 4; ++m) _Pragma("unroll") for (int k = 0; k < 2; ++k) dst[m][k] = *(const PG8_LAS bf16x8*)(lds + PG8_SA(b, h) + aoff + m * 2048 + k * 1024); } while (0)
; #define PG8_LDB(dst, b, h) do { _Pragma("unroll") for (int n = 0; n < 2; ++n) _Pragma("unroll") for (int k = 0; k < 2; ++k) dst[n][k] = *(const PG8_LAS bf16x8*)(lds + PG8_SB(b, h) + boff + n * 2048 + k * 1024); } while (0)
; #define PG8_MMA(ai, bj, At, Bt) do { __builtin_amdgcn_s_setprio(1); _Pragma("unroll") for (int m = 0; m < 4; ++m) _Pragma("unroll") for (int n = 0; n < 2; ++n) _Pragma("unroll") for (int k = 0; k < 2; ++k) \
;         acc[ai][bj][m][n] = __builtin_amdgcn_mfma_f32_16x16x32_bf16(Bt[n][k], At[m][k], acc[ai][bj][m][n], 0, 0, 0); __builtin_amdgcn_s_setprio(0); } while (0)
; #define PG8_WAIT_V(n) asm volatile("s_waitcnt vmcnt(" #n ")" ::: "memory")
; #define PG8_WAIT_L(n) asm volatile("s_waitcnt lgkmcnt(" #n ")" ::: "memory")
; #define PG8_BAR __builtin_amdgcn_s_barrier()
; #define PG8_SCHED __builtin_amdgcn_sched_barrier(0)
;     ...
;             PG8_WAIT_V(8); PG8_WAIT_L(0); PG8_BAR; PG8_MMA(1, 0, At, B0); PG8_MMA(1, 1, At, B1); PG8_BAR; PG8_SCHED;
;             PG8_LDB(B0, 1, 0); PG8_LDB(B1, 1, 1); PG8_SCHED; PG8_LDA(At, 1, 0); PG8_STAGE(PG8_SA(0, 1), a2 + hstep, voffA);
;             PG8_WAIT_V(8); PG8_WAIT_L(0); PG8_BAR; PG8_MMA(0, 0, At, B0); PG8_MMA(0, 1, At, B1); PG8_BAR; PG8_SCHED;
;             PG8_LDA(At, 1, 1); PG8_STAGE(PG8_SB(1, 0), b3, voffB); PG8_STAGE(PG8_SB(1, 1), b3 + hstep, voffB); PG8_STAGE(PG8_SA(1, 0), a3, voffA);
;             PG8_WAIT_V(8); PG8_WAIT_L(0); PG8_BAR; PG8_MMA(1, 0, At, B0); PG8_MMA(1, 1, At, B1); PG8_BAR; PG8_SCHED;
	v_mfma_f32_16x16x32_bf16 v[64:67], v[132:135], v[180:183], v[64:67]
	v_mfma_f32_16x16x32_bf16 v[60:63], v[150:153], v[180:183], v[60:63]
	v_mfma_f32_16x16x32_bf16 v[52:55], v[132:135], v[188:191], v[52:55]
	v_mfma_f32_16x16x32_bf16 v[44:47], v[150:153], v[188:191], v[44:47]
	v_mfma_f32_16x16x32_bf16 v[36:39], v[132:135], v[196:199], v[36:39]
	v_mfma_f32_16x16x32_bf16 v[28:31], v[150:153], v[196:199], v[28:31]
	v_mfma_f32_16x16x32_bf16 v[20:23], v[132:135], v[214:217], v[20:23]
	v_mfma_f32_16x16x32_bf16 v[12:15], v[150:153], v[214:217], v[12:15]
	v_mfma_f32_16x16x32_bf16 v[64:67], v[146:149], v[184:187], v[64:67]
	v_mfma_f32_16x16x32_bf16 v[60:63], v[154:157], v[184:187], v[60:63]
	v_mfma_f32_16x16x32_bf16 v[52:55], v[146:149], v[192:195], v[52:55]
	v_mfma_f32_16x16x32_bf16 v[44:47], v[154:157], v[192:195], v[44:47]
	v_mfma_f32_16x16x32_bf16 v[36:39], v[146:149], v[210:213], v[36:39]
	v_mfma_f32_16x16x32_bf16 v[28:31], v[154:157], v[210:213], v[28:31]
	v_mfma_f32_16x16x32_bf16 v[20:23], v[146:149], v[218:221], v[20:23]
	v_mfma_f32_16x16x32_bf16 v[12:15], v[154:157], v[218:221], v[12:15]
	v_mfma_f32_16x16x32_bf16 v[56:59], v[158:161], v[180:183], v[56:59]
	v_mfma_f32_16x16x32_bf16 v[48:51], v[166:169], v[180:183], v[48:51]
	v_mfma_f32_16x16x32_bf16 v[40:43], v[158:161], v[188:191], v[40:43]
	v_mfma_f32_16x16x32_bf16 v[32:35], v[166:169], v[188:191], v[32:35]
	v_mfma_f32_16x16x32_bf16 v[24:27], v[158:161], v[196:199], v[24:27]
	v_mfma_f32_16x16x32_bf16 v[16:19], v[166:169], v[196:199], v[16:19]
	v_mfma_f32_16x16x32_bf16 v[8:11], v[158:161], v[214:217], v[8:11]
	v_mfma_f32_16x16x32_bf16 v[4:7], v[166:169], v[214:217], v[4:7]
	v_mfma_f32_16x16x32_bf16 v[56:59], v[162:165], v[184:187], v[56:59]
	v_mfma_f32_16x16x32_bf16 v[48:51], v[176:179], v[184:187], v[48:51]
	v_mfma_f32_16x16x32_bf16 v[40:43], v[162:165], v[192:195], v[40:43]
	v_mfma_f32_16x16x32_bf16 v[32:35], v[176:179], v[192:195], v[32:35]
	v_mfma_f32_16x16x32_bf16 v[24:27], v[162:165], v[210:213], v[24:27]
	v_mfma_f32_16x16x32_bf16 v[16:19], v[176:179], v[210:213], v[16:19]
	v_mfma_f32_16x16x32_bf16 v[8:11], v[162:165], v[218:221], v[8:11]
	v_mfma_f32_16x16x32_bf16 v[4:7], v[176:179], v[218:221], v[4:7]
	s_barrier
	s_setprio 0
	s_add_i32 s48, 0, 0x18000
	s_add_i32 s49, 0, 0x1c000
	ds_read_b128 v[132:135], v251 offset:32768
	ds_read_b128 v[146:149], v251 offset:33792
	ds_read_b128 v[150:153], v251 offset:34816
	ds_read_b128 v[154:157], v251 offset:35840
	ds_read_b128 v[158:161], v251 offset:49152
	ds_read_b128 v[162:165], v251 offset:50176
	ds_read_b128 v[166:169], v251 offset:51200
	ds_read_b128 v[176:179], v251 offset:52224
	s_add_u32 s50, s50, 0x20000
	s_addc_u32 s51, s51, 0
	s_mov_b32 m0, s68
	v_lshl_add_u64 v[224:225], s[50:51], 0, v[140:141]
	ds_read_b128 v[180:183], v174 offset:32768
	ds_read_b128 v[184:187], v174 offset:33792
	ds_read_b128 v[188:191], v174 offset:34816
	ds_read_b128 v[192:195], v174 offset:35840
	ds_read_b128 v[196:199], v174 offset:36864
	ds_read_b128 v[210:213], v174 offset:37888
	ds_read_b128 v[214:217], v174 offset:38912
	ds_read_b128 v[218:221], v174 offset:39936
	global_load_lds_dwordx4 v[224:225], off
	v_lshl_add_u64 v[224:225], s[50:51], 0, v[138:139]
	s_mov_b32 m0, s69
	s_nop 0
	global_load_lds_dwordx4 v[224:225], off
	s_waitcnt vmcnt(8) lgkmcnt(0)
	s_setprio 1
	s_barrier
	v_mfma_f32_16x16x32_bf16 v[128:131], v[132:135], v[180:183], v[128:131]
	v_mfma_f32_16x16x32_bf16 v[124:127], v[150:153], v[180:183], v[124:127]
	v_mfma_f32_16x16x32_bf16 v[116:119], v[132:135], v[188:191], v[116:119]
	v_mfma_f32_16x16x32_bf16 v[108:111], v[150:153], v[188:191], v[108:111]
	v_mfma_f32_16x16x32_bf16 v[100:103], v[132:135], v[196:199], v[100:103]
	v_mfma_f32_16x16x32_bf16 v[92:95], v[150:153], v[196:199], v[92:95]
	v_mfma_f32_16x16x32_bf16 v[84:87], v[132:135], v[214:217], v[84:87]
	v_mfma_f32_16x16x32_bf16 v[76:79], v[150:153], v[214:217], v[76:79]
	v_mfma_f32_16x16x32_bf16 v[128:131], v[146:149], v[184:187], v[128:131]
	v_mfma_f32_16x16x32_bf16 v[124:127], v[154:157], v[184:187], v[124:127]
	v_mfma_f32_16x16x32_bf16 v[116:119], v[146:149], v[192:195], v[116:119]
	v_mfma_f32_16x16x32_bf16 v[108:111], v[154:157], v[192:195], v[108:111]
	v_mfma_f32_16x16x32_bf16 v[100:103], v[146:149], v[210:213], v[100:103]
	v_mfma_f32_16x16x32_bf16 v[92:95], v[154:157], v[210:213], v[92:95]
	v_mfma_f32_16x16x32_bf16 v[84:87], v[146:149], v[218:221], v[84:87]
	v_mfma_f32_16x16x32_bf16 v[76:79], v[154:157], v[218:221], v[76:79]
	v_mfma_f32_16x16x32_bf16 v[120:123], v[158:161], v[180:183], v[120:123]
	v_mfma_f32_16x16x32_bf16 v[112:115], v[166:169], v[180:183], v[112:115]
	v_mfma_f32_16x16x32_bf16 v[104:107], v[158:161], v[188:191], v[104:107]
	v_mfma_f32_16x16x32_bf16 v[96:99], v[166:169], v[188:191], v[96:99]
	v_mfma_f32_16x16x32_bf16 v[88:91], v[158:161], v[196:199], v[88:91]
	v_mfma_f32_16x16x32_bf16 v[80:83], v[166:169], v[196:199], v[80:83]
	v_mfma_f32_16x16x32_bf16 v[72:75], v[158:161], v[214:217], v[72:75]
	v_mfma_f32_16x16x32_bf16 v[68:71], v[166:169], v[214:217], v[68:71]
	v_mfma_f32_16x16x32_bf16 v[120:123], v[162:165], v[184:187], v[120:123]
	v_mfma_f32_16x16x32_bf16 v[112:115], v[176:179], v[184:187], v[112:115]
	v_mfma_f32_16x16x32_bf16 v[104:107], v[162:165], v[192:195], v[104:107]
	v_mfma_f32_16x16x32_bf16 v[96:99], v[176:179], v[192:195], v[96:99]
	v_mfma_f32_16x16x32_bf16 v[88:91], v[162:165], v[210:213], v[88:91]
	v_mfma_f32_16x16x32_bf16 v[80:83], v[176:179], v[210:213], v[80:83]
	v_mfma_f32_16x16x32_bf16 v[72:75], v[162:165], v[218:221], v[72:75]
	v_mfma_f32_16x16x32_bf16 v[68:71], v[176:179], v[218:221], v[68:71]
	s_barrier
; #define PG8_G __attribute__((address_space(1)))
; __device__ __forceinline__ u32x4 pack8bf(const f32x4 a, const f32x4 b) { u32x4 w; w.x = cvt_pk_bf16(a[0], a[1]); w.y = cvt_pk_bf16(a[2], a[3]); w.z = cvt_pk_bf16(b[0], b[1]); w.w = cvt_pk_bf16(b[2], b[3]); return w; }
; #define PG8_STAGE(bufoff, gbase, voff) do { _Pragma("unroll") for (int _i = 0; _i < 2; ++_i) \
;         __builtin_amdgcn_global_load_lds((const unsigned*)((const char*)(gbase) + (voff)[_i]), (PG8_LAS unsigned*)(lds + (bufoff) + ldsw + _i * 8192), 16, 0, 0); } while (0)
; #define PG8_LDA(dst, b, h) do { _Pragma("unroll") for (int m = 0; m < 4; ++m) _Pragma("unroll") for (int k = 0; k < 2; ++k) dst[m][k] = *(const PG8_LAS bf16x8*)(lds + PG8_SA(b, h) + aoff + m * 2048 + k * 1024); } while (0)
; #define PG8_MMA(ai, bj, At, Bt) do { __builtin_amdgcn_s_setprio(1); _Pragma("unroll") for (int m = 0; m < 4; ++m) _Pragma("unroll") for (int n = 0; n < 2; ++n) _Pragma("unroll") for (int k = 0; k < 2; ++k) \
;         acc[ai][bj][m][n] = __builtin_amdgcn_mfma_f32_16x16x32_bf16(Bt[n][k], At[m][k], acc[ai][bj][m][n], 0, 0, 0); __builtin_amdgcn_s_setprio(0); } while (0)
; #define PG8_WAIT_V(n) asm volatile("s_waitcnt vmcnt(" #n ")" ::: "memory")
; #define PG8_BAR __builtin_amdgcn_s_barrier()
;     __device__ __forceinline__ void operator()(const f32x4 (&acc)[2][2][4][2], const Unit& u, int wr, int wc, int fr_, int fq_, int ui) const {
;         int fr = fr_, fq = fq_; asm volatile("" : "+v"(fr), "+v"(fq));
;         const int row0 = u.pm * BM + wr * 64 + fr;
;         float r[2][4]; load_rs(r, rsl, wr, fr);
;         if (u.pn < 8) {
;             const int col0 = u.pn * BM + wc * 32 + 8 * fq;
; #pragma unroll
;             for (int ai = 0; ai < 2; ++ai)
; #pragma unroll
;                 for (int m = 0; m < 4; ++m) { bf16_t* rowp = Q + (size_t)(row0 + ai * HALF + m * 16) * 3072 + col0;
; #pragma unroll
;                     for (int bj = 0; bj < 2; ++bj) *(PG8_G u32x4*)(rowp + bj * HALF) = pack8bf(acc[ai][bj][m][0] * r[ai][m], acc[ai][bj][m][1] * r[ai][m]); }
;         } else {
;             const int head = 4 * (u.pn - 8) + wc, i0 = 8 * fq;
;     ...
;             PG8_LDA(At, 1, 1); PG8_STAGE(PG8_SB(1, 0), b3, voffB); PG8_STAGE(PG8_SB(1, 1), b3 + hstep, voffB); PG8_STAGE(PG8_SA(1, 0), a3, voffA);
;             PG8_WAIT_V(8); PG8_WAIT_L(0); PG8_BAR; PG8_MMA(1, 0, At, B0); PG8_MMA(1, 1, At, B1); PG8_BAR; PG8_SCHED;
	s_setprio 0
	s_add_i32 s48, s48, s61
	v_lshl_add_u64 v[170:171], v[170:171], 0, s[66:67]
	s_mov_b32 m0, s48
	ds_read_b128 v[180:183], v174 offset:49152
	ds_read_b128 v[184:187], v174 offset:50176
	ds_read_b128 v[188:191], v174 offset:51200
	ds_read_b128 v[192:195], v174 offset:52224
	ds_read_b128 v[196:199], v174 offset:53248
	ds_read_b128 v[210:213], v174 offset:54272
	ds_read_b128 v[214:217], v174 offset:55296
	ds_read_b128 v[218:221], v174 offset:56320
	global_load_lds_dwordx4 v[170:171], off
	s_add_i32 m0, s48, 0x2000
	s_add_u32 s24, s24, 0x20080
	v_lshl_add_u64 v[170:171], v[206:207], 0, s[66:67]
	s_addc_u32 s25, s25, 0
	s_add_i32 s48, s49, s61
	global_load_lds_dwordx4 v[170:171], off
	v_lshl_add_u64 v[170:171], s[24:25], 0, v[200:201]
	s_mov_b32 m0, s48
	s_nop 0
	global_load_lds_dwordx4 v[170:171], off
	v_lshl_add_u64 v[170:171], s[24:25], 0, v[136:137]
	s_add_i32 m0, s48, 0x2000
	s_nop 0
	global_load_lds_dwordx4 v[170:171], off
	v_lshl_add_u64 v[170:171], v[208:209], 0, s[66:67]
	s_mov_b32 m0, s71
	s_nop 0
	global_load_lds_dwordx4 v[170:171], off
	v_lshl_add_u64 v[170:171], v[222:223], 0, s[66:67]
	s_mov_b32 m0, s73
	s_nop 0
	global_load_lds_dwordx4 v[170:171], off
	s_waitcnt vmcnt(8) lgkmcnt(0)
	s_setprio 1
	s_barrier
	v_mfma_f32_16x16x32_bf16 v[64:67], v[132:135], v[180:183], v[64:67]
	v_mfma_f32_16x16x32_bf16 v[60:63], v[150:153], v[180:183], v[60:63]
	v_mfma_f32_16x16x32_bf16 v[52:55], v[132:135], v[188:191], v[52:55]
	v_mfma_f32_16x16x32_bf16 v[44:47], v[150:153], v[188:191], v[44:47]
	v_mfma_f32_16x16x32_bf16 v[36:39], v[132:135], v[196:199], v[36:39]
	v_mfma_f32_16x16x32_bf16 v[28:31], v[150:153], v[196:199], v[28:31]
	v_mfma_f32_16x16x32_bf16 v[20:23], v[132:135], v[214:217], v[20:23]
	v_mfma_f32_16x16x32_bf16 v[12:15], v[150:153], v[214:217], v[12:15]
	v_mfma_f32_16x16x32_bf16 v[64:67], v[146:149], v[184:187], v[64:67]
	v_mfma_f32_16x16x32_bf16 v[60:63], v[154:157], v[184:187], v[60:63]
	v_mfma_f32_16x16x32_bf16 v[52:55], v[146:149], v[192:195], v[52:55]
	v_mfma_f32_16x16x32_bf16 v[44:47], v[154:157], v[192:195], v[44:47]
	v_mfma_f32_16x16x32_bf16 v[36:39], v[146:149], v[210:213], v[36:39]
	v_mfma_f32_16x16x32_bf16 v[28:31], v[154:157], v[210:213], v[28:31]
	v_mfma_f32_16x16x32_bf16 v[20:23], v[146:149], v[218:221], v[20:23]
	v_mfma_f32_16x16x32_bf16 v[12:15], v[154:157], v[218:221], v[12:15]
	v_mfma_f32_16x16x32_bf16 v[56:59], v[158:161], v[180:183], v[56:59]
	v_mfma_f32_16x16x32_bf16 v[48:51], v[166:169], v[180:183], v[48:51]
	v_mfma_f32_16x16x32_bf16 v[40:43], v[158:161], v[188:191], v[40:43]
	v_mfma_f32_16x16x32_bf16 v[32:35], v[166:169], v[188:191], v[32:35]
	v_mfma_f32_16x16x32_bf16 v[24:27], v[158:161], v[196:199], v[24:27]
	v_mfma_f32_16x16x32_bf16 v[16:19], v[166:169], v[196:199], v[16:19]
	v_mfma_f32_16x16x32_bf16 v[8:11], v[158:161], v[214:217], v[8:11]
	v_mfma_f32_16x16x32_bf16 v[4:7], v[166:169], v[214:217], v[4:7]
	v_mfma_f32_16x16x32_bf16 v[56:59], v[162:165], v[184:187], v[56:59]
	v_mfma_f32_16x16x32_bf16 v[48:51], v[176:179], v[184:187], v[48:51]
	v_mfma_f32_16x16x32_bf16 v[40:43], v[162:165], v[192:195], v[40:43]
	v_mfma_f32_16x16x32_bf16 v[32:35], v[176:179], v[192:195], v[32:35]
	v_mfma_f32_16x16x32_bf16 v[24:27], v[162:165], v[210:213], v[24:27]
	v_mfma_f32_16x16x32_bf16 v[16:19], v[176:179], v[210:213], v[16:19]
	v_mfma_f32_16x16x32_bf16 v[8:11], v[162:165], v[218:221], v[8:11]
	v_mfma_f32_16x16x32_bf16 v[4:7], v[176:179], v[218:221], v[4:7]
	s_barrier
	s_setprio 0
	s_add_i32 s54, s54, 2
	s_add_u32 s52, s52, 0x100
	s_addc_u32 s53, s53, 0
	s_add_u32 s14, s14, 0x100
	s_addc_u32 s15, s15, 0
	s_cmp_gt_u32 s54, 5
	s_cbranch_scc0 .LBB0_301
	v_mov_b32_e32 v132, v3
	v_mov_b32_e32 v133, v172
	v_readlane_b32 s14, v254, 30
	v_add_u32_e32 v146, s1, v132
	v_lshl_add_u32 v132, v132, 2, s78
	ds_read2_b32 v[164:165], v132 offset1:16
	ds_read2_b32 v[158:159], v132 offset0:32 offset1:48
	ds_read2_b32 v[152:153], v132 offset0:128 offset1:144
	ds_read2_b32 v[148:149], v132 offset0:160 offset1:176
	s_add_i32 s14, s20, s14
	s_lshl_b32 s20, s14, 8
	s_cmp_gt_u32 s14, 7
	v_lshlrev_b32_e32 v168, 3, v133
	v_ashrrev_i32_e32 v147, 31, v146
	s_mov_b64 s[14:15], -1
	v_add_u32_e32 v166, 16, v146
	v_add_u32_e32 v162, 32, v146
	v_add_u32_e32 v160, 48, v146
	v_add_u32_e32 v156, 0x80, v146
	v_add_u32_e32 v154, 0x90, v146
	v_add_u32_e32 v150, 0xa0, v146
	s_cbranch_scc0 .LBB0_304
; #define PG8_G __attribute__((address_space(1)))
; __device__ __forceinline__ u32x4 pack8bf(const f32x4 a, const f32x4 b) { u32x4 w; w.x = cvt_pk_bf16(a[0], a[1]); w.y = cvt_pk_bf16(a[2], a[3]); w.z = cvt_pk_bf16(b[0], b[1]); w.w = cvt_pk_bf16(b[2], b[3]); return w; }
;     __device__ __forceinline__ void operator()(const f32x4 (&acc)[2][2][4][2], const Unit& u, int wr, int wc, int fr_, int fq_, int ui) const {
;     ...
;             const int head = 4 * (u.pn - 8) + wc, i0 = 8 * fq;
; #pragma unroll
;             for (int ai = 0; ai < 2; ++ai)
; #pragma unroll
;                 for (int m = 0; m < 4; ++m) { const int row = row0 + ai * HALF + m * 16;
;                     const f32x4 c0 = *(const PG8_G f32x4*)(cosT + (size_t)row * 32 + i0), c1 = *(const PG8_G f32x4*)(cosT + (size_t)row * 32 + i0 + 4);
;                     const f32x4 s0 = *(const PG8_G f32x4*)(sinT + (size_t)row * 32 + i0), s1 = *(const PG8_G f32x4*)(sinT + (size_t)row * 32 + i0 + 4);
;                     const f32x4 x1a = acc[ai][0][m][0] * r[ai][m], x1b = acc[ai][0][m][1] * r[ai][m], x2a = acc[ai][1][m][0] * r[ai][m], x2b = acc[ai][1][m][1] * r[ai][m];
;                     const f32x4 y1a = x1a * c0 - x2a * s0, y1b = x1b * c1 - x2b * s1, y2a = x2a * c0 + x1a * s0, y2b = x2b * c1 + x1b * s1;
;                     bf16_t* dst = Q + (size_t)row * 3072 + 2048 + head * 64 + i0;
;                     *(PG8_G u32x4*)dst = pack8bf(y1a, y1b); *(PG8_G u32x4*)(dst + 32) = pack8bf(y2a, y2b); }
	v_ashrrev_i32_e32 v169, 31, v168
	v_lshlrev_b64 v[180:181], 7, v[146:147]
	v_lshl_add_u64 v[132:133], s[38:39], 0, v[180:181]
	v_lshlrev_b64 v[170:171], 2, v[168:169]
	v_lshl_add_u64 v[180:181], s[40:41], 0, v[180:181]
	v_lshl_add_u64 v[176:177], v[132:133], 0, v[170:171]
	v_lshl_add_u64 v[184:185], v[180:181], 0, v[170:171]
	global_load_dwordx4 v[132:135], v[176:177], off offset:16
	s_nop 0
	global_load_dwordx4 v[176:179], v[176:177], off
	s_nop 0
	global_load_dwordx4 v[180:183], v[184:185], off offset:16
	s_nop 0
	global_load_dwordx4 v[184:187], v[184:185], off
	s_waitcnt lgkmcnt(0)
	v_pk_mul_f32 v[188:189], v[130:131], v[164:165] op_sel_hi:[1,0]
	v_pk_mul_f32 v[196:197], v[122:123], v[164:165] op_sel_hi:[1,0]
	v_pk_mul_f32 v[190:191], v[128:129], v[164:165] op_sel_hi:[1,0]
	v_pk_mul_f32 v[194:195], v[124:125], v[164:165] op_sel_hi:[1,0]
	v_pk_mul_f32 v[198:199], v[120:121], v[164:165] op_sel_hi:[1,0]
	v_pk_mul_f32 v[208:209], v[112:113], v[164:165] op_sel_hi:[1,0]
	v_pk_mul_f32 v[192:193], v[126:127], v[164:165] op_sel_hi:[1,0]
	v_pk_mul_f32 v[206:207], v[114:115], v[164:165] op_sel_hi:[1,0]
	s_add_i32 s44, s0, s20
	s_mov_b64 s[48:49], 0x1000
	v_ashrrev_i32_e32 v167, 31, v166
	v_ashrrev_i32_e32 v163, 31, v162
	v_ashrrev_i32_e32 v161, 31, v160
	v_ashrrev_i32_e32 v157, 31, v156
	v_ashrrev_i32_e32 v155, 31, v154
	v_ashrrev_i32_e32 v151, 31, v150
	s_waitcnt vmcnt(0)
	v_pk_mul_f32 v[216:217], v[208:209], v[180:181]
	v_pk_mul_f32 v[210:211], v[196:197], v[186:187]
	v_pk_mul_f32 v[186:187], v[188:189], v[186:187]
	v_pk_mul_f32 v[212:213], v[198:199], v[184:185]
	v_pk_fma_f32 v[210:211], v[188:189], v[178:179], v[210:211] neg_lo:[0,0,1] neg_hi:[0,0,1]
	v_pk_mul_f32 v[184:185], v[190:191], v[184:185]
	v_pk_fma_f32 v[186:187], v[196:197], v[178:179], v[186:187]
	v_pk_mul_f32 v[178:179], v[194:195], v[180:181]
	v_pk_fma_f32 v[212:213], v[190:191], v[176:177], v[212:213] neg_lo:[0,0,1] neg_hi:[0,0,1]
	v_pk_mul_f32 v[214:215], v[206:207], v[182:183]
	v_pk_fma_f32 v[216:217], v[194:195], v[132:133], v[216:217] neg_lo:[0,0,1] neg_hi:[0,0,1]
	v_pk_fma_f32 v[184:185], v[198:199], v[176:177], v[184:185]
	v_pk_mul_f32 v[176:177], v[192:193], v[182:183]
	v_pk_fma_f32 v[182:183], v[208:209], v[132:133], v[178:179]
	v_mov_b64_e32 v[132:133], s[10:11]
	v_pk_fma_f32 v[214:215], v[192:193], v[134:135], v[214:215] neg_lo:[0,0,1] neg_hi:[0,0,1]
	v_pk_fma_f32 v[180:181], v[206:207], v[134:135], v[176:177]
	v_mad_i64_i32 v[134:135], s[14:15], v146, s26, v[132:133]
	s_lshl_b64 s[14:15], s[44:45], 1
	s_nop 0
	v_lshl_add_u64 v[176:177], v[134:135], 0, s[14:15]
	v_lshlrev_b64 v[134:135], 1, v[168:169]
	v_lshl_add_u64 v[188:189], v[176:177], 0, v[134:135]
	v_lshl_add_u64 v[190:191], v[188:189], 0, s[48:49]
	v_add_co_u32_e32 v188, vcc, s27, v188
	v_cvt_pk_bf16_f32 v176, v212, v213
	v_cvt_pk_bf16_f32 v177, v210, v211
	v_cvt_pk_bf16_f32 v178, v216, v217
	v_cvt_pk_bf16_f32 v179, v214, v215
	s_nop 1
	v_addc_co_u32_e32 v189, vcc, 0, v189, vcc
	global_store_dwordx4 v[188:189], v[176:179], off
	v_mov_b32_e32 v192, v165
	v_pk_mul_f32 v[194:195], v[118:119], v[192:193] op_sel_hi:[1,0]
	v_cvt_pk_bf16_f32 v176, v184, v185
	v_cvt_pk_bf16_f32 v177, v186, v187
	v_lshlrev_b64 v[184:185], 7, v[166:167]
	v_cvt_pk_bf16_f32 v178, v182, v183
	v_cvt_pk_bf16_f32 v179, v180, v181
	global_store_dwordx4 v[190:191], v[176:179], off offset:64
	v_pk_mul_f32 v[196:197], v[116:117], v[192:193] op_sel_hi:[1,0]
	v_pk_mul_f32 v[198:199], v[110:111], v[192:193] op_sel_hi:[1,0]
	v_lshl_add_u64 v[176:177], s[38:39], 0, v[184:185]
	v_lshl_add_u64 v[184:185], s[40:41], 0, v[184:185]
	v_lshl_add_u64 v[180:181], v[176:177], 0, v[170:171]
	v_lshl_add_u64 v[188:189], v[184:185], 0, v[170:171]
	global_load_dwordx4 v[176:179], v[180:181], off offset:16
	s_nop 0
	global_load_dwordx4 v[180:183], v[180:181], off
	s_nop 0
	global_load_dwordx4 v[184:187], v[188:189], off offset:16
	s_nop 0
	global_load_dwordx4 v[188:191], v[188:189], off
	v_pk_mul_f32 v[206:207], v[108:109], v[192:193] op_sel_hi:[1,0]
	v_pk_mul_f32 v[208:209], v[106:107], v[192:193] op_sel_hi:[1,0]
	v_pk_mul_f32 v[210:211], v[104:105], v[192:193] op_sel_hi:[1,0]
	v_pk_mul_f32 v[212:213], v[98:99], v[192:193] op_sel_hi:[1,0]
	v_pk_mul_f32 v[192:193], v[96:97], v[192:193] op_sel_hi:[1,0]
	s_waitcnt vmcnt(1)
	v_pk_mul_f32 v[218:219], v[212:213], v[186:187]
	v_pk_mul_f32 v[220:221], v[192:193], v[184:185]
	v_pk_mul_f32 v[184:185], v[206:207], v[184:185]
	v_pk_fma_f32 v[220:221], v[206:207], v[176:177], v[220:221] neg_lo:[0,0,1] neg_hi:[0,0,1]
	v_pk_fma_f32 v[184:185], v[192:193], v[176:177], v[184:185]
	v_mad_i64_i32 v[176:177], s[24:25], v166, s26, v[132:133]
	s_waitcnt vmcnt(0)
; #define PG8_G __attribute__((address_space(1)))
; __device__ __forceinline__ u32x4 pack8bf(const f32x4 a, const f32x4 b) { u32x4 w; w.x = cvt_pk_bf16(a[0], a[1]); w.y = cvt_pk_bf16(a[2], a[3]); w.z = cvt_pk_bf16(b[0], b[1]); w.w = cvt_pk_bf16(b[2], b[3]); return w; }
;     __device__ __forceinline__ void operator()(const f32x4 (&acc)[2][2][4][2], const Unit& u, int wr, int wc, int fr_, int fq_, int ui) const {
;     ...
;                 for (int m = 0; m < 4; ++m) { const int row = row0 + ai * HALF + m * 16;
;                     const f32x4 c0 = *(const PG8_G f32x4*)(cosT + (size_t)row * 32 + i0), c1 = *(const PG8_G f32x4*)(cosT + (size_t)row * 32 + i0 + 4);
;                     const f32x4 s0 = *(const PG8_G f32x4*)(sinT + (size_t)row * 32 + i0), s1 = *(const PG8_G f32x4*)(sinT + (size_t)row * 32 + i0 + 4);
;                     const f32x4 x1a = acc[ai][0][m][0] * r[ai][m], x1b = acc[ai][0][m][1] * r[ai][m], x2a = acc[ai][1][m][0] * r[ai][m], x2b = acc[ai][1][m][1] * r[ai][m];
;                     const f32x4 y1a = x1a * c0 - x2a * s0, y1b = x1b * c1 - x2b * s1, y2a = x2a * c0 + x1a * s0, y2b = x2b * c1 + x1b * s1;
;                     bf16_t* dst = Q + (size_t)row * 3072 + 2048 + head * 64 + i0;
;                     *(PG8_G u32x4*)dst = pack8bf(y1a, y1b); *(PG8_G u32x4*)(dst + 32) = pack8bf(y2a, y2b); }
	v_pk_mul_f32 v[216:217], v[210:211], v[188:189]
	v_pk_mul_f32 v[188:189], v[196:197], v[188:189]
	v_lshl_add_u64 v[176:177], v[176:177], 0, s[14:15]
	v_pk_mul_f32 v[214:215], v[208:209], v[190:191]
	v_pk_fma_f32 v[216:217], v[196:197], v[180:181], v[216:217] neg_lo:[0,0,1] neg_hi:[0,0,1]
	v_pk_mul_f32 v[190:191], v[194:195], v[190:191]
	v_pk_fma_f32 v[180:181], v[210:211], v[180:181], v[188:189]
	v_lshl_add_u64 v[188:189], v[176:177], 0, v[134:135]
	v_pk_fma_f32 v[214:215], v[194:195], v[182:183], v[214:215] neg_lo:[0,0,1] neg_hi:[0,0,1]
	v_pk_fma_f32 v[182:183], v[208:209], v[182:183], v[190:191]
	v_pk_mul_f32 v[186:187], v[198:199], v[186:187]
	v_lshl_add_u64 v[190:191], v[188:189], 0, s[48:49]
	v_add_co_u32_e32 v188, vcc, s27, v188
	v_pk_fma_f32 v[218:219], v[198:199], v[178:179], v[218:219] neg_lo:[0,0,1] neg_hi:[0,0,1]
	v_pk_fma_f32 v[186:187], v[212:213], v[178:179], v[186:187]
	v_cvt_pk_bf16_f32 v176, v216, v217
	v_cvt_pk_bf16_f32 v177, v214, v215
	v_cvt_pk_bf16_f32 v178, v220, v221
	v_addc_co_u32_e32 v189, vcc, 0, v189, vcc
	v_cvt_pk_bf16_f32 v179, v218, v219
	global_store_dwordx4 v[188:189], v[176:179], off
	v_pk_mul_f32 v[198:199], v[92:93], v[158:159] op_sel_hi:[1,0]
	v_pk_mul_f32 v[212:213], v[80:81], v[158:159] op_sel_hi:[1,0]
	v_cvt_pk_bf16_f32 v176, v180, v181
	v_cvt_pk_bf16_f32 v177, v182, v183
	v_cvt_pk_bf16_f32 v178, v184, v185
	v_lshlrev_b64 v[184:185], 7, v[162:163]
	v_cvt_pk_bf16_f32 v179, v186, v187
	global_store_dwordx4 v[190:191], v[176:179], off offset:64
	v_pk_mul_f32 v[194:195], v[100:101], v[158:159] op_sel_hi:[1,0]
	v_pk_mul_f32 v[208:209], v[88:89], v[158:159] op_sel_hi:[1,0]
	v_lshl_add_u64 v[176:177], s[38:39], 0, v[184:185]
	v_lshl_add_u64 v[184:185], s[40:41], 0, v[184:185]
	v_lshl_add_u64 v[180:181], v[176:177], 0, v[170:171]
	v_lshl_add_u64 v[188:189], v[184:185], 0, v[170:171]
	global_load_dwordx4 v[176:179], v[180:181], off offset:16
	s_nop 0
	global_load_dwordx4 v[180:183], v[180:181], off
	s_nop 0
	global_load_dwordx4 v[184:187], v[188:189], off offset:16
	s_nop 0
	global_load_dwordx4 v[188:191], v[188:189], off
	v_pk_mul_f32 v[192:193], v[102:103], v[158:159] op_sel_hi:[1,0]
	v_pk_mul_f32 v[206:207], v[90:91], v[158:159] op_sel_hi:[1,0]
	v_pk_mul_f32 v[196:197], v[94:95], v[158:159] op_sel_hi:[1,0]
	v_pk_mul_f32 v[210:211], v[82:83], v[158:159] op_sel_hi:[1,0]
	s_waitcnt vmcnt(1)
	v_pk_mul_f32 v[220:221], v[212:213], v[184:185]
	v_pk_mul_f32 v[184:185], v[198:199], v[184:185]
	v_pk_fma_f32 v[220:221], v[198:199], v[176:177], v[220:221] neg_lo:[0,0,1] neg_hi:[0,0,1]
	v_pk_fma_f32 v[184:185], v[212:213], v[176:177], v[184:185]
	v_mad_i64_i32 v[176:177], s[24:25], v162, s26, v[132:133]
	s_waitcnt vmcnt(0)
	v_pk_mul_f32 v[216:217], v[208:209], v[188:189]
	v_pk_mul_f32 v[188:189], v[194:195], v[188:189]
	v_lshl_add_u64 v[176:177], v[176:177], 0, s[14:15]
	v_pk_mul_f32 v[214:215], v[206:207], v[190:191]
	v_pk_fma_f32 v[216:217], v[194:195], v[180:181], v[216:217] neg_lo:[0,0,1] neg_hi:[0,0,1]
	v_pk_mul_f32 v[190:191], v[192:193], v[190:191]
	v_pk_fma_f32 v[180:181], v[208:209], v[180:181], v[188:189]
	v_lshl_add_u64 v[188:189], v[176:177], 0, v[134:135]
	v_pk_fma_f32 v[214:215], v[192:193], v[182:183], v[214:215] neg_lo:[0,0,1] neg_hi:[0,0,1]
	v_pk_mul_f32 v[218:219], v[210:211], v[186:187]
	v_pk_fma_f32 v[182:183], v[206:207], v[182:183], v[190:191]
	v_pk_mul_f32 v[186:187], v[196:197], v[186:187]
	v_lshl_add_u64 v[190:191], v[188:189], 0, s[48:49]
	v_add_co_u32_e32 v188, vcc, s27, v188
	v_pk_fma_f32 v[218:219], v[196:197], v[178:179], v[218:219] neg_lo:[0,0,1] neg_hi:[0,0,1]
	v_pk_fma_f32 v[186:187], v[210:211], v[178:179], v[186:187]
	v_cvt_pk_bf16_f32 v176, v216, v217
	v_cvt_pk_bf16_f32 v177, v214, v215
	v_cvt_pk_bf16_f32 v178, v220, v221
	v_addc_co_u32_e32 v189, vcc, 0, v189, vcc
	v_cvt_pk_bf16_f32 v179, v218, v219
	global_store_dwordx4 v[188:189], v[176:179], off
	v_mov_b32_e32 v192, v159
	v_pk_mul_f32 v[194:195], v[86:87], v[192:193] op_sel_hi:[1,0]
	v_cvt_pk_bf16_f32 v176, v180, v181
	v_cvt_pk_bf16_f32 v177, v182, v183
	v_cvt_pk_bf16_f32 v178, v184, v185
	v_lshlrev_b64 v[184:185], 7, v[160:161]
	v_cvt_pk_bf16_f32 v179, v186, v187
	global_store_dwordx4 v[190:191], v[176:179], off offset:64
	v_pk_mul_f32 v[196:197], v[84:85], v[192:193] op_sel_hi:[1,0]
	v_pk_mul_f32 v[198:199], v[78:79], v[192:193] op_sel_hi:[1,0]
	v_lshl_add_u64 v[176:177], s[38:39], 0, v[184:185]
	v_lshl_add_u64 v[184:185], s[40:41], 0, v[184:185]
	v_lshl_add_u64 v[180:181], v[176:177], 0, v[170:171]
	v_lshl_add_u64 v[188:189], v[184:185], 0, v[170:171]
	global_load_dwordx4 v[176:179], v[180:181], off offset:16
	s_nop 0
	global_load_dwordx4 v[180:183], v[180:181], off
	s_nop 0
	global_load_dwordx4 v[184:187], v[188:189], off offset:16
	s_nop 0
	global_load_dwordx4 v[188:191], v[188:189], off
	v_pk_mul_f32 v[206:207], v[76:77], v[192:193] op_sel_hi:[1,0]
	v_pk_mul_f32 v[208:209], v[74:75], v[192:193] op_sel_hi:[1,0]
	v_pk_mul_f32 v[210:211], v[72:73], v[192:193] op_sel_hi:[1,0]
	v_pk_mul_f32 v[212:213], v[70:71], v[192:193] op_sel_hi:[1,0]
	v_pk_mul_f32 v[192:193], v[68:69], v[192:193] op_sel_hi:[1,0]
	s_waitcnt vmcnt(1)
	v_pk_mul_f32 v[218:219], v[212:213], v[186:187]
	v_pk_mul_f32 v[220:221], v[192:193], v[184:185]
	v_pk_mul_f32 v[184:185], v[206:207], v[184:185]
	v_pk_fma_f32 v[220:221], v[206:207], v[176:177], v[220:221] neg_lo:[0,0,1] neg_hi:[0,0,1]
	v_pk_fma_f32 v[184:185], v[192:193], v[176:177], v[184:185]
	v_mad_i64_i32 v[176:177], s[24:25], v160, s26, v[132:133]
	s_waitcnt vmcnt(0)
; #define PG8_G __attribute__((address_space(1)))
; __device__ __forceinline__ u32x4 pack8bf(const f32x4 a, const f32x4 b) { u32x4 w; w.x = cvt_pk_bf16(a[0], a[1]); w.y = cvt_pk_bf16(a[2], a[3]); w.z = cvt_pk_bf16(b[0], b[1]); w.w = cvt_pk_bf16(b[2], b[3]); return w; }
;     __device__ __forceinline__ void operator()(const f32x4 (&acc)[2][2][4][2], const Unit& u, int wr, int wc, int fr_, int fq_, int ui) const {
;     ...
;                 for (int m = 0; m < 4; ++m) { const int row = row0 + ai * HALF + m * 16;
;                     const f32x4 c0 = *(const PG8_G f32x4*)(cosT + (size_t)row * 32 + i0), c1 = *(const PG8_G f32x4*)(cosT + (size_t)row * 32 + i0 + 4);
;                     const f32x4 s0 = *(const PG8_G f32x4*)(sinT + (size_t)row * 32 + i0), s1 = *(const PG8_G f32x4*)(sinT + (size_t)row * 32 + i0 + 4);
;                     const f32x4 x1a = acc[ai][0][m][0] * r[ai][m], x1b = acc[ai][0][m][1] * r[ai][m], x2a = acc[ai][1][m][0] * r[ai][m], x2b = acc[ai][1][m][1] * r[ai][m];
;                     const f32x4 y1a = x1a * c0 - x2a * s0, y1b = x1b * c1 - x2b * s1, y2a = x2a * c0 + x1a * s0, y2b = x2b * c1 + x1b * s1;
;                     bf16_t* dst = Q + (size_t)row * 3072 + 2048 + head * 64 + i0;
;                     *(PG8_G u32x4*)dst = pack8bf(y1a, y1b); *(PG8_G u32x4*)(dst + 32) = pack8bf(y2a, y2b); }
	v_pk_mul_f32 v[216:217], v[210:211], v[188:189]
	v_pk_mul_f32 v[188:189], v[196:197], v[188:189]
	v_lshl_add_u64 v[176:177], v[176:177], 0, s[14:15]
	v_pk_mul_f32 v[214:215], v[208:209], v[190:191]
	v_pk_fma_f32 v[216:217], v[196:197], v[180:181], v[216:217] neg_lo:[0,0,1] neg_hi:[0,0,1]
	v_pk_mul_f32 v[190:191], v[194:195], v[190:191]
	v_pk_fma_f32 v[180:181], v[210:211], v[180:181], v[188:189]
	v_lshl_add_u64 v[188:189], v[176:177], 0, v[134:135]
	v_pk_fma_f32 v[214:215], v[194:195], v[182:183], v[214:215] neg_lo:[0,0,1] neg_hi:[0,0,1]
	v_pk_fma_f32 v[182:183], v[208:209], v[182:183], v[190:191]
	v_pk_mul_f32 v[186:187], v[198:199], v[186:187]
	v_lshl_add_u64 v[190:191], v[188:189], 0, s[48:49]
	v_add_co_u32_e32 v188, vcc, s27, v188
	v_pk_fma_f32 v[218:219], v[198:199], v[178:179], v[218:219] neg_lo:[0,0,1] neg_hi:[0,0,1]
	v_pk_fma_f32 v[186:187], v[212:213], v[178:179], v[186:187]
	v_cvt_pk_bf16_f32 v176, v216, v217
	v_cvt_pk_bf16_f32 v177, v214, v215
	v_cvt_pk_bf16_f32 v178, v220, v221
	v_addc_co_u32_e32 v189, vcc, 0, v189, vcc
	v_cvt_pk_bf16_f32 v179, v218, v219
	global_store_dwordx4 v[188:189], v[176:179], off
	v_pk_mul_f32 v[198:199], v[60:61], v[152:153] op_sel_hi:[1,0]
	v_pk_mul_f32 v[212:213], v[48:49], v[152:153] op_sel_hi:[1,0]
	v_cvt_pk_bf16_f32 v176, v180, v181
	v_cvt_pk_bf16_f32 v177, v182, v183
	v_cvt_pk_bf16_f32 v178, v184, v185
	v_lshlrev_b64 v[184:185], 7, v[156:157]
	v_cvt_pk_bf16_f32 v179, v186, v187
	global_store_dwordx4 v[190:191], v[176:179], off offset:64
	v_pk_mul_f32 v[194:195], v[64:65], v[152:153] op_sel_hi:[1,0]
	v_pk_mul_f32 v[208:209], v[56:57], v[152:153] op_sel_hi:[1,0]
	v_lshl_add_u64 v[176:177], s[38:39], 0, v[184:185]
	v_lshl_add_u64 v[184:185], s[40:41], 0, v[184:185]
	v_lshl_add_u64 v[180:181], v[176:177], 0, v[170:171]
	v_lshl_add_u64 v[188:189], v[184:185], 0, v[170:171]
	global_load_dwordx4 v[176:179], v[180:181], off offset:16
	s_nop 0
	global_load_dwordx4 v[180:183], v[180:181], off
	s_nop 0
	global_load_dwordx4 v[184:187], v[188:189], off offset:16
	s_nop 0
	global_load_dwordx4 v[188:191], v[188:189], off
	v_pk_mul_f32 v[192:193], v[66:67], v[152:153] op_sel_hi:[1,0]
	v_pk_mul_f32 v[206:207], v[58:59], v[152:153] op_sel_hi:[1,0]
	v_pk_mul_f32 v[196:197], v[62:63], v[152:153] op_sel_hi:[1,0]
	v_pk_mul_f32 v[210:211], v[50:51], v[152:153] op_sel_hi:[1,0]
	s_waitcnt vmcnt(1)
	v_pk_mul_f32 v[220:221], v[212:213], v[184:185]
	v_pk_mul_f32 v[184:185], v[198:199], v[184:185]
	v_pk_fma_f32 v[220:221], v[198:199], v[176:177], v[220:221] neg_lo:[0,0,1] neg_hi:[0,0,1]
	v_pk_fma_f32 v[184:185], v[212:213], v[176:177], v[184:185]
	v_mad_i64_i32 v[176:177], s[24:25], v156, s26, v[132:133]
	s_waitcnt vmcnt(0)
	v_pk_mul_f32 v[216:217], v[208:209], v[188:189]
	v_pk_mul_f32 v[188:189], v[194:195], v[188:189]
	v_lshl_add_u64 v[176:177], v[176:177], 0, s[14:15]
	v_pk_mul_f32 v[214:215], v[206:207], v[190:191]
	v_pk_fma_f32 v[216:217], v[194:195], v[180:181], v[216:217] neg_lo:[0,0,1] neg_hi:[0,0,1]
	v_pk_mul_f32 v[190:191], v[192:193], v[190:191]
	v_pk_fma_f32 v[180:181], v[208:209], v[180:181], v[188:189]
	v_lshl_add_u64 v[188:189], v[176:177], 0, v[134:135]
	v_pk_fma_f32 v[214:215], v[192:193], v[182:183], v[214:215] neg_lo:[0,0,1] neg_hi:[0,0,1]
	v_pk_mul_f32 v[218:219], v[210:211], v[186:187]
	v_pk_fma_f32 v[182:183], v[206:207], v[182:183], v[190:191]
	v_pk_mul_f32 v[186:187], v[196:197], v[186:187]
	v_lshl_add_u64 v[190:191], v[188:189], 0, s[48:49]
	v_add_co_u32_e32 v188, vcc, s27, v188
	v_pk_fma_f32 v[218:219], v[196:197], v[178:179], v[218:219] neg_lo:[0,0,1] neg_hi:[0,0,1]
	v_pk_fma_f32 v[186:187], v[210:211], v[178:179], v[186:187]
	v_cvt_pk_bf16_f32 v176, v216, v217
	v_cvt_pk_bf16_f32 v177, v214, v215
	v_cvt_pk_bf16_f32 v178, v220, v221
	v_addc_co_u32_e32 v189, vcc, 0, v189, vcc
	v_cvt_pk_bf16_f32 v179, v218, v219
	global_store_dwordx4 v[188:189], v[176:179], off
	v_mov_b32_e32 v192, v153
	v_pk_mul_f32 v[194:195], v[54:55], v[192:193] op_sel_hi:[1,0]
	v_cvt_pk_bf16_f32 v176, v180, v181
	v_cvt_pk_bf16_f32 v177, v182, v183
	v_cvt_pk_bf16_f32 v178, v184, v185
	v_lshlrev_b64 v[184:185], 7, v[154:155]
	v_cvt_pk_bf16_f32 v179, v186, v187
	global_store_dwordx4 v[190:191], v[176:179], off offset:64
	v_pk_mul_f32 v[196:197], v[52:53], v[192:193] op_sel_hi:[1,0]
	v_pk_mul_f32 v[198:199], v[46:47], v[192:193] op_sel_hi:[1,0]
	v_lshl_add_u64 v[176:177], s[38:39], 0, v[184:185]
	v_lshl_add_u64 v[184:185], s[40:41], 0, v[184:185]
	v_lshl_add_u64 v[180:181], v[176:177], 0, v[170:171]
	v_lshl_add_u64 v[188:189], v[184:185], 0, v[170:171]
	global_load_dwordx4 v[176:179], v[180:181], off offset:16
	s_nop 0
	global_load_dwordx4 v[180:183], v[180:181], off
	s_nop 0
	global_load_dwordx4 v[184:187], v[188:189], off offset:16
	s_nop 0
	global_load_dwordx4 v[188:191], v[188:189], off
	v_pk_mul_f32 v[206:207], v[44:45], v[192:193] op_sel_hi:[1,0]
	v_pk_mul_f32 v[208:209], v[42:43], v[192:193] op_sel_hi:[1,0]
	v_pk_mul_f32 v[210:211], v[40:41], v[192:193] op_sel_hi:[1,0]
	v_pk_mul_f32 v[212:213], v[34:35], v[192:193] op_sel_hi:[1,0]
	v_pk_mul_f32 v[192:193], v[32:33], v[192:193] op_sel_hi:[1,0]
	s_waitcnt vmcnt(1)
	v_pk_mul_f32 v[218:219], v[212:213], v[186:187]
	v_pk_mul_f32 v[220:221], v[192:193], v[184:185]
	v_pk_mul_f32 v[184:185], v[206:207], v[184:185]
	v_pk_fma_f32 v[220:221], v[206:207], v[176:177], v[220:221] neg_lo:[0,0,1] neg_hi:[0,0,1]
	v_pk_fma_f32 v[184:185], v[192:193], v[176:177], v[184:185]
	v_mad_i64_i32 v[176:177], s[24:25], v154, s26, v[132:133]
	s_waitcnt vmcnt(0)
; #define PG8_G __attribute__((address_space(1)))
; __device__ __forceinline__ u32x4 pack8bf(const f32x4 a, const f32x4 b) { u32x4 w; w.x = cvt_pk_bf16(a[0], a[1]); w.y = cvt_pk_bf16(a[2], a[3]); w.z = cvt_pk_bf16(b[0], b[1]); w.w = cvt_pk_bf16(b[2], b[3]); return w; }
;     __device__ __forceinline__ void operator()(const f32x4 (&acc)[2][2][4][2], const Unit& u, int wr, int wc, int fr_, int fq_, int ui) const {
;     ...
;                 for (int m = 0; m < 4; ++m) { const int row = row0 + ai * HALF + m * 16;
;                     const f32x4 c0 = *(const PG8_G f32x4*)(cosT + (size_t)row * 32 + i0), c1 = *(const PG8_G f32x4*)(cosT + (size_t)row * 32 + i0 + 4);
;                     const f32x4 s0 = *(const PG8_G f32x4*)(sinT + (size_t)row * 32 + i0), s1 = *(const PG8_G f32x4*)(sinT + (size_t)row * 32 + i0 + 4);
;                     const f32x4 x1a = acc[ai][0][m][0] * r[ai][m], x1b = acc[ai][0][m][1] * r[ai][m], x2a = acc[ai][1][m][0] * r[ai][m], x2b = acc[ai][1][m][1] * r[ai][m];
;                     const f32x4 y1a = x1a * c0 - x2a * s0, y1b = x1b * c1 - x2b * s1, y2a = x2a * c0 + x1a * s0, y2b = x2b * c1 + x1b * s1;
;                     bf16_t* dst = Q + (size_t)row * 3072 + 2048 + head * 64 + i0;
;                     *(PG8_G u32x4*)dst = pack8bf(y1a, y1b); *(PG8_G u32x4*)(dst + 32) = pack8bf(y2a, y2b); }
	v_pk_mul_f32 v[216:217], v[210:211], v[188:189]
	v_pk_mul_f32 v[188:189], v[196:197], v[188:189]
	v_lshl_add_u64 v[176:177], v[176:177], 0, s[14:15]
	v_pk_mul_f32 v[214:215], v[208:209], v[190:191]
	v_pk_fma_f32 v[216:217], v[196:197], v[180:181], v[216:217] neg_lo:[0,0,1] neg_hi:[0,0,1]
	v_pk_mul_f32 v[190:191], v[194:195], v[190:191]
	v_pk_fma_f32 v[180:181], v[210:211], v[180:181], v[188:189]
	v_lshl_add_u64 v[188:189], v[176:177], 0, v[134:135]
	v_pk_fma_f32 v[214:215], v[194:195], v[182:183], v[214:215] neg_lo:[0,0,1] neg_hi:[0,0,1]
	v_pk_fma_f32 v[182:183], v[208:209], v[182:183], v[190:191]
	v_pk_mul_f32 v[186:187], v[198:199], v[186:187]
	v_lshl_add_u64 v[190:191], v[188:189], 0, s[48:49]
	v_add_co_u32_e32 v188, vcc, s27, v188
	v_pk_fma_f32 v[218:219], v[198:199], v[178:179], v[218:219] neg_lo:[0,0,1] neg_hi:[0,0,1]
	v_pk_fma_f32 v[186:187], v[212:213], v[178:179], v[186:187]
	v_cvt_pk_bf16_f32 v176, v216, v217
	v_cvt_pk_bf16_f32 v177, v214, v215
	v_cvt_pk_bf16_f32 v178, v220, v221
	v_addc_co_u32_e32 v189, vcc, 0, v189, vcc
	v_cvt_pk_bf16_f32 v179, v218, v219
	global_store_dwordx4 v[188:189], v[176:179], off
	v_pk_mul_f32 v[198:199], v[28:29], v[148:149] op_sel_hi:[1,0]
	v_pk_mul_f32 v[212:213], v[16:17], v[148:149] op_sel_hi:[1,0]
	v_cvt_pk_bf16_f32 v176, v180, v181
	v_cvt_pk_bf16_f32 v177, v182, v183
	v_cvt_pk_bf16_f32 v178, v184, v185
	v_lshlrev_b64 v[184:185], 7, v[150:151]
	v_cvt_pk_bf16_f32 v179, v186, v187
	global_store_dwordx4 v[190:191], v[176:179], off offset:64
	v_pk_mul_f32 v[194:195], v[36:37], v[148:149] op_sel_hi:[1,0]
	v_pk_mul_f32 v[208:209], v[24:25], v[148:149] op_sel_hi:[1,0]
	v_lshl_add_u64 v[176:177], s[38:39], 0, v[184:185]
	v_lshl_add_u64 v[184:185], s[40:41], 0, v[184:185]
	v_lshl_add_u64 v[180:181], v[176:177], 0, v[170:171]
	v_lshl_add_u64 v[188:189], v[184:185], 0, v[170:171]
	global_load_dwordx4 v[176:179], v[180:181], off offset:16
	s_nop 0
	global_load_dwordx4 v[180:183], v[180:181], off
	s_nop 0
	global_load_dwordx4 v[184:187], v[188:189], off offset:16
	s_nop 0
	global_load_dwordx4 v[188:191], v[188:189], off
	v_pk_mul_f32 v[192:193], v[38:39], v[148:149] op_sel_hi:[1,0]
	v_pk_mul_f32 v[206:207], v[26:27], v[148:149] op_sel_hi:[1,0]
	v_pk_mul_f32 v[196:197], v[30:31], v[148:149] op_sel_hi:[1,0]
	v_pk_mul_f32 v[210:211], v[18:19], v[148:149] op_sel_hi:[1,0]
	s_waitcnt vmcnt(1)
	v_pk_mul_f32 v[220:221], v[212:213], v[184:185]
	v_pk_mul_f32 v[184:185], v[198:199], v[184:185]
	v_pk_fma_f32 v[220:221], v[198:199], v[176:177], v[220:221] neg_lo:[0,0,1] neg_hi:[0,0,1]
	v_pk_fma_f32 v[184:185], v[212:213], v[176:177], v[184:185]
	v_mad_i64_i32 v[176:177], s[24:25], v150, s26, v[132:133]
	s_waitcnt vmcnt(0)
	v_pk_mul_f32 v[216:217], v[208:209], v[188:189]
	v_pk_mul_f32 v[188:189], v[194:195], v[188:189]
	v_lshl_add_u64 v[176:177], v[176:177], 0, s[14:15]
	v_pk_mul_f32 v[214:215], v[206:207], v[190:191]
	v_pk_fma_f32 v[216:217], v[194:195], v[180:181], v[216:217] neg_lo:[0,0,1] neg_hi:[0,0,1]
	v_pk_mul_f32 v[190:191], v[192:193], v[190:191]
	v_pk_fma_f32 v[180:181], v[208:209], v[180:181], v[188:189]
	v_lshl_add_u64 v[188:189], v[176:177], 0, v[134:135]
	v_pk_fma_f32 v[214:215], v[192:193], v[182:183], v[214:215] neg_lo:[0,0,1] neg_hi:[0,0,1]
	v_pk_mul_f32 v[218:219], v[210:211], v[186:187]
	v_pk_fma_f32 v[182:183], v[206:207], v[182:183], v[190:191]
	v_pk_mul_f32 v[186:187], v[196:197], v[186:187]
	v_lshl_add_u64 v[190:191], v[188:189], 0, s[48:49]
	v_add_co_u32_e32 v188, vcc, s27, v188
	v_add_u32_e32 v192, 0xb0, v146
	v_pk_fma_f32 v[218:219], v[196:197], v[178:179], v[218:219] neg_lo:[0,0,1] neg_hi:[0,0,1]
	v_pk_fma_f32 v[186:187], v[210:211], v[178:179], v[186:187]
	v_cvt_pk_bf16_f32 v176, v216, v217
	v_cvt_pk_bf16_f32 v177, v214, v215
	v_cvt_pk_bf16_f32 v178, v220, v221
	v_addc_co_u32_e32 v189, vcc, 0, v189, vcc
	v_ashrrev_i32_e32 v193, 31, v192
	v_cvt_pk_bf16_f32 v179, v218, v219
	global_store_dwordx4 v[188:189], v[176:179], off
	v_mad_i64_i32 v[132:133], s[24:25], v192, s26, v[132:133]
	s_nop 0
	v_cvt_pk_bf16_f32 v176, v180, v181
	v_cvt_pk_bf16_f32 v177, v182, v183
	v_cvt_pk_bf16_f32 v178, v184, v185
	v_lshlrev_b64 v[184:185], 7, v[192:193]
	v_cvt_pk_bf16_f32 v179, v186, v187
	global_store_dwordx4 v[190:191], v[176:179], off offset:64
	v_lshl_add_u64 v[132:133], v[132:133], 0, s[14:15]
	s_mov_b64 s[14:15], 0x1040
	v_lshl_add_u64 v[176:177], s[38:39], 0, v[184:185]
	v_lshl_add_u64 v[184:185], s[40:41], 0, v[184:185]
	v_lshl_add_u64 v[180:181], v[176:177], 0, v[170:171]
	v_lshl_add_u64 v[170:171], v[184:185], 0, v[170:171]
	global_load_dwordx4 v[176:179], v[180:181], off offset:16
	s_nop 0
	global_load_dwordx4 v[180:183], v[180:181], off
	s_nop 0
	global_load_dwordx4 v[184:187], v[170:171], off offset:16
	global_load_dwordx4 v[188:191], v[170:171], off
	v_mov_b32_e32 v170, v149
	v_pk_mul_f32 v[194:195], v[22:23], v[170:171] op_sel_hi:[1,0]
	v_pk_mul_f32 v[196:197], v[20:21], v[170:171] op_sel_hi:[1,0]
	v_pk_mul_f32 v[198:199], v[14:15], v[170:171] op_sel_hi:[1,0]
	v_pk_mul_f32 v[206:207], v[12:13], v[170:171] op_sel_hi:[1,0]
	v_pk_mul_f32 v[208:209], v[10:11], v[170:171] op_sel_hi:[1,0]
	v_pk_mul_f32 v[210:211], v[8:9], v[170:171] op_sel_hi:[1,0]
	v_pk_mul_f32 v[212:213], v[6:7], v[170:171] op_sel_hi:[1,0]
	v_pk_mul_f32 v[170:171], v[4:5], v[170:171] op_sel_hi:[1,0]
	s_waitcnt vmcnt(1)
	v_pk_mul_f32 v[218:219], v[212:213], v[186:187]
	v_pk_mul_f32 v[220:221], v[170:171], v[184:185]
	v_pk_mul_f32 v[184:185], v[206:207], v[184:185]
	v_pk_fma_f32 v[220:221], v[206:207], v[176:177], v[220:221] neg_lo:[0,0,1] neg_hi:[0,0,1]
	v_pk_fma_f32 v[170:171], v[170:171], v[176:177], v[184:185]
	v_lshl_add_u64 v[176:177], v[132:133], 0, v[134:135]
	s_waitcnt vmcnt(0)
	v_pk_mul_f32 v[214:215], v[208:209], v[190:191]
	v_pk_mul_f32 v[216:217], v[210:211], v[188:189]
	v_add_co_u32_e32 v184, vcc, s27, v176
	v_pk_fma_f32 v[214:215], v[194:195], v[182:183], v[214:215] neg_lo:[0,0,1] neg_hi:[0,0,1]
	v_pk_fma_f32 v[216:217], v[196:197], v[180:181], v[216:217] neg_lo:[0,0,1] neg_hi:[0,0,1]
	v_pk_fma_f32 v[218:219], v[198:199], v[178:179], v[218:219] neg_lo:[0,0,1] neg_hi:[0,0,1]
	v_pk_mul_f32 v[190:191], v[194:195], v[190:191]
	v_pk_mul_f32 v[188:189], v[196:197], v[188:189]
	v_pk_mul_f32 v[186:187], v[198:199], v[186:187]
	v_cvt_pk_bf16_f32 v132, v216, v217
	v_cvt_pk_bf16_f32 v133, v214, v215
	v_cvt_pk_bf16_f32 v134, v220, v221
	v_cvt_pk_bf16_f32 v135, v218, v219
	v_addc_co_u32_e32 v185, vcc, 0, v177, vcc
	v_pk_fma_f32 v[182:183], v[208:209], v[182:183], v[190:191]
	v_pk_fma_f32 v[180:181], v[210:211], v[180:181], v[188:189]
	v_pk_fma_f32 v[178:179], v[212:213], v[178:179], v[186:187]
	global_store_dwordx4 v[184:185], v[132:135], off
	s_nop 1
	v_cvt_pk_bf16_f32 v132, v180, v181
	v_cvt_pk_bf16_f32 v133, v182, v183
	v_cvt_pk_bf16_f32 v134, v170, v171
	v_cvt_pk_bf16_f32 v135, v178, v179
	v_lshl_add_u64 v[170:171], v[176:177], 0, s[14:15]
	s_mov_b64 s[14:15], 0

; #define PG8_STAGE(bufoff, gbase, voff) do { _Pragma("unroll") for (int _i = 0; _i < 2; ++_i) \
;         __builtin_amdgcn_global_load_lds((const unsigned*)((const char*)(gbase) + (voff)[_i]), (PG8_LAS unsigned*)(lds + (bufoff) + ldsw + _i * 8192), 16, 0, 0); } while (0)
; #define PG8_LDA(dst, b, h) do { _Pragma("unroll") for (int m = 0; m < 4; ++m) _Pragma("unroll") for (int k = 0; k < 2; ++k) dst[m][k] = *(const PG8_LAS bf16x8*)(lds + PG8_SA(b, h) + aoff + m * 2048 + k * 1024); } while (0)
; #define PG8_LDB(dst, b, h) do { _Pragma("unroll") for (int n = 0; n < 2; ++n) _Pragma("unroll") for (int k = 0; k < 2; ++k) dst[n][k] = *(const PG8_LAS bf16x8*)(lds + PG8_SB(b, h) + boff + n * 2048 + k * 1024); } while (0)
; #define PG8_MMA(ai, bj, At, Bt) do { __builtin_amdgcn_s_setprio(1); _Pragma("unroll") for (int m = 0; m < 4; ++m) _Pragma("unroll") for (int n = 0; n < 2; ++n) _Pragma("unroll") for (int k = 0; k < 2; ++k) \
;         acc[ai][bj][m][n] = __builtin_amdgcn_mfma_f32_16x16x32_bf16(Bt[n][k], At[m][k], acc[ai][bj][m][n], 0, 0, 0); __builtin_amdgcn_s_setprio(0); } while (0)
; #define PG8_WAIT_V(n) asm volatile("s_waitcnt vmcnt(" #n ")" ::: "memory")
;     ...
;             const char* a1 = cA + (size_t)(t + 1) * kstep;
;             const char* a2 = last ? nA : cA + (size_t)(t + 2) * kstep; const char* b2 = last ? nB : cB + (size_t)(t + 2) * kstep;
;             const char* a3 = a2 + kstep; const char* b3 = b2 + kstep;
;             if (last && has_next) S.a_ready(nxt);
;             if (t == 0) E.pre_issue(pre, cur, tid, ui); else if (t == 2) E.pre_finish(pre, tid, ui);
;             if constexpr (SP2) {
;             PG8_LDB(B0, 0, 0); PG8_LDB(B1, 0, 1); PG8_SCHED; PG8_LDA(At, 0, 0); PG8_STAGE(PG8_SA(1, 1), a1 + hstep, voffA);
;             PG8_WAIT_V(8); PG8_WAIT_L(0); PG8_BAR; PG8_MMA(0, 0, At, B0); PG8_MMA(0, 1, At, B1); PG8_BAR; PG8_SCHED;
;             PG8_LDA(At, 0, 1); PG8_STAGE(PG8_SB(0, 0), b2, voffB); PG8_STAGE(PG8_SB(0, 1), b2 + hstep, voffB); PG8_STAGE(PG8_SA(0, 0), a2, voffA);
;             PG8_WAIT_V(8); PG8_WAIT_L(0); PG8_BAR; PG8_MMA(1, 0, At, B0); PG8_MMA(1, 1, At, B1); PG8_BAR; PG8_SCHED;
;             PG8_LDB(B0, 1, 0); PG8_LDB(B1, 1, 1); PG8_SCHED; PG8_LDA(At, 1, 0); PG8_STAGE(PG8_SA(0, 1), a2 + hstep, voffA);
;             PG8_WAIT_V(8); PG8_WAIT_L(0); PG8_BAR; PG8_MMA(0, 0, At, B0); PG8_MMA(0, 1, At, B1); PG8_BAR; PG8_SCHED;
.LBB0_454:
	s_add_u32 s48, s62, 0xfff80080
	s_addc_u32 s49, s63, -1
	s_add_i32 s82, 0, 0x10000
	s_cmp_eq_u32 s81, 28
	s_cselect_b32 s71, s25, s49
	s_cselect_b32 s70, s76, s48
	s_cselect_b32 s69, s15, s79
	s_cselect_b32 s68, s77, s78
	s_add_i32 s48, 0, 0x14000
	ds_read_b128 v[108:111], v251
	ds_read_b128 v[112:115], v251 offset:1024
	ds_read_b128 v[128:131], v251 offset:2048
	ds_read_b128 v[136:139], v251 offset:3072
	ds_read_b128 v[148:151], v251 offset:16384
	ds_read_b128 v[152:155], v251 offset:17408
	ds_read_b128 v[156:159], v251 offset:18432
	ds_read_b128 v[160:163], v251 offset:19456
	v_lshl_add_u64 v[198:199], s[62:63], 0, v[196:197]
	s_add_i32 m0, s20, 0xc000
	ds_read_b128 v[164:167], v234
	ds_read_b128 v[168:171], v234 offset:1024
	ds_read_b128 v[172:175], v234 offset:2048
	ds_read_b128 v[176:179], v234 offset:3072
	ds_read_b128 v[180:183], v234 offset:4096
	ds_read_b128 v[184:187], v234 offset:5120
	ds_read_b128 v[206:209], v234 offset:6144
	ds_read_b128 v[210:213], v234 offset:7168
	global_load_lds_dwordx4 v[198:199], off
	v_lshl_add_u64 v[198:199], s[62:63], 0, v[194:195]
	s_add_i32 m0, s20, 0xe000
	s_nop 0
	global_load_lds_dwordx4 v[198:199], off
	s_waitcnt vmcnt(8) lgkmcnt(0)
	s_setprio 1
	s_barrier
	v_mfma_f32_16x16x32_bf16 v[144:147], v[108:111], v[164:167], v[144:147]
	v_mfma_f32_16x16x32_bf16 v[140:143], v[128:131], v[164:167], v[140:143]
	v_mfma_f32_16x16x32_bf16 v[120:123], v[108:111], v[172:175], v[120:123]
	v_mfma_f32_16x16x32_bf16 v[116:119], v[128:131], v[172:175], v[116:119]
	v_mfma_f32_16x16x32_bf16 v[96:99], v[108:111], v[180:183], v[96:99]
	v_mfma_f32_16x16x32_bf16 v[92:95], v[128:131], v[180:183], v[92:95]
	v_mfma_f32_16x16x32_bf16 v[80:83], v[108:111], v[206:209], v[80:83]
	v_mfma_f32_16x16x32_bf16 v[76:79], v[128:131], v[206:209], v[76:79]
	v_mfma_f32_16x16x32_bf16 v[144:147], v[112:115], v[168:171], v[144:147]
	v_mfma_f32_16x16x32_bf16 v[140:143], v[136:139], v[168:171], v[140:143]
	v_mfma_f32_16x16x32_bf16 v[120:123], v[112:115], v[176:179], v[120:123]
	v_mfma_f32_16x16x32_bf16 v[116:119], v[136:139], v[176:179], v[116:119]
	v_mfma_f32_16x16x32_bf16 v[96:99], v[112:115], v[184:187], v[96:99]
	v_mfma_f32_16x16x32_bf16 v[92:95], v[136:139], v[184:187], v[92:95]
	v_mfma_f32_16x16x32_bf16 v[80:83], v[112:115], v[210:213], v[80:83]
	v_mfma_f32_16x16x32_bf16 v[76:79], v[136:139], v[210:213], v[76:79]
	v_mfma_f32_16x16x32_bf16 v[132:135], v[148:151], v[164:167], v[132:135]
	v_mfma_f32_16x16x32_bf16 v[124:127], v[156:159], v[164:167], v[124:127]
	v_mfma_f32_16x16x32_bf16 v[104:107], v[148:151], v[172:175], v[104:107]
	v_mfma_f32_16x16x32_bf16 v[100:103], v[156:159], v[172:175], v[100:103]
	v_mfma_f32_16x16x32_bf16 v[88:91], v[148:151], v[180:183], v[88:91]
	v_mfma_f32_16x16x32_bf16 v[84:87], v[156:159], v[180:183], v[84:87]
	v_mfma_f32_16x16x32_bf16 v[72:75], v[148:151], v[206:209], v[72:75]
	v_mfma_f32_16x16x32_bf16 v[68:71], v[156:159], v[206:209], v[68:71]
	v_mfma_f32_16x16x32_bf16 v[132:135], v[152:155], v[168:171], v[132:135]
	v_mfma_f32_16x16x32_bf16 v[124:127], v[160:163], v[168:171], v[124:127]
	v_mfma_f32_16x16x32_bf16 v[104:107], v[152:155], v[176:179], v[104:107]
	v_mfma_f32_16x16x32_bf16 v[100:103], v[160:163], v[176:179], v[100:103]
	v_mfma_f32_16x16x32_bf16 v[88:91], v[152:155], v[184:187], v[88:91]
	v_mfma_f32_16x16x32_bf16 v[84:87], v[160:163], v[184:187], v[84:87]
	v_mfma_f32_16x16x32_bf16 v[72:75], v[152:155], v[210:213], v[72:75]
	v_mfma_f32_16x16x32_bf16 v[68:71], v[160:163], v[210:213], v[68:71]
	s_barrier
	s_setprio 0
	s_add_i32 s49, s82, s5
	v_lshl_add_u64 v[198:199], s[68:69], 0, v[200:201]
	s_mov_b32 m0, s49
	ds_read_b128 v[164:167], v234 offset:16384
	ds_read_b128 v[168:171], v234 offset:17408
	ds_read_b128 v[172:175], v234 offset:18432
	ds_read_b128 v[176:179], v234 offset:19456
	ds_read_b128 v[180:183], v234 offset:20480
	ds_read_b128 v[184:187], v234 offset:21504
	ds_read_b128 v[206:209], v234 offset:22528
	ds_read_b128 v[210:213], v234 offset:23552
	global_load_lds_dwordx4 v[198:199], off
	s_add_i32 m0, s49, 0x2000
	s_add_u32 s82, s68, 0x80000
	v_lshl_add_u64 v[214:215], s[68:69], 0, v[188:189]
	s_addc_u32 s83, s69, 0
	s_add_i32 s48, s48, s5
	global_load_lds_dwordx4 v[214:215], off
	v_lshl_add_u64 v[216:217], s[82:83], 0, v[200:201]
	s_mov_b32 m0, s48
	v_lshl_add_u64 v[218:219], s[70:71], 0, v[190:191]
	global_load_lds_dwordx4 v[216:217], off
	v_lshl_add_u64 v[216:217], s[82:83], 0, v[188:189]
	s_add_i32 m0, s48, 0x2000
	s_nop 0
	global_load_lds_dwordx4 v[216:217], off
	v_lshl_add_u64 v[216:217], s[70:71], 0, v[192:193]
	s_mov_b32 m0, s20
	s_nop 0
	global_load_lds_dwordx4 v[216:217], off
	s_mov_b32 m0, s21
	s_nop 0
	global_load_lds_dwordx4 v[218:219], off
	s_waitcnt vmcnt(8) lgkmcnt(0)
	s_setprio 1
	s_barrier
; #define PG8_STAGE(bufoff, gbase, voff) do { _Pragma("unroll") for (int _i = 0; _i < 2; ++_i) \
;         __builtin_amdgcn_global_load_lds((const unsigned*)((const char*)(gbase) + (voff)[_i]), (PG8_LAS unsigned*)(lds + (bufoff) + ldsw + _i * 8192), 16, 0, 0); } while (0)
; #define PG8_LDA(dst, b, h) do { _Pragma("unroll") for (int m = 0; m < 4; ++m) _Pragma("unroll") for (int k = 0; k < 2; ++k) dst[m][k] = *(const PG8_LAS bf16x8*)(lds + PG8_SA(b, h) + aoff + m * 2048 + k * 1024); } while (0)
; #define PG8_LDB(dst, b, h) do { _Pragma("unroll") for (int n = 0; n < 2; ++n) _Pragma("unroll") for (int k = 0; k < 2; ++k) dst[n][k] = *(const PG8_LAS bf16x8*)(lds + PG8_SB(b, h) + boff + n * 2048 + k * 1024); } while (0)
; #define PG8_MMA(ai, bj, At, Bt) do { __builtin_amdgcn_s_setprio(1); _Pragma("unroll") for (int m = 0; m < 4; ++m) _Pragma("unroll") for (int n = 0; n < 2; ++n) _Pragma("unroll") for (int k = 0; k < 2; ++k) \
;         acc[ai][bj][m][n] = __builtin_amdgcn_mfma_f32_16x16x32_bf16(Bt[n][k], At[m][k], acc[ai][bj][m][n], 0, 0, 0); __builtin_amdgcn_s_setprio(0); } while (0)
; #define PG8_WAIT_V(n) asm volatile("s_waitcnt vmcnt(" #n ")" ::: "memory")
; #define PG8_WAIT_L(n) asm volatile("s_waitcnt lgkmcnt(" #n ")" ::: "memory")
; #define PG8_BAR __builtin_amdgcn_s_barrier()
; #define PG8_SCHED __builtin_amdgcn_sched_barrier(0)
;     ...
;             PG8_WAIT_V(8); PG8_WAIT_L(0); PG8_BAR; PG8_MMA(1, 0, At, B0); PG8_MMA(1, 1, At, B1); PG8_BAR; PG8_SCHED;
;             PG8_LDB(B0, 1, 0); PG8_LDB(B1, 1, 1); PG8_SCHED; PG8_LDA(At, 1, 0); PG8_STAGE(PG8_SA(0, 1), a2 + hstep, voffA);
;             PG8_WAIT_V(8); PG8_WAIT_L(0); PG8_BAR; PG8_MMA(0, 0, At, B0); PG8_MMA(0, 1, At, B1); PG8_BAR; PG8_SCHED;
;             PG8_LDA(At, 1, 1); PG8_STAGE(PG8_SB(1, 0), b3, voffB); PG8_STAGE(PG8_SB(1, 1), b3 + hstep, voffB); PG8_STAGE(PG8_SA(1, 0), a3, voffA);
;             PG8_WAIT_V(8); PG8_WAIT_L(0); PG8_BAR; PG8_MMA(1, 0, At, B0); PG8_MMA(1, 1, At, B1); PG8_BAR; PG8_SCHED;
	v_mfma_f32_16x16x32_bf16 v[64:67], v[108:111], v[164:167], v[64:67]
	v_mfma_f32_16x16x32_bf16 v[60:63], v[128:131], v[164:167], v[60:63]
	v_mfma_f32_16x16x32_bf16 v[48:51], v[108:111], v[172:175], v[48:51]
	v_mfma_f32_16x16x32_bf16 v[44:47], v[128:131], v[172:175], v[44:47]
	v_mfma_f32_16x16x32_bf16 v[32:35], v[108:111], v[180:183], v[32:35]
	v_mfma_f32_16x16x32_bf16 v[28:31], v[128:131], v[180:183], v[28:31]
	v_mfma_f32_16x16x32_bf16 v[16:19], v[108:111], v[206:209], v[16:19]
	v_mfma_f32_16x16x32_bf16 v[12:15], v[128:131], v[206:209], v[12:15]
	v_mfma_f32_16x16x32_bf16 v[64:67], v[112:115], v[168:171], v[64:67]
	v_mfma_f32_16x16x32_bf16 v[60:63], v[136:139], v[168:171], v[60:63]
	v_mfma_f32_16x16x32_bf16 v[48:51], v[112:115], v[176:179], v[48:51]
	v_mfma_f32_16x16x32_bf16 v[44:47], v[136:139], v[176:179], v[44:47]
	v_mfma_f32_16x16x32_bf16 v[32:35], v[112:115], v[184:187], v[32:35]
	v_mfma_f32_16x16x32_bf16 v[28:31], v[136:139], v[184:187], v[28:31]
	v_mfma_f32_16x16x32_bf16 v[16:19], v[112:115], v[210:213], v[16:19]
	v_mfma_f32_16x16x32_bf16 v[12:15], v[136:139], v[210:213], v[12:15]
	v_mfma_f32_16x16x32_bf16 v[56:59], v[148:151], v[164:167], v[56:59]
	v_mfma_f32_16x16x32_bf16 v[52:55], v[156:159], v[164:167], v[52:55]
	v_mfma_f32_16x16x32_bf16 v[40:43], v[148:151], v[172:175], v[40:43]
	v_mfma_f32_16x16x32_bf16 v[36:39], v[156:159], v[172:175], v[36:39]
	v_mfma_f32_16x16x32_bf16 v[24:27], v[148:151], v[180:183], v[24:27]
	v_mfma_f32_16x16x32_bf16 v[20:23], v[156:159], v[180:183], v[20:23]
	v_mfma_f32_16x16x32_bf16 v[8:11], v[148:151], v[206:209], v[8:11]
	v_mfma_f32_16x16x32_bf16 v[4:7], v[156:159], v[206:209], v[4:7]
	v_mfma_f32_16x16x32_bf16 v[56:59], v[152:155], v[168:171], v[56:59]
	v_mfma_f32_16x16x32_bf16 v[52:55], v[160:163], v[168:171], v[52:55]
	v_mfma_f32_16x16x32_bf16 v[40:43], v[152:155], v[176:179], v[40:43]
	v_mfma_f32_16x16x32_bf16 v[36:39], v[160:163], v[176:179], v[36:39]
	v_mfma_f32_16x16x32_bf16 v[24:27], v[152:155], v[184:187], v[24:27]
	v_mfma_f32_16x16x32_bf16 v[20:23], v[160:163], v[184:187], v[20:23]
	v_mfma_f32_16x16x32_bf16 v[8:11], v[152:155], v[210:213], v[8:11]
	v_mfma_f32_16x16x32_bf16 v[4:7], v[160:163], v[210:213], v[4:7]
	s_barrier
	s_setprio 0
	s_add_i32 s48, 0, 0x18000
	s_add_i32 s49, 0, 0x1c000
	ds_read_b128 v[108:111], v251 offset:32768
	ds_read_b128 v[112:115], v251 offset:33792
	ds_read_b128 v[128:131], v251 offset:34816
	ds_read_b128 v[136:139], v251 offset:35840
	ds_read_b128 v[148:151], v251 offset:49152
	ds_read_b128 v[152:155], v251 offset:50176
	ds_read_b128 v[156:159], v251 offset:51200
	ds_read_b128 v[160:163], v251 offset:52224
	s_add_u32 s70, s70, 0x80000
	s_addc_u32 s71, s71, 0
	s_mov_b32 m0, s23
	v_lshl_add_u64 v[220:221], s[70:71], 0, v[192:193]
	ds_read_b128 v[164:167], v234 offset:32768
	ds_read_b128 v[168:171], v234 offset:33792
	ds_read_b128 v[172:175], v234 offset:34816
	ds_read_b128 v[176:179], v234 offset:35840
	ds_read_b128 v[180:183], v234 offset:36864
	ds_read_b128 v[184:187], v234 offset:37888
	ds_read_b128 v[206:209], v234 offset:38912
	ds_read_b128 v[210:213], v234 offset:39936
	global_load_lds_dwordx4 v[220:221], off
	v_lshl_add_u64 v[220:221], s[70:71], 0, v[190:191]
	s_mov_b32 m0, s42
	s_nop 0
	global_load_lds_dwordx4 v[220:221], off
	s_waitcnt vmcnt(8) lgkmcnt(0)
	s_setprio 1
	s_barrier
	v_mfma_f32_16x16x32_bf16 v[144:147], v[108:111], v[164:167], v[144:147]
	v_mfma_f32_16x16x32_bf16 v[140:143], v[128:131], v[164:167], v[140:143]
	v_mfma_f32_16x16x32_bf16 v[120:123], v[108:111], v[172:175], v[120:123]
	v_mfma_f32_16x16x32_bf16 v[116:119], v[128:131], v[172:175], v[116:119]
	v_mfma_f32_16x16x32_bf16 v[96:99], v[108:111], v[180:183], v[96:99]
	v_mfma_f32_16x16x32_bf16 v[92:95], v[128:131], v[180:183], v[92:95]
	v_mfma_f32_16x16x32_bf16 v[80:83], v[108:111], v[206:209], v[80:83]
	v_mfma_f32_16x16x32_bf16 v[76:79], v[128:131], v[206:209], v[76:79]
	v_mfma_f32_16x16x32_bf16 v[144:147], v[112:115], v[168:171], v[144:147]
	v_mfma_f32_16x16x32_bf16 v[140:143], v[136:139], v[168:171], v[140:143]
	v_mfma_f32_16x16x32_bf16 v[120:123], v[112:115], v[176:179], v[120:123]
	v_mfma_f32_16x16x32_bf16 v[116:119], v[136:139], v[176:179], v[116:119]
	v_mfma_f32_16x16x32_bf16 v[96:99], v[112:115], v[184:187], v[96:99]
	v_mfma_f32_16x16x32_bf16 v[92:95], v[136:139], v[184:187], v[92:95]
	v_mfma_f32_16x16x32_bf16 v[80:83], v[112:115], v[210:213], v[80:83]
	v_mfma_f32_16x16x32_bf16 v[76:79], v[136:139], v[210:213], v[76:79]
	v_mfma_f32_16x16x32_bf16 v[132:135], v[148:151], v[164:167], v[132:135]
	v_mfma_f32_16x16x32_bf16 v[124:127], v[156:159], v[164:167], v[124:127]
	v_mfma_f32_16x16x32_bf16 v[104:107], v[148:151], v[172:175], v[104:107]
	v_mfma_f32_16x16x32_bf16 v[100:103], v[156:159], v[172:175], v[100:103]
	v_mfma_f32_16x16x32_bf16 v[88:91], v[148:151], v[180:183], v[88:91]
	v_mfma_f32_16x16x32_bf16 v[84:87], v[156:159], v[180:183], v[84:87]
	v_mfma_f32_16x16x32_bf16 v[72:75], v[148:151], v[206:209], v[72:75]
	v_mfma_f32_16x16x32_bf16 v[68:71], v[156:159], v[206:209], v[68:71]
	v_mfma_f32_16x16x32_bf16 v[132:135], v[152:155], v[168:171], v[132:135]
	v_mfma_f32_16x16x32_bf16 v[124:127], v[160:163], v[168:171], v[124:127]
	v_mfma_f32_16x16x32_bf16 v[104:107], v[152:155], v[176:179], v[104:107]
	v_mfma_f32_16x16x32_bf16 v[100:103], v[160:163], v[176:179], v[100:103]
	v_mfma_f32_16x16x32_bf16 v[88:91], v[152:155], v[184:187], v[88:91]
	v_mfma_f32_16x16x32_bf16 v[84:87], v[160:163], v[184:187], v[84:87]
	v_mfma_f32_16x16x32_bf16 v[72:75], v[152:155], v[210:213], v[72:75]
	v_mfma_f32_16x16x32_bf16 v[68:71], v[160:163], v[210:213], v[68:71]
	s_barrier
; #define PG8_STAGE(bufoff, gbase, voff) do { _Pragma("unroll") for (int _i = 0; _i < 2; ++_i) \
;         __builtin_amdgcn_global_load_lds((const unsigned*)((const char*)(gbase) + (voff)[_i]), (PG8_LAS unsigned*)(lds + (bufoff) + ldsw + _i * 8192), 16, 0, 0); } while (0)
; #define PG8_LDA(dst, b, h) do { _Pragma("unroll") for (int m = 0; m < 4; ++m) _Pragma("unroll") for (int k = 0; k < 2; ++k) dst[m][k] = *(const PG8_LAS bf16x8*)(lds + PG8_SA(b, h) + aoff + m * 2048 + k * 1024); } while (0)
; #define PG8_MMA(ai, bj, At, Bt) do { __builtin_amdgcn_s_setprio(1); _Pragma("unroll") for (int m = 0; m < 4; ++m) _Pragma("unroll") for (int n = 0; n < 2; ++n) _Pragma("unroll") for (int k = 0; k < 2; ++k) \
;         acc[ai][bj][m][n] = __builtin_amdgcn_mfma_f32_16x16x32_bf16(Bt[n][k], At[m][k], acc[ai][bj][m][n], 0, 0, 0); __builtin_amdgcn_s_setprio(0); } while (0)
; #define PG8_WAIT_V(n) asm volatile("s_waitcnt vmcnt(" #n ")" ::: "memory")
; #define PG8_WAIT_L(n) asm volatile("s_waitcnt lgkmcnt(" #n ")" ::: "memory")
; #define PG8_BAR __builtin_amdgcn_s_barrier()
; #define PG8_SCHED __builtin_amdgcn_sched_barrier(0)
;     ...
;         for (int t = 0; t < nt; t += 2) {
;     ...
;             PG8_LDA(At, 1, 1); PG8_STAGE(PG8_SB(1, 0), b3, voffB); PG8_STAGE(PG8_SB(1, 1), b3 + hstep, voffB); PG8_STAGE(PG8_SA(1, 0), a3, voffA);
;             PG8_WAIT_V(8); PG8_WAIT_L(0); PG8_BAR; PG8_MMA(1, 0, At, B0); PG8_MMA(1, 1, At, B1); PG8_BAR; PG8_SCHED;
	s_setprio 0
	s_add_i32 s48, s48, s5
	v_lshl_add_u64 v[198:199], v[198:199], 0, s[66:67]
	s_mov_b32 m0, s48
	ds_read_b128 v[164:167], v234 offset:49152
	ds_read_b128 v[168:171], v234 offset:50176
	ds_read_b128 v[172:175], v234 offset:51200
	ds_read_b128 v[176:179], v234 offset:52224
	ds_read_b128 v[180:183], v234 offset:53248
	ds_read_b128 v[184:187], v234 offset:54272
	ds_read_b128 v[206:209], v234 offset:55296
	ds_read_b128 v[210:213], v234 offset:56320
	global_load_lds_dwordx4 v[198:199], off
	s_add_i32 m0, s48, 0x2000
	s_add_u32 s68, s68, 0x80080
	v_lshl_add_u64 v[198:199], v[214:215], 0, s[66:67]
	s_addc_u32 s69, s69, 0
	s_add_i32 s48, s49, s5
	global_load_lds_dwordx4 v[198:199], off
	v_lshl_add_u64 v[198:199], s[68:69], 0, v[200:201]
	s_mov_b32 m0, s48
	s_nop 0
	global_load_lds_dwordx4 v[198:199], off
	v_lshl_add_u64 v[198:199], s[68:69], 0, v[188:189]
	s_add_i32 m0, s48, 0x2000
	s_nop 0
	global_load_lds_dwordx4 v[198:199], off
	v_lshl_add_u64 v[198:199], v[216:217], 0, s[66:67]
	s_mov_b32 m0, s55
	s_nop 0
	global_load_lds_dwordx4 v[198:199], off
	v_lshl_add_u64 v[198:199], v[218:219], 0, s[66:67]
	s_mov_b32 m0, s56
	s_nop 0
	global_load_lds_dwordx4 v[198:199], off
	s_waitcnt vmcnt(8) lgkmcnt(0)
	s_setprio 1
	s_barrier
	v_mfma_f32_16x16x32_bf16 v[64:67], v[108:111], v[164:167], v[64:67]
	v_mfma_f32_16x16x32_bf16 v[60:63], v[128:131], v[164:167], v[60:63]
	v_mfma_f32_16x16x32_bf16 v[48:51], v[108:111], v[172:175], v[48:51]
	v_mfma_f32_16x16x32_bf16 v[44:47], v[128:131], v[172:175], v[44:47]
	v_mfma_f32_16x16x32_bf16 v[32:35], v[108:111], v[180:183], v[32:35]
	v_mfma_f32_16x16x32_bf16 v[28:31], v[128:131], v[180:183], v[28:31]
	v_mfma_f32_16x16x32_bf16 v[16:19], v[108:111], v[206:209], v[16:19]
	v_mfma_f32_16x16x32_bf16 v[12:15], v[128:131], v[206:209], v[12:15]
	v_mfma_f32_16x16x32_bf16 v[64:67], v[112:115], v[168:171], v[64:67]
	v_mfma_f32_16x16x32_bf16 v[60:63], v[136:139], v[168:171], v[60:63]
	v_mfma_f32_16x16x32_bf16 v[48:51], v[112:115], v[176:179], v[48:51]
	v_mfma_f32_16x16x32_bf16 v[44:47], v[136:139], v[176:179], v[44:47]
	v_mfma_f32_16x16x32_bf16 v[32:35], v[112:115], v[184:187], v[32:35]
	v_mfma_f32_16x16x32_bf16 v[28:31], v[136:139], v[184:187], v[28:31]
	v_mfma_f32_16x16x32_bf16 v[16:19], v[112:115], v[210:213], v[16:19]
	v_mfma_f32_16x16x32_bf16 v[12:15], v[136:139], v[210:213], v[12:15]
	v_mfma_f32_16x16x32_bf16 v[56:59], v[148:151], v[164:167], v[56:59]
	v_mfma_f32_16x16x32_bf16 v[52:55], v[156:159], v[164:167], v[52:55]
	v_mfma_f32_16x16x32_bf16 v[40:43], v[148:151], v[172:175], v[40:43]
	v_mfma_f32_16x16x32_bf16 v[36:39], v[156:159], v[172:175], v[36:39]
	v_mfma_f32_16x16x32_bf16 v[24:27], v[148:151], v[180:183], v[24:27]
	v_mfma_f32_16x16x32_bf16 v[20:23], v[156:159], v[180:183], v[20:23]
	v_mfma_f32_16x16x32_bf16 v[8:11], v[148:151], v[206:209], v[8:11]
	v_mfma_f32_16x16x32_bf16 v[4:7], v[156:159], v[206:209], v[4:7]
	v_mfma_f32_16x16x32_bf16 v[56:59], v[152:155], v[168:171], v[56:59]
	v_mfma_f32_16x16x32_bf16 v[52:55], v[160:163], v[168:171], v[52:55]
	v_mfma_f32_16x16x32_bf16 v[40:43], v[152:155], v[176:179], v[40:43]
	v_mfma_f32_16x16x32_bf16 v[36:39], v[160:163], v[176:179], v[36:39]
	v_mfma_f32_16x16x32_bf16 v[24:27], v[152:155], v[184:187], v[24:27]
	v_mfma_f32_16x16x32_bf16 v[20:23], v[160:163], v[184:187], v[20:23]
	v_mfma_f32_16x16x32_bf16 v[8:11], v[152:155], v[210:213], v[8:11]
	v_mfma_f32_16x16x32_bf16 v[4:7], v[160:163], v[210:213], v[4:7]
	s_barrier
	s_setprio 0
	s_add_i32 s81, s81, 2
	s_add_u32 s78, s78, 0x100
	s_addc_u32 s79, s79, 0
	s_add_u32 s62, s62, 0x100
	s_addc_u32 s63, s63, 0
	s_cmp_gt_u32 s81, 29
	s_cbranch_scc0 .LBB0_454
	s_and_b64 vcc, exec, s[12:13]
	s_cbranch_vccz .LBB0_457
	s_barrier

; #define PG8_STAGE(bufoff, gbase, voff) do { _Pragma("unroll") for (int _i = 0; _i < 2; ++_i) \
;         __builtin_amdgcn_global_load_lds((const unsigned*)((const char*)(gbase) + (voff)[_i]), (PG8_LAS unsigned*)(lds + (bufoff) + ldsw + _i * 8192), 16, 0, 0); } while (0)
; #define PG8_LDA(dst, b, h) do { _Pragma("unroll") for (int m = 0; m < 4; ++m) _Pragma("unroll") for (int k = 0; k < 2; ++k) dst[m][k] = *(const PG8_LAS bf16x8*)(lds + PG8_SA(b, h) + aoff + m * 2048 + k * 1024); } while (0)
; #define PG8_LDB(dst, b, h) do { _Pragma("unroll") for (int n = 0; n < 2; ++n) _Pragma("unroll") for (int k = 0; k < 2; ++k) dst[n][k] = *(const PG8_LAS bf16x8*)(lds + PG8_SB(b, h) + boff + n * 2048 + k * 1024); } while (0)
; #define PG8_MMA(ai, bj, At, Bt) do { __builtin_amdgcn_s_setprio(1); _Pragma("unroll") for (int m = 0; m < 4; ++m) _Pragma("unroll") for (int n = 0; n < 2; ++n) _Pragma("unroll") for (int k = 0; k < 2; ++k) \
;         acc[ai][bj][m][n] = __builtin_amdgcn_mfma_f32_16x16x32_bf16(Bt[n][k], At[m][k], acc[ai][bj][m][n], 0, 0, 0); __builtin_amdgcn_s_setprio(0); } while (0)
; #define PG8_WAIT_V(n) asm volatile("s_waitcnt vmcnt(" #n ")" ::: "memory")
;     ...
;             const char* a1 = cA + (size_t)(t + 1) * kstep;
;             const char* a2 = last ? nA : cA + (size_t)(t + 2) * kstep; const char* b2 = last ? nB : cB + (size_t)(t + 2) * kstep;
;             const char* a3 = a2 + kstep; const char* b3 = b2 + kstep;
;             if (last && has_next) S.a_ready(nxt);
;             if (t == 0) E.pre_issue(pre, cur, tid, ui); else if (t == 2) E.pre_finish(pre, tid, ui);
;             if constexpr (SP2) {
;             PG8_LDB(B0, 0, 0); PG8_LDB(B1, 0, 1); PG8_SCHED; PG8_LDA(At, 0, 0); PG8_STAGE(PG8_SA(1, 1), a1 + hstep, voffA);
;             PG8_WAIT_V(8); PG8_WAIT_L(0); PG8_BAR; PG8_MMA(0, 0, At, B0); PG8_MMA(0, 1, At, B1); PG8_BAR; PG8_SCHED;
;             PG8_LDA(At, 0, 1); PG8_STAGE(PG8_SB(0, 0), b2, voffB); PG8_STAGE(PG8_SB(0, 1), b2 + hstep, voffB); PG8_STAGE(PG8_SA(0, 0), a2, voffA);
;             PG8_WAIT_V(8); PG8_WAIT_L(0); PG8_BAR; PG8_MMA(1, 0, At, B0); PG8_MMA(1, 1, At, B1); PG8_BAR; PG8_SCHED;
;             PG8_LDB(B0, 1, 0); PG8_LDB(B1, 1, 1); PG8_SCHED; PG8_LDA(At, 1, 0); PG8_STAGE(PG8_SA(0, 1), a2 + hstep, voffA);
;             PG8_WAIT_V(8); PG8_WAIT_L(0); PG8_BAR; PG8_MMA(0, 0, At, B0); PG8_MMA(0, 1, At, B1); PG8_BAR; PG8_SCHED;
.LBB0_542:
	s_add_u32 s12, s10, 0xfff80080
	s_addc_u32 s13, s11, -1
	s_add_i32 s48, 0, 0x10000
	s_cmp_eq_u32 s89, 28
	s_cselect_b32 s15, s25, s13
	s_cselect_b32 s14, s69, s12
	s_cselect_b32 s13, s76, s83
	s_cselect_b32 s12, s77, s82
	s_add_i32 s49, 0, 0x14000
	ds_read_b128 v[106:109], v251
	ds_read_b128 v[110:113], v251 offset:1024
	ds_read_b128 v[114:117], v251 offset:2048
	ds_read_b128 v[118:121], v251 offset:3072
	ds_read_b128 v[122:125], v251 offset:16384
	ds_read_b128 v[126:129], v251 offset:17408
	ds_read_b128 v[130:133], v251 offset:18432
	ds_read_b128 v[134:137], v251 offset:19456
	v_lshl_add_u64 v[100:101], s[10:11], 0, v[190:191]
	s_add_i32 m0, s1, 0xc000
	ds_read_b128 v[166:169], v222
	ds_read_b128 v[170:173], v222 offset:1024
	ds_read_b128 v[174:177], v222 offset:2048
	ds_read_b128 v[178:181], v222 offset:3072
	ds_read_b128 v[194:197], v222 offset:4096
	ds_read_b128 v[206:209], v222 offset:5120
	ds_read_b128 v[210:213], v222 offset:6144
	ds_read_b128 v[214:217], v222 offset:7168
	global_load_lds_dwordx4 v[100:101], off
	v_lshl_add_u64 v[100:101], s[10:11], 0, v[192:193]
	s_add_i32 m0, s1, 0xe000
	s_nop 0
	global_load_lds_dwordx4 v[100:101], off
	s_waitcnt vmcnt(8) lgkmcnt(0)
	s_setprio 1
	s_barrier
	v_mfma_f32_16x16x32_bf16 v[4:7], v[106:109], v[166:169], v[4:7]
	v_mfma_f32_16x16x32_bf16 v[72:75], v[114:117], v[166:169], v[72:75]
	v_mfma_f32_16x16x32_bf16 v[162:165], v[106:109], v[174:177], v[162:165]
	v_mfma_f32_16x16x32_bf16 v[60:63], v[114:117], v[174:177], v[60:63]
	v_mfma_f32_16x16x32_bf16 v[158:161], v[106:109], v[194:197], v[158:161]
	v_mfma_f32_16x16x32_bf16 v[56:59], v[114:117], v[194:197], v[56:59]
	v_mfma_f32_16x16x32_bf16 v[96:99], v[106:109], v[210:213], v[96:99]
	v_mfma_f32_16x16x32_bf16 v[76:79], v[114:117], v[210:213], v[76:79]
	v_mfma_f32_16x16x32_bf16 v[4:7], v[110:113], v[170:173], v[4:7]
	v_mfma_f32_16x16x32_bf16 v[72:75], v[118:121], v[170:173], v[72:75]
	v_mfma_f32_16x16x32_bf16 v[162:165], v[110:113], v[178:181], v[162:165]
	v_mfma_f32_16x16x32_bf16 v[60:63], v[118:121], v[178:181], v[60:63]
	v_mfma_f32_16x16x32_bf16 v[158:161], v[110:113], v[206:209], v[158:161]
	v_mfma_f32_16x16x32_bf16 v[56:59], v[118:121], v[206:209], v[56:59]
	v_mfma_f32_16x16x32_bf16 v[96:99], v[110:113], v[214:217], v[96:99]
	v_mfma_f32_16x16x32_bf16 v[76:79], v[118:121], v[214:217], v[76:79]
	v_mfma_f32_16x16x32_bf16 v[8:11], v[122:125], v[166:169], v[8:11]
	v_mfma_f32_16x16x32_bf16 v[64:67], v[130:133], v[166:169], v[64:67]
	v_mfma_f32_16x16x32_bf16 v[154:157], v[122:125], v[174:177], v[154:157]
	v_mfma_f32_16x16x32_bf16 v[52:55], v[130:133], v[174:177], v[52:55]
	v_mfma_f32_16x16x32_bf16 v[150:153], v[122:125], v[194:197], v[150:153]
	v_mfma_f32_16x16x32_bf16 v[48:51], v[130:133], v[194:197], v[48:51]
	v_mfma_f32_16x16x32_bf16 v[92:95], v[122:125], v[210:213], v[92:95]
	v_mfma_f32_16x16x32_bf16 v[68:71], v[130:133], v[210:213], v[68:71]
	v_mfma_f32_16x16x32_bf16 v[8:11], v[126:129], v[170:173], v[8:11]
	v_mfma_f32_16x16x32_bf16 v[64:67], v[134:137], v[170:173], v[64:67]
	v_mfma_f32_16x16x32_bf16 v[154:157], v[126:129], v[178:181], v[154:157]
	v_mfma_f32_16x16x32_bf16 v[52:55], v[134:137], v[178:181], v[52:55]
	v_mfma_f32_16x16x32_bf16 v[150:153], v[126:129], v[206:209], v[150:153]
	v_mfma_f32_16x16x32_bf16 v[48:51], v[134:137], v[206:209], v[48:51]
	v_mfma_f32_16x16x32_bf16 v[92:95], v[126:129], v[214:217], v[92:95]
	v_mfma_f32_16x16x32_bf16 v[68:71], v[134:137], v[214:217], v[68:71]
	s_barrier
	s_setprio 0
	s_add_i32 s48, s48, s0
	v_lshl_add_u64 v[198:199], s[12:13], 0, v[186:187]
	s_mov_b32 m0, s48
	ds_read_b128 v[166:169], v222 offset:16384
	ds_read_b128 v[170:173], v222 offset:17408
	ds_read_b128 v[174:177], v222 offset:18432
	ds_read_b128 v[178:181], v222 offset:19456
	ds_read_b128 v[194:197], v222 offset:20480
	ds_read_b128 v[206:209], v222 offset:21504
	ds_read_b128 v[210:213], v222 offset:22528
	ds_read_b128 v[214:217], v222 offset:23552
	global_load_lds_dwordx4 v[198:199], off
	s_add_i32 m0, s48, 0x2000
	s_add_u32 vcc_lo, s12, 0x80000
	v_lshl_add_u64 v[218:219], s[12:13], 0, v[182:183]
	s_addc_u32 vcc_hi, s13, 0
	s_add_i32 s48, s49, s0
	global_load_lds_dwordx4 v[218:219], off
	v_lshl_add_u64 v[100:101], vcc, 0, v[186:187]
	s_mov_b32 m0, s48
	v_lshl_add_u64 v[224:225], s[14:15], 0, v[188:189]
	global_load_lds_dwordx4 v[100:101], off
	v_lshl_add_u64 v[100:101], vcc, 0, v[182:183]
	s_add_i32 m0, s48, 0x2000
	v_lshl_add_u64 v[232:233], s[14:15], 0, v[184:185]
	global_load_lds_dwordx4 v[100:101], off
	s_mov_b32 m0, s1
	s_nop 0
	global_load_lds_dwordx4 v[224:225], off
	s_mov_b32 m0, s4
	s_nop 0
	global_load_lds_dwordx4 v[232:233], off
	s_waitcnt vmcnt(8) lgkmcnt(0)
	s_setprio 1
	s_barrier
; #define PG8_STAGE(bufoff, gbase, voff) do { _Pragma("unroll") for (int _i = 0; _i < 2; ++_i) \
;         __builtin_amdgcn_global_load_lds((const unsigned*)((const char*)(gbase) + (voff)[_i]), (PG8_LAS unsigned*)(lds + (bufoff) + ldsw + _i * 8192), 16, 0, 0); } while (0)
; #define PG8_LDA(dst, b, h) do { _Pragma("unroll") for (int m = 0; m < 4; ++m) _Pragma("unroll") for (int k = 0; k < 2; ++k) dst[m][k] = *(const PG8_LAS bf16x8*)(lds + PG8_SA(b, h) + aoff + m * 2048 + k * 1024); } while (0)
; #define PG8_LDB(dst, b, h) do { _Pragma("unroll") for (int n = 0; n < 2; ++n) _Pragma("unroll") for (int k = 0; k < 2; ++k) dst[n][k] = *(const PG8_LAS bf16x8*)(lds + PG8_SB(b, h) + boff + n * 2048 + k * 1024); } while (0)
; #define PG8_MMA(ai, bj, At, Bt) do { __builtin_amdgcn_s_setprio(1); _Pragma("unroll") for (int m = 0; m < 4; ++m) _Pragma("unroll") for (int n = 0; n < 2; ++n) _Pragma("unroll") for (int k = 0; k < 2; ++k) \
;         acc[ai][bj][m][n] = __builtin_amdgcn_mfma_f32_16x16x32_bf16(Bt[n][k], At[m][k], acc[ai][bj][m][n], 0, 0, 0); __builtin_amdgcn_s_setprio(0); } while (0)
; #define PG8_WAIT_V(n) asm volatile("s_waitcnt vmcnt(" #n ")" ::: "memory")
; #define PG8_WAIT_L(n) asm volatile("s_waitcnt lgkmcnt(" #n ")" ::: "memory")
; #define PG8_BAR __builtin_amdgcn_s_barrier()
; #define PG8_SCHED __builtin_amdgcn_sched_barrier(0)
;     ...
;             PG8_WAIT_V(8); PG8_WAIT_L(0); PG8_BAR; PG8_MMA(1, 0, At, B0); PG8_MMA(1, 1, At, B1); PG8_BAR; PG8_SCHED;
;             PG8_LDB(B0, 1, 0); PG8_LDB(B1, 1, 1); PG8_SCHED; PG8_LDA(At, 1, 0); PG8_STAGE(PG8_SA(0, 1), a2 + hstep, voffA);
;             PG8_WAIT_V(8); PG8_WAIT_L(0); PG8_BAR; PG8_MMA(0, 0, At, B0); PG8_MMA(0, 1, At, B1); PG8_BAR; PG8_SCHED;
;             PG8_LDA(At, 1, 1); PG8_STAGE(PG8_SB(1, 0), b3, voffB); PG8_STAGE(PG8_SB(1, 1), b3 + hstep, voffB); PG8_STAGE(PG8_SA(1, 0), a3, voffA);
;             PG8_WAIT_V(8); PG8_WAIT_L(0); PG8_BAR; PG8_MMA(1, 0, At, B0); PG8_MMA(1, 1, At, B1); PG8_BAR; PG8_SCHED;
	v_mfma_f32_16x16x32_bf16 v[146:149], v[106:109], v[166:169], v[146:149]
	v_mfma_f32_16x16x32_bf16 v[44:47], v[114:117], v[166:169], v[44:47]
	v_mfma_f32_16x16x32_bf16 v[142:145], v[106:109], v[174:177], v[142:145]
	v_mfma_f32_16x16x32_bf16 v[40:43], v[114:117], v[174:177], v[40:43]
	v_mfma_f32_16x16x32_bf16 v[138:141], v[106:109], v[194:197], v[138:141]
	v_mfma_f32_16x16x32_bf16 v[36:39], v[114:117], v[194:197], v[36:39]
	v_mfma_f32_16x16x32_bf16 v[80:83], v[106:109], v[210:213], v[80:83]
	v_mfma_f32_16x16x32_bf16 v[20:23], v[114:117], v[210:213], v[20:23]
	v_mfma_f32_16x16x32_bf16 v[146:149], v[110:113], v[170:173], v[146:149]
	v_mfma_f32_16x16x32_bf16 v[44:47], v[118:121], v[170:173], v[44:47]
	v_mfma_f32_16x16x32_bf16 v[142:145], v[110:113], v[178:181], v[142:145]
	v_mfma_f32_16x16x32_bf16 v[40:43], v[118:121], v[178:181], v[40:43]
	v_mfma_f32_16x16x32_bf16 v[138:141], v[110:113], v[206:209], v[138:141]
	v_mfma_f32_16x16x32_bf16 v[36:39], v[118:121], v[206:209], v[36:39]
	v_mfma_f32_16x16x32_bf16 v[80:83], v[110:113], v[214:217], v[80:83]
	v_mfma_f32_16x16x32_bf16 v[20:23], v[118:121], v[214:217], v[20:23]
	v_mfma_f32_16x16x32_bf16 v[100:103], v[122:125], v[166:169], v[102:105]
	v_mfma_f32_16x16x32_bf16 v[32:35], v[130:133], v[166:169], v[32:35]
	v_mfma_f32_16x16x32_bf16 v[88:91], v[122:125], v[174:177], v[88:91]
	v_mfma_f32_16x16x32_bf16 v[28:31], v[130:133], v[174:177], v[28:31]
	v_mfma_f32_16x16x32_bf16 v[84:87], v[122:125], v[194:197], v[84:87]
	v_mfma_f32_16x16x32_bf16 v[24:27], v[130:133], v[194:197], v[24:27]
	v_mfma_f32_16x16x32_bf16 v[16:19], v[122:125], v[210:213], v[16:19]
	v_mfma_f32_16x16x32_bf16 v[12:15], v[130:133], v[210:213], v[12:15]
	v_mfma_f32_16x16x32_bf16 v[100:103], v[126:129], v[170:173], v[100:103]
	v_mfma_f32_16x16x32_bf16 v[32:35], v[134:137], v[170:173], v[32:35]
	v_mfma_f32_16x16x32_bf16 v[88:91], v[126:129], v[178:181], v[88:91]
	v_mfma_f32_16x16x32_bf16 v[28:31], v[134:137], v[178:181], v[28:31]
	v_mfma_f32_16x16x32_bf16 v[84:87], v[126:129], v[206:209], v[84:87]
	v_mfma_f32_16x16x32_bf16 v[24:27], v[134:137], v[206:209], v[24:27]
	v_mfma_f32_16x16x32_bf16 v[16:19], v[126:129], v[214:217], v[16:19]
	v_mfma_f32_16x16x32_bf16 v[12:15], v[134:137], v[214:217], v[12:15]
	s_barrier
	s_setprio 0
	s_add_i32 s48, 0, 0x18000
	s_add_i32 s49, 0, 0x1c000
	ds_read_b128 v[104:107], v251 offset:32768
	ds_read_b128 v[108:111], v251 offset:33792
	ds_read_b128 v[112:115], v251 offset:34816
	ds_read_b128 v[116:119], v251 offset:35840
	ds_read_b128 v[120:123], v251 offset:49152
	ds_read_b128 v[124:127], v251 offset:50176
	ds_read_b128 v[128:131], v251 offset:51200
	ds_read_b128 v[132:135], v251 offset:52224
	s_add_u32 s14, s14, 0x80000
	s_addc_u32 s15, s15, 0
	s_mov_b32 m0, s5
	v_lshl_add_u64 v[136:137], s[14:15], 0, v[188:189]
	ds_read_b128 v[166:169], v222 offset:32768
	ds_read_b128 v[170:173], v222 offset:33792
	ds_read_b128 v[174:177], v222 offset:34816
	ds_read_b128 v[178:181], v222 offset:35840
	ds_read_b128 v[194:197], v222 offset:36864
	ds_read_b128 v[206:209], v222 offset:37888
	ds_read_b128 v[210:213], v222 offset:38912
	ds_read_b128 v[214:217], v222 offset:39936
	global_load_lds_dwordx4 v[136:137], off
	v_lshl_add_u64 v[136:137], s[14:15], 0, v[184:185]
	s_mov_b32 m0, s44
	s_nop 0
	global_load_lds_dwordx4 v[136:137], off
	s_waitcnt vmcnt(8) lgkmcnt(0)
	s_setprio 1
	s_barrier
	v_mfma_f32_16x16x32_bf16 v[4:7], v[104:107], v[166:169], v[4:7]
	v_mfma_f32_16x16x32_bf16 v[72:75], v[112:115], v[166:169], v[72:75]
	v_mfma_f32_16x16x32_bf16 v[162:165], v[104:107], v[174:177], v[162:165]
	v_mfma_f32_16x16x32_bf16 v[60:63], v[112:115], v[174:177], v[60:63]
	v_mfma_f32_16x16x32_bf16 v[158:161], v[104:107], v[194:197], v[158:161]
	v_mfma_f32_16x16x32_bf16 v[56:59], v[112:115], v[194:197], v[56:59]
	v_mfma_f32_16x16x32_bf16 v[96:99], v[104:107], v[210:213], v[96:99]
	v_mfma_f32_16x16x32_bf16 v[76:79], v[112:115], v[210:213], v[76:79]
	v_mfma_f32_16x16x32_bf16 v[4:7], v[108:111], v[170:173], v[4:7]
	v_mfma_f32_16x16x32_bf16 v[72:75], v[116:119], v[170:173], v[72:75]
	v_mfma_f32_16x16x32_bf16 v[162:165], v[108:111], v[178:181], v[162:165]
	v_mfma_f32_16x16x32_bf16 v[60:63], v[116:119], v[178:181], v[60:63]
	v_mfma_f32_16x16x32_bf16 v[158:161], v[108:111], v[206:209], v[158:161]
	v_mfma_f32_16x16x32_bf16 v[56:59], v[116:119], v[206:209], v[56:59]
	v_mfma_f32_16x16x32_bf16 v[96:99], v[108:111], v[214:217], v[96:99]
	v_mfma_f32_16x16x32_bf16 v[76:79], v[116:119], v[214:217], v[76:79]
	v_mfma_f32_16x16x32_bf16 v[8:11], v[120:123], v[166:169], v[8:11]
	v_mfma_f32_16x16x32_bf16 v[64:67], v[128:131], v[166:169], v[64:67]
	v_mfma_f32_16x16x32_bf16 v[154:157], v[120:123], v[174:177], v[154:157]
	v_mfma_f32_16x16x32_bf16 v[52:55], v[128:131], v[174:177], v[52:55]
	v_mfma_f32_16x16x32_bf16 v[150:153], v[120:123], v[194:197], v[150:153]
	v_mfma_f32_16x16x32_bf16 v[48:51], v[128:131], v[194:197], v[48:51]
	v_mfma_f32_16x16x32_bf16 v[92:95], v[120:123], v[210:213], v[92:95]
	v_mfma_f32_16x16x32_bf16 v[68:71], v[128:131], v[210:213], v[68:71]
	v_mfma_f32_16x16x32_bf16 v[8:11], v[124:127], v[170:173], v[8:11]
	v_mfma_f32_16x16x32_bf16 v[64:67], v[132:135], v[170:173], v[64:67]
	v_mfma_f32_16x16x32_bf16 v[154:157], v[124:127], v[178:181], v[154:157]
	v_mfma_f32_16x16x32_bf16 v[52:55], v[132:135], v[178:181], v[52:55]
	v_mfma_f32_16x16x32_bf16 v[150:153], v[124:127], v[206:209], v[150:153]
	v_mfma_f32_16x16x32_bf16 v[48:51], v[132:135], v[206:209], v[48:51]
	v_mfma_f32_16x16x32_bf16 v[92:95], v[124:127], v[214:217], v[92:95]
	v_mfma_f32_16x16x32_bf16 v[68:71], v[132:135], v[214:217], v[68:71]
	s_barrier
; #define PG8_STAGE(bufoff, gbase, voff) do { _Pragma("unroll") for (int _i = 0; _i < 2; ++_i) \
;         __builtin_amdgcn_global_load_lds((const unsigned*)((const char*)(gbase) + (voff)[_i]), (PG8_LAS unsigned*)(lds + (bufoff) + ldsw + _i * 8192), 16, 0, 0); } while (0)
; #define PG8_LDA(dst, b, h) do { _Pragma("unroll") for (int m = 0; m < 4; ++m) _Pragma("unroll") for (int k = 0; k < 2; ++k) dst[m][k] = *(const PG8_LAS bf16x8*)(lds + PG8_SA(b, h) + aoff + m * 2048 + k * 1024); } while (0)
; #define PG8_MMA(ai, bj, At, Bt) do { __builtin_amdgcn_s_setprio(1); _Pragma("unroll") for (int m = 0; m < 4; ++m) _Pragma("unroll") for (int n = 0; n < 2; ++n) _Pragma("unroll") for (int k = 0; k < 2; ++k) \
;         acc[ai][bj][m][n] = __builtin_amdgcn_mfma_f32_16x16x32_bf16(Bt[n][k], At[m][k], acc[ai][bj][m][n], 0, 0, 0); __builtin_amdgcn_s_setprio(0); } while (0)
; #define PG8_WAIT_V(n) asm volatile("s_waitcnt vmcnt(" #n ")" ::: "memory")
; #define PG8_WAIT_L(n) asm volatile("s_waitcnt lgkmcnt(" #n ")" ::: "memory")
; #define PG8_BAR __builtin_amdgcn_s_barrier()
; #define PG8_SCHED __builtin_amdgcn_sched_barrier(0)
;     ...
;         for (int t = 0; t < nt; t += 2) {
;     ...
;             PG8_LDA(At, 1, 1); PG8_STAGE(PG8_SB(1, 0), b3, voffB); PG8_STAGE(PG8_SB(1, 1), b3 + hstep, voffB); PG8_STAGE(PG8_SA(1, 0), a3, voffA);
;             PG8_WAIT_V(8); PG8_WAIT_L(0); PG8_BAR; PG8_MMA(1, 0, At, B0); PG8_MMA(1, 1, At, B1); PG8_BAR; PG8_SCHED;
	s_setprio 0
	s_add_i32 s14, s48, s0
	v_lshl_add_u64 v[136:137], v[198:199], 0, s[66:67]
	s_mov_b32 m0, s14
	ds_read_b128 v[166:169], v222 offset:49152
	ds_read_b128 v[170:173], v222 offset:50176
	ds_read_b128 v[174:177], v222 offset:51200
	ds_read_b128 v[178:181], v222 offset:52224
	ds_read_b128 v[194:197], v222 offset:53248
	ds_read_b128 v[206:209], v222 offset:54272
	ds_read_b128 v[210:213], v222 offset:55296
	ds_read_b128 v[214:217], v222 offset:56320
	global_load_lds_dwordx4 v[136:137], off
	s_add_i32 m0, s14, 0x2000
	s_add_u32 s12, s12, 0x80080
	v_lshl_add_u64 v[136:137], v[218:219], 0, s[66:67]
	s_addc_u32 s13, s13, 0
	s_add_i32 s14, s49, s0
	global_load_lds_dwordx4 v[136:137], off
	v_lshl_add_u64 v[136:137], s[12:13], 0, v[186:187]
	s_mov_b32 m0, s14
	s_nop 0
	global_load_lds_dwordx4 v[136:137], off
	v_lshl_add_u64 v[136:137], s[12:13], 0, v[182:183]
	s_add_i32 m0, s14, 0x2000
	s_nop 0
	global_load_lds_dwordx4 v[136:137], off
	v_lshl_add_u64 v[136:137], v[224:225], 0, s[66:67]
	s_mov_b32 m0, s81
	s_nop 0
	global_load_lds_dwordx4 v[136:137], off
	v_lshl_add_u64 v[136:137], v[232:233], 0, s[66:67]
	s_mov_b32 m0, s42
	s_nop 0
	global_load_lds_dwordx4 v[136:137], off
	s_waitcnt vmcnt(8) lgkmcnt(0)
	s_setprio 1
	s_barrier
	v_mfma_f32_16x16x32_bf16 v[146:149], v[104:107], v[166:169], v[146:149]
	v_mfma_f32_16x16x32_bf16 v[44:47], v[112:115], v[166:169], v[44:47]
	v_mfma_f32_16x16x32_bf16 v[142:145], v[104:107], v[174:177], v[142:145]
	v_mfma_f32_16x16x32_bf16 v[40:43], v[112:115], v[174:177], v[40:43]
	v_mfma_f32_16x16x32_bf16 v[136:139], v[104:107], v[194:197], v[138:141]
	v_mfma_f32_16x16x32_bf16 v[36:39], v[112:115], v[194:197], v[36:39]
	v_mfma_f32_16x16x32_bf16 v[80:83], v[104:107], v[210:213], v[80:83]
	v_mfma_f32_16x16x32_bf16 v[20:23], v[112:115], v[210:213], v[20:23]
	v_mfma_f32_16x16x32_bf16 v[146:149], v[108:111], v[170:173], v[146:149]
	v_mfma_f32_16x16x32_bf16 v[44:47], v[116:119], v[170:173], v[44:47]
	v_mfma_f32_16x16x32_bf16 v[142:145], v[108:111], v[178:181], v[142:145]
	v_mfma_f32_16x16x32_bf16 v[40:43], v[116:119], v[178:181], v[40:43]
	v_mfma_f32_16x16x32_bf16 v[138:141], v[108:111], v[206:209], v[136:139]
	v_mfma_f32_16x16x32_bf16 v[36:39], v[116:119], v[206:209], v[36:39]
	v_mfma_f32_16x16x32_bf16 v[80:83], v[108:111], v[214:217], v[80:83]
	v_mfma_f32_16x16x32_bf16 v[20:23], v[116:119], v[214:217], v[20:23]
	v_mfma_f32_16x16x32_bf16 v[100:103], v[120:123], v[166:169], v[100:103]
	v_mfma_f32_16x16x32_bf16 v[32:35], v[128:131], v[166:169], v[32:35]
	v_mfma_f32_16x16x32_bf16 v[88:91], v[120:123], v[174:177], v[88:91]
	v_mfma_f32_16x16x32_bf16 v[28:31], v[128:131], v[174:177], v[28:31]
	v_mfma_f32_16x16x32_bf16 v[84:87], v[120:123], v[194:197], v[84:87]
	v_mfma_f32_16x16x32_bf16 v[24:27], v[128:131], v[194:197], v[24:27]
	v_mfma_f32_16x16x32_bf16 v[16:19], v[120:123], v[210:213], v[16:19]
	v_mfma_f32_16x16x32_bf16 v[12:15], v[128:131], v[210:213], v[12:15]
	v_mfma_f32_16x16x32_bf16 v[102:105], v[124:127], v[170:173], v[100:103]
	v_mfma_f32_16x16x32_bf16 v[32:35], v[132:135], v[170:173], v[32:35]
	v_mfma_f32_16x16x32_bf16 v[88:91], v[124:127], v[178:181], v[88:91]
	v_mfma_f32_16x16x32_bf16 v[28:31], v[132:135], v[178:181], v[28:31]
	v_mfma_f32_16x16x32_bf16 v[84:87], v[124:127], v[206:209], v[84:87]
	v_mfma_f32_16x16x32_bf16 v[24:27], v[132:135], v[206:209], v[24:27]
	v_mfma_f32_16x16x32_bf16 v[16:19], v[124:127], v[214:217], v[16:19]
	v_mfma_f32_16x16x32_bf16 v[12:15], v[132:135], v[214:217], v[12:15]
	s_barrier
	s_setprio 0
	s_add_i32 s89, s89, 2
	s_add_u32 s10, s10, 0x100
	s_addc_u32 s11, s11, 0
	s_add_u32 s82, s82, 0x100
	s_addc_u32 s83, s83, 0
	s_cmp_gt_u32 s89, 29
	s_cbranch_scc0 .LBB0_542
	s_and_b64 vcc, exec, s[70:71]
	s_cbranch_vccz .LBB0_545
	s_barrier

; #define PG8_STAGE(bufoff, gbase, voff) do { _Pragma("unroll") for (int _i = 0; _i < 2; ++_i) \
;         __builtin_amdgcn_global_load_lds((const unsigned*)((const char*)(gbase) + (voff)[_i]), (PG8_LAS unsigned*)(lds + (bufoff) + ldsw + _i * 8192), 16, 0, 0); } while (0)
; #define PG8_LDA(dst, b, h) do { _Pragma("unroll") for (int m = 0; m < 4; ++m) _Pragma("unroll") for (int k = 0; k < 2; ++k) dst[m][k] = *(const PG8_LAS bf16x8*)(lds + PG8_SA(b, h) + aoff + m * 2048 + k * 1024); } while (0)
; #define PG8_LDB(dst, b, h) do { _Pragma("unroll") for (int n = 0; n < 2; ++n) _Pragma("unroll") for (int k = 0; k < 2; ++k) dst[n][k] = *(const PG8_LAS bf16x8*)(lds + PG8_SB(b, h) + boff + n * 2048 + k * 1024); } while (0)
; #define PG8_MMA(ai, bj, At, Bt) do { __builtin_amdgcn_s_setprio(1); _Pragma("unroll") for (int m = 0; m < 4; ++m) _Pragma("unroll") for (int n = 0; n < 2; ++n) _Pragma("unroll") for (int k = 0; k < 2; ++k) \
;         acc[ai][bj][m][n] = __builtin_amdgcn_mfma_f32_16x16x32_bf16(Bt[n][k], At[m][k], acc[ai][bj][m][n], 0, 0, 0); __builtin_amdgcn_s_setprio(0); } while (0)
; #define PG8_WAIT_V(n) asm volatile("s_waitcnt vmcnt(" #n ")" ::: "memory")
;     ...
;             const char* a1 = cA + (size_t)(t + 1) * kstep;
;             const char* a2 = last ? nA : cA + (size_t)(t + 2) * kstep; const char* b2 = last ? nB : cB + (size_t)(t + 2) * kstep;
;             const char* a3 = a2 + kstep; const char* b3 = b2 + kstep;
;             if (last && has_next) S.a_ready(nxt);
;             if (t == 0) E.pre_issue(pre, cur, tid, ui); else if (t == 2) E.pre_finish(pre, tid, ui);
;             if constexpr (SP2) {
;             PG8_LDB(B0, 0, 0); PG8_LDB(B1, 0, 1); PG8_SCHED; PG8_LDA(At, 0, 0); PG8_STAGE(PG8_SA(1, 1), a1 + hstep, voffA);
;             PG8_WAIT_V(8); PG8_WAIT_L(0); PG8_BAR; PG8_MMA(0, 0, At, B0); PG8_MMA(0, 1, At, B1); PG8_BAR; PG8_SCHED;
;             PG8_LDA(At, 0, 1); PG8_STAGE(PG8_SB(0, 0), b2, voffB); PG8_STAGE(PG8_SB(0, 1), b2 + hstep, voffB); PG8_STAGE(PG8_SA(0, 0), a2, voffA);
;             PG8_WAIT_V(8); PG8_WAIT_L(0); PG8_BAR; PG8_MMA(1, 0, At, B0); PG8_MMA(1, 1, At, B1); PG8_BAR; PG8_SCHED;
;             PG8_LDB(B0, 1, 0); PG8_LDB(B1, 1, 1); PG8_SCHED; PG8_LDA(At, 1, 0); PG8_STAGE(PG8_SA(0, 1), a2 + hstep, voffA);
;             PG8_WAIT_V(8); PG8_WAIT_L(0); PG8_BAR; PG8_MMA(0, 0, At, B0); PG8_MMA(0, 1, At, B1); PG8_BAR; PG8_SCHED;
.LBB0_667:
	s_add_u32 s68, s62, 0x100
	s_addc_u32 s69, s63, 0
	s_add_i32 s48, 0, 0x10000
	s_cmpk_eq_i32 s78, 0x54
	s_cselect_b32 s77, s11, s69
	s_cselect_b32 s76, s10, s68
	s_cselect_b32 s71, s61, s75
	s_cselect_b32 s70, s60, s73
	s_add_i32 s49, 0, 0x14000
	ds_read_b128 v[108:111], v251
	ds_read_b128 v[112:115], v251 offset:1024
	ds_read_b128 v[128:131], v251 offset:2048
	ds_read_b128 v[136:139], v251 offset:3072
	ds_read_b128 v[148:151], v251 offset:16384
	ds_read_b128 v[152:155], v251 offset:17408
	ds_read_b128 v[156:159], v251 offset:18432
	ds_read_b128 v[160:163], v251 offset:19456
	v_lshl_add_u64 v[198:199], s[62:63], 0, v[196:197]
	s_add_i32 m0, s6, 0xc000
	ds_read_b128 v[164:167], v234
	ds_read_b128 v[168:171], v234 offset:1024
	ds_read_b128 v[172:175], v234 offset:2048
	ds_read_b128 v[176:179], v234 offset:3072
	ds_read_b128 v[180:183], v234 offset:4096
	ds_read_b128 v[184:187], v234 offset:5120
	ds_read_b128 v[206:209], v234 offset:6144
	ds_read_b128 v[210:213], v234 offset:7168
	global_load_lds_dwordx4 v[198:199], off
	v_lshl_add_u64 v[198:199], s[62:63], 0, v[194:195]
	s_add_i32 m0, s6, 0xe000
	s_nop 0
	global_load_lds_dwordx4 v[198:199], off
	s_waitcnt vmcnt(8) lgkmcnt(0)
	s_setprio 1
	s_barrier
	v_mfma_f32_16x16x32_bf16 v[144:147], v[108:111], v[164:167], v[144:147]
	v_mfma_f32_16x16x32_bf16 v[140:143], v[128:131], v[164:167], v[140:143]
	v_mfma_f32_16x16x32_bf16 v[120:123], v[108:111], v[172:175], v[120:123]
	v_mfma_f32_16x16x32_bf16 v[116:119], v[128:131], v[172:175], v[116:119]
	v_mfma_f32_16x16x32_bf16 v[96:99], v[108:111], v[180:183], v[96:99]
	v_mfma_f32_16x16x32_bf16 v[92:95], v[128:131], v[180:183], v[92:95]
	v_mfma_f32_16x16x32_bf16 v[80:83], v[108:111], v[206:209], v[80:83]
	v_mfma_f32_16x16x32_bf16 v[76:79], v[128:131], v[206:209], v[76:79]
	v_mfma_f32_16x16x32_bf16 v[144:147], v[112:115], v[168:171], v[144:147]
	v_mfma_f32_16x16x32_bf16 v[140:143], v[136:139], v[168:171], v[140:143]
	v_mfma_f32_16x16x32_bf16 v[120:123], v[112:115], v[176:179], v[120:123]
	v_mfma_f32_16x16x32_bf16 v[116:119], v[136:139], v[176:179], v[116:119]
	v_mfma_f32_16x16x32_bf16 v[96:99], v[112:115], v[184:187], v[96:99]
	v_mfma_f32_16x16x32_bf16 v[92:95], v[136:139], v[184:187], v[92:95]
	v_mfma_f32_16x16x32_bf16 v[80:83], v[112:115], v[210:213], v[80:83]
	v_mfma_f32_16x16x32_bf16 v[76:79], v[136:139], v[210:213], v[76:79]
	v_mfma_f32_16x16x32_bf16 v[132:135], v[148:151], v[164:167], v[132:135]
	v_mfma_f32_16x16x32_bf16 v[124:127], v[156:159], v[164:167], v[124:127]
	v_mfma_f32_16x16x32_bf16 v[104:107], v[148:151], v[172:175], v[104:107]
	v_mfma_f32_16x16x32_bf16 v[100:103], v[156:159], v[172:175], v[100:103]
	v_mfma_f32_16x16x32_bf16 v[88:91], v[148:151], v[180:183], v[88:91]
	v_mfma_f32_16x16x32_bf16 v[84:87], v[156:159], v[180:183], v[84:87]
	v_mfma_f32_16x16x32_bf16 v[72:75], v[148:151], v[206:209], v[72:75]
	v_mfma_f32_16x16x32_bf16 v[68:71], v[156:159], v[206:209], v[68:71]
	v_mfma_f32_16x16x32_bf16 v[132:135], v[152:155], v[168:171], v[132:135]
	v_mfma_f32_16x16x32_bf16 v[124:127], v[160:163], v[168:171], v[124:127]
	v_mfma_f32_16x16x32_bf16 v[104:107], v[152:155], v[176:179], v[104:107]
	v_mfma_f32_16x16x32_bf16 v[100:103], v[160:163], v[176:179], v[100:103]
	v_mfma_f32_16x16x32_bf16 v[88:91], v[152:155], v[184:187], v[88:91]
	v_mfma_f32_16x16x32_bf16 v[84:87], v[160:163], v[184:187], v[84:87]
	v_mfma_f32_16x16x32_bf16 v[72:75], v[152:155], v[210:213], v[72:75]
	v_mfma_f32_16x16x32_bf16 v[68:71], v[160:163], v[210:213], v[68:71]
	s_barrier
	s_setprio 0
	s_add_i32 s48, s48, s5
	v_lshl_add_u64 v[198:199], s[70:71], 0, v[200:201]
	s_mov_b32 m0, s48
	ds_read_b128 v[164:167], v234 offset:16384
	ds_read_b128 v[168:171], v234 offset:17408
	ds_read_b128 v[172:175], v234 offset:18432
	ds_read_b128 v[176:179], v234 offset:19456
	ds_read_b128 v[180:183], v234 offset:20480
	ds_read_b128 v[184:187], v234 offset:21504
	ds_read_b128 v[206:209], v234 offset:22528
	ds_read_b128 v[210:213], v234 offset:23552
	global_load_lds_dwordx4 v[198:199], off
	s_add_i32 m0, s48, 0x2000
	s_add_u32 s62, s70, 0x160000
	v_lshl_add_u64 v[214:215], s[70:71], 0, v[188:189]
	s_addc_u32 s63, s71, 0
	s_add_i32 s48, s49, s5
	global_load_lds_dwordx4 v[214:215], off
	v_lshl_add_u64 v[216:217], s[62:63], 0, v[200:201]
	s_mov_b32 m0, s48
	v_lshl_add_u64 v[218:219], s[76:77], 0, v[190:191]
	global_load_lds_dwordx4 v[216:217], off
	v_lshl_add_u64 v[216:217], s[62:63], 0, v[188:189]
	s_add_i32 m0, s48, 0x2000
	s_nop 0
	global_load_lds_dwordx4 v[216:217], off
	v_lshl_add_u64 v[216:217], s[76:77], 0, v[192:193]
	s_mov_b32 m0, s6
	s_nop 0
	global_load_lds_dwordx4 v[216:217], off
	s_mov_b32 m0, s7
	s_nop 0
	global_load_lds_dwordx4 v[218:219], off
	s_waitcnt vmcnt(8) lgkmcnt(0)
	s_setprio 1
	s_barrier
; #define PG8_STAGE(bufoff, gbase, voff) do { _Pragma("unroll") for (int _i = 0; _i < 2; ++_i) \
;         __builtin_amdgcn_global_load_lds((const unsigned*)((const char*)(gbase) + (voff)[_i]), (PG8_LAS unsigned*)(lds + (bufoff) + ldsw + _i * 8192), 16, 0, 0); } while (0)
; #define PG8_LDA(dst, b, h) do { _Pragma("unroll") for (int m = 0; m < 4; ++m) _Pragma("unroll") for (int k = 0; k < 2; ++k) dst[m][k] = *(const PG8_LAS bf16x8*)(lds + PG8_SA(b, h) + aoff + m * 2048 + k * 1024); } while (0)
; #define PG8_LDB(dst, b, h) do { _Pragma("unroll") for (int n = 0; n < 2; ++n) _Pragma("unroll") for (int k = 0; k < 2; ++k) dst[n][k] = *(const PG8_LAS bf16x8*)(lds + PG8_SB(b, h) + boff + n * 2048 + k * 1024); } while (0)
; #define PG8_MMA(ai, bj, At, Bt) do { __builtin_amdgcn_s_setprio(1); _Pragma("unroll") for (int m = 0; m < 4; ++m) _Pragma("unroll") for (int n = 0; n < 2; ++n) _Pragma("unroll") for (int k = 0; k < 2; ++k) \
;         acc[ai][bj][m][n] = __builtin_amdgcn_mfma_f32_16x16x32_bf16(Bt[n][k], At[m][k], acc[ai][bj][m][n], 0, 0, 0); __builtin_amdgcn_s_setprio(0); } while (0)
; #define PG8_WAIT_V(n) asm volatile("s_waitcnt vmcnt(" #n ")" ::: "memory")
; #define PG8_WAIT_L(n) asm volatile("s_waitcnt lgkmcnt(" #n ")" ::: "memory")
; #define PG8_BAR __builtin_amdgcn_s_barrier()
; #define PG8_SCHED __builtin_amdgcn_sched_barrier(0)
;     ...
;             PG8_WAIT_V(8); PG8_WAIT_L(0); PG8_BAR; PG8_MMA(1, 0, At, B0); PG8_MMA(1, 1, At, B1); PG8_BAR; PG8_SCHED;
;             PG8_LDB(B0, 1, 0); PG8_LDB(B1, 1, 1); PG8_SCHED; PG8_LDA(At, 1, 0); PG8_STAGE(PG8_SA(0, 1), a2 + hstep, voffA);
;             PG8_WAIT_V(8); PG8_WAIT_L(0); PG8_BAR; PG8_MMA(0, 0, At, B0); PG8_MMA(0, 1, At, B1); PG8_BAR; PG8_SCHED;
;             PG8_LDA(At, 1, 1); PG8_STAGE(PG8_SB(1, 0), b3, voffB); PG8_STAGE(PG8_SB(1, 1), b3 + hstep, voffB); PG8_STAGE(PG8_SA(1, 0), a3, voffA);
;             PG8_WAIT_V(8); PG8_WAIT_L(0); PG8_BAR; PG8_MMA(1, 0, At, B0); PG8_MMA(1, 1, At, B1); PG8_BAR; PG8_SCHED;
	v_mfma_f32_16x16x32_bf16 v[64:67], v[108:111], v[164:167], v[64:67]
	v_mfma_f32_16x16x32_bf16 v[60:63], v[128:131], v[164:167], v[60:63]
	v_mfma_f32_16x16x32_bf16 v[48:51], v[108:111], v[172:175], v[48:51]
	v_mfma_f32_16x16x32_bf16 v[44:47], v[128:131], v[172:175], v[44:47]
	v_mfma_f32_16x16x32_bf16 v[32:35], v[108:111], v[180:183], v[32:35]
	v_mfma_f32_16x16x32_bf16 v[28:31], v[128:131], v[180:183], v[28:31]
	v_mfma_f32_16x16x32_bf16 v[16:19], v[108:111], v[206:209], v[16:19]
	v_mfma_f32_16x16x32_bf16 v[12:15], v[128:131], v[206:209], v[12:15]
	v_mfma_f32_16x16x32_bf16 v[64:67], v[112:115], v[168:171], v[64:67]
	v_mfma_f32_16x16x32_bf16 v[60:63], v[136:139], v[168:171], v[60:63]
	v_mfma_f32_16x16x32_bf16 v[48:51], v[112:115], v[176:179], v[48:51]
	v_mfma_f32_16x16x32_bf16 v[44:47], v[136:139], v[176:179], v[44:47]
	v_mfma_f32_16x16x32_bf16 v[32:35], v[112:115], v[184:187], v[32:35]
	v_mfma_f32_16x16x32_bf16 v[28:31], v[136:139], v[184:187], v[28:31]
	v_mfma_f32_16x16x32_bf16 v[16:19], v[112:115], v[210:213], v[16:19]
	v_mfma_f32_16x16x32_bf16 v[12:15], v[136:139], v[210:213], v[12:15]
	v_mfma_f32_16x16x32_bf16 v[56:59], v[148:151], v[164:167], v[56:59]
	v_mfma_f32_16x16x32_bf16 v[52:55], v[156:159], v[164:167], v[52:55]
	v_mfma_f32_16x16x32_bf16 v[40:43], v[148:151], v[172:175], v[40:43]
	v_mfma_f32_16x16x32_bf16 v[36:39], v[156:159], v[172:175], v[36:39]
	v_mfma_f32_16x16x32_bf16 v[24:27], v[148:151], v[180:183], v[24:27]
	v_mfma_f32_16x16x32_bf16 v[20:23], v[156:159], v[180:183], v[20:23]
	v_mfma_f32_16x16x32_bf16 v[8:11], v[148:151], v[206:209], v[8:11]
	v_mfma_f32_16x16x32_bf16 v[4:7], v[156:159], v[206:209], v[4:7]
	v_mfma_f32_16x16x32_bf16 v[56:59], v[152:155], v[168:171], v[56:59]
	v_mfma_f32_16x16x32_bf16 v[52:55], v[160:163], v[168:171], v[52:55]
	v_mfma_f32_16x16x32_bf16 v[40:43], v[152:155], v[176:179], v[40:43]
	v_mfma_f32_16x16x32_bf16 v[36:39], v[160:163], v[176:179], v[36:39]
	v_mfma_f32_16x16x32_bf16 v[24:27], v[152:155], v[184:187], v[24:27]
	v_mfma_f32_16x16x32_bf16 v[20:23], v[160:163], v[184:187], v[20:23]
	v_mfma_f32_16x16x32_bf16 v[8:11], v[152:155], v[210:213], v[8:11]
	v_mfma_f32_16x16x32_bf16 v[4:7], v[160:163], v[210:213], v[4:7]
	s_barrier
	s_setprio 0
	s_add_i32 s48, 0, 0x18000
	s_add_i32 s49, 0, 0x1c000
	ds_read_b128 v[108:111], v251 offset:32768
	ds_read_b128 v[112:115], v251 offset:33792
	ds_read_b128 v[128:131], v251 offset:34816
	ds_read_b128 v[136:139], v251 offset:35840
	ds_read_b128 v[148:151], v251 offset:49152
	ds_read_b128 v[152:155], v251 offset:50176
	ds_read_b128 v[156:159], v251 offset:51200
	ds_read_b128 v[160:163], v251 offset:52224
	s_add_u32 s62, s76, 0x160000
	s_addc_u32 s63, s77, 0
	s_mov_b32 m0, s20
	v_lshl_add_u64 v[220:221], s[62:63], 0, v[192:193]
	ds_read_b128 v[164:167], v234 offset:32768
	ds_read_b128 v[168:171], v234 offset:33792
	ds_read_b128 v[172:175], v234 offset:34816
	ds_read_b128 v[176:179], v234 offset:35840
	ds_read_b128 v[180:183], v234 offset:36864
	ds_read_b128 v[184:187], v234 offset:37888
	ds_read_b128 v[206:209], v234 offset:38912
	ds_read_b128 v[210:213], v234 offset:39936
	global_load_lds_dwordx4 v[220:221], off
	v_lshl_add_u64 v[220:221], s[62:63], 0, v[190:191]
	s_mov_b32 m0, s21
	s_nop 0
	global_load_lds_dwordx4 v[220:221], off
	s_waitcnt vmcnt(8) lgkmcnt(0)
	s_setprio 1
	s_barrier
	v_mfma_f32_16x16x32_bf16 v[144:147], v[108:111], v[164:167], v[144:147]
	v_mfma_f32_16x16x32_bf16 v[140:143], v[128:131], v[164:167], v[140:143]
	v_mfma_f32_16x16x32_bf16 v[120:123], v[108:111], v[172:175], v[120:123]
	v_mfma_f32_16x16x32_bf16 v[116:119], v[128:131], v[172:175], v[116:119]
	v_mfma_f32_16x16x32_bf16 v[96:99], v[108:111], v[180:183], v[96:99]
	v_mfma_f32_16x16x32_bf16 v[92:95], v[128:131], v[180:183], v[92:95]
	v_mfma_f32_16x16x32_bf16 v[80:83], v[108:111], v[206:209], v[80:83]
	v_mfma_f32_16x16x32_bf16 v[76:79], v[128:131], v[206:209], v[76:79]
	v_mfma_f32_16x16x32_bf16 v[144:147], v[112:115], v[168:171], v[144:147]
	v_mfma_f32_16x16x32_bf16 v[140:143], v[136:139], v[168:171], v[140:143]
	v_mfma_f32_16x16x32_bf16 v[120:123], v[112:115], v[176:179], v[120:123]
	v_mfma_f32_16x16x32_bf16 v[116:119], v[136:139], v[176:179], v[116:119]
	v_mfma_f32_16x16x32_bf16 v[96:99], v[112:115], v[184:187], v[96:99]
	v_mfma_f32_16x16x32_bf16 v[92:95], v[136:139], v[184:187], v[92:95]
	v_mfma_f32_16x16x32_bf16 v[80:83], v[112:115], v[210:213], v[80:83]
	v_mfma_f32_16x16x32_bf16 v[76:79], v[136:139], v[210:213], v[76:79]
	v_mfma_f32_16x16x32_bf16 v[132:135], v[148:151], v[164:167], v[132:135]
	v_mfma_f32_16x16x32_bf16 v[124:127], v[156:159], v[164:167], v[124:127]
	v_mfma_f32_16x16x32_bf16 v[104:107], v[148:151], v[172:175], v[104:107]
	v_mfma_f32_16x16x32_bf16 v[100:103], v[156:159], v[172:175], v[100:103]
	v_mfma_f32_16x16x32_bf16 v[88:91], v[148:151], v[180:183], v[88:91]
	v_mfma_f32_16x16x32_bf16 v[84:87], v[156:159], v[180:183], v[84:87]
	v_mfma_f32_16x16x32_bf16 v[72:75], v[148:151], v[206:209], v[72:75]
	v_mfma_f32_16x16x32_bf16 v[68:71], v[156:159], v[206:209], v[68:71]
	v_mfma_f32_16x16x32_bf16 v[132:135], v[152:155], v[168:171], v[132:135]
	v_mfma_f32_16x16x32_bf16 v[124:127], v[160:163], v[168:171], v[124:127]
	v_mfma_f32_16x16x32_bf16 v[104:107], v[152:155], v[176:179], v[104:107]
	v_mfma_f32_16x16x32_bf16 v[100:103], v[160:163], v[176:179], v[100:103]
	v_mfma_f32_16x16x32_bf16 v[88:91], v[152:155], v[184:187], v[88:91]
	v_mfma_f32_16x16x32_bf16 v[84:87], v[160:163], v[184:187], v[84:87]
	v_mfma_f32_16x16x32_bf16 v[72:75], v[152:155], v[210:213], v[72:75]
	v_mfma_f32_16x16x32_bf16 v[68:71], v[160:163], v[210:213], v[68:71]
	s_barrier
; #define PG8_STAGE(bufoff, gbase, voff) do { _Pragma("unroll") for (int _i = 0; _i < 2; ++_i) \
;         __builtin_amdgcn_global_load_lds((const unsigned*)((const char*)(gbase) + (voff)[_i]), (PG8_LAS unsigned*)(lds + (bufoff) + ldsw + _i * 8192), 16, 0, 0); } while (0)
; #define PG8_LDA(dst, b, h) do { _Pragma("unroll") for (int m = 0; m < 4; ++m) _Pragma("unroll") for (int k = 0; k < 2; ++k) dst[m][k] = *(const PG8_LAS bf16x8*)(lds + PG8_SA(b, h) + aoff + m * 2048 + k * 1024); } while (0)
; #define PG8_MMA(ai, bj, At, Bt) do { __builtin_amdgcn_s_setprio(1); _Pragma("unroll") for (int m = 0; m < 4; ++m) _Pragma("unroll") for (int n = 0; n < 2; ++n) _Pragma("unroll") for (int k = 0; k < 2; ++k) \
;         acc[ai][bj][m][n] = __builtin_amdgcn_mfma_f32_16x16x32_bf16(Bt[n][k], At[m][k], acc[ai][bj][m][n], 0, 0, 0); __builtin_amdgcn_s_setprio(0); } while (0)
; #define PG8_WAIT_V(n) asm volatile("s_waitcnt vmcnt(" #n ")" ::: "memory")
; #define PG8_WAIT_L(n) asm volatile("s_waitcnt lgkmcnt(" #n ")" ::: "memory")
; #define PG8_BAR __builtin_amdgcn_s_barrier()
; #define PG8_SCHED __builtin_amdgcn_sched_barrier(0)
;     ...
;         for (int t = 0; t < nt; t += 2) {
;     ...
;             PG8_LDA(At, 1, 1); PG8_STAGE(PG8_SB(1, 0), b3, voffB); PG8_STAGE(PG8_SB(1, 1), b3 + hstep, voffB); PG8_STAGE(PG8_SA(1, 0), a3, voffA);
;             PG8_WAIT_V(8); PG8_WAIT_L(0); PG8_BAR; PG8_MMA(1, 0, At, B0); PG8_MMA(1, 1, At, B1); PG8_BAR; PG8_SCHED;
	s_setprio 0
	s_add_i32 s48, s48, s5
	v_lshl_add_u64 v[198:199], v[198:199], 0, s[66:67]
	s_mov_b32 m0, s48
	ds_read_b128 v[164:167], v234 offset:49152
	ds_read_b128 v[168:171], v234 offset:50176
	ds_read_b128 v[172:175], v234 offset:51200
	ds_read_b128 v[176:179], v234 offset:52224
	ds_read_b128 v[180:183], v234 offset:53248
	ds_read_b128 v[184:187], v234 offset:54272
	ds_read_b128 v[206:209], v234 offset:55296
	ds_read_b128 v[210:213], v234 offset:56320
	global_load_lds_dwordx4 v[198:199], off
	s_add_i32 m0, s48, 0x2000
	s_add_u32 s62, s70, 0x160080
	v_lshl_add_u64 v[198:199], v[214:215], 0, s[66:67]
	s_addc_u32 s63, s71, 0
	s_add_i32 s48, s49, s5
	global_load_lds_dwordx4 v[198:199], off
	v_lshl_add_u64 v[198:199], s[62:63], 0, v[200:201]
	s_mov_b32 m0, s48
	s_nop 0
	global_load_lds_dwordx4 v[198:199], off
	v_lshl_add_u64 v[198:199], s[62:63], 0, v[188:189]
	s_add_i32 m0, s48, 0x2000
	s_nop 0
	global_load_lds_dwordx4 v[198:199], off
	v_lshl_add_u64 v[198:199], v[216:217], 0, s[66:67]
	s_mov_b32 m0, s53
	s_nop 0
	global_load_lds_dwordx4 v[198:199], off
	v_lshl_add_u64 v[198:199], v[218:219], 0, s[66:67]
	s_mov_b32 m0, s54
	s_nop 0
	global_load_lds_dwordx4 v[198:199], off
	s_waitcnt vmcnt(8) lgkmcnt(0)
	s_setprio 1
	s_barrier
	v_mfma_f32_16x16x32_bf16 v[64:67], v[108:111], v[164:167], v[64:67]
	v_mfma_f32_16x16x32_bf16 v[60:63], v[128:131], v[164:167], v[60:63]
	v_mfma_f32_16x16x32_bf16 v[48:51], v[108:111], v[172:175], v[48:51]
	v_mfma_f32_16x16x32_bf16 v[44:47], v[128:131], v[172:175], v[44:47]
	v_mfma_f32_16x16x32_bf16 v[32:35], v[108:111], v[180:183], v[32:35]
	v_mfma_f32_16x16x32_bf16 v[28:31], v[128:131], v[180:183], v[28:31]
	v_mfma_f32_16x16x32_bf16 v[16:19], v[108:111], v[206:209], v[16:19]
	v_mfma_f32_16x16x32_bf16 v[12:15], v[128:131], v[206:209], v[12:15]
	v_mfma_f32_16x16x32_bf16 v[64:67], v[112:115], v[168:171], v[64:67]
	v_mfma_f32_16x16x32_bf16 v[60:63], v[136:139], v[168:171], v[60:63]
	v_mfma_f32_16x16x32_bf16 v[48:51], v[112:115], v[176:179], v[48:51]
	v_mfma_f32_16x16x32_bf16 v[44:47], v[136:139], v[176:179], v[44:47]
	v_mfma_f32_16x16x32_bf16 v[32:35], v[112:115], v[184:187], v[32:35]
	v_mfma_f32_16x16x32_bf16 v[28:31], v[136:139], v[184:187], v[28:31]
	v_mfma_f32_16x16x32_bf16 v[16:19], v[112:115], v[210:213], v[16:19]
	v_mfma_f32_16x16x32_bf16 v[12:15], v[136:139], v[210:213], v[12:15]
	v_mfma_f32_16x16x32_bf16 v[56:59], v[148:151], v[164:167], v[56:59]
	v_mfma_f32_16x16x32_bf16 v[52:55], v[156:159], v[164:167], v[52:55]
	v_mfma_f32_16x16x32_bf16 v[40:43], v[148:151], v[172:175], v[40:43]
	v_mfma_f32_16x16x32_bf16 v[36:39], v[156:159], v[172:175], v[36:39]
	v_mfma_f32_16x16x32_bf16 v[24:27], v[148:151], v[180:183], v[24:27]
	v_mfma_f32_16x16x32_bf16 v[20:23], v[156:159], v[180:183], v[20:23]
	v_mfma_f32_16x16x32_bf16 v[8:11], v[148:151], v[206:209], v[8:11]
	v_mfma_f32_16x16x32_bf16 v[4:7], v[156:159], v[206:209], v[4:7]
	v_mfma_f32_16x16x32_bf16 v[56:59], v[152:155], v[168:171], v[56:59]
	v_mfma_f32_16x16x32_bf16 v[52:55], v[160:163], v[168:171], v[52:55]
	v_mfma_f32_16x16x32_bf16 v[40:43], v[152:155], v[176:179], v[40:43]
	v_mfma_f32_16x16x32_bf16 v[36:39], v[160:163], v[176:179], v[36:39]
	v_mfma_f32_16x16x32_bf16 v[24:27], v[152:155], v[184:187], v[24:27]
	v_mfma_f32_16x16x32_bf16 v[20:23], v[160:163], v[184:187], v[20:23]
	v_mfma_f32_16x16x32_bf16 v[8:11], v[152:155], v[210:213], v[8:11]
	v_mfma_f32_16x16x32_bf16 v[4:7], v[160:163], v[210:213], v[4:7]
	s_barrier
	s_setprio 0
	s_add_i32 s78, s78, 2
	s_add_u32 s73, s73, 0x100
	s_addc_u32 s75, s75, 0
	s_cmpk_gt_u32 s78, 0x55
	s_mov_b64 s[62:63], s[68:69]
	s_cbranch_scc0 .LBB0_667
	s_and_b64 vcc, exec, s[24:25]
	s_cbranch_vccz .LBB0_670
	s_barrier

; #define PG8_STAGE(bufoff, gbase, voff) do { _Pragma("unroll") for (int _i = 0; _i < 2; ++_i) \
;         __builtin_amdgcn_global_load_lds((const unsigned*)((const char*)(gbase) + (voff)[_i]), (PG8_LAS unsigned*)(lds + (bufoff) + ldsw + _i * 8192), 16, 0, 0); } while (0)
; #define PG8_LDA(dst, b, h) do { _Pragma("unroll") for (int m = 0; m < 4; ++m) _Pragma("unroll") for (int k = 0; k < 2; ++k) dst[m][k] = *(const PG8_LAS bf16x8*)(lds + PG8_SA(b, h) + aoff + m * 2048 + k * 1024); } while (0)
; #define PG8_LDB(dst, b, h) do { _Pragma("unroll") for (int n = 0; n < 2; ++n) _Pragma("unroll") for (int k = 0; k < 2; ++k) dst[n][k] = *(const PG8_LAS bf16x8*)(lds + PG8_SB(b, h) + boff + n * 2048 + k * 1024); } while (0)
; #define PG8_MMA(ai, bj, At, Bt) do { __builtin_amdgcn_s_setprio(1); _Pragma("unroll") for (int m = 0; m < 4; ++m) _Pragma("unroll") for (int n = 0; n < 2; ++n) _Pragma("unroll") for (int k = 0; k < 2; ++k) \
;         acc[ai][bj][m][n] = __builtin_amdgcn_mfma_f32_16x16x32_bf16(Bt[n][k], At[m][k], acc[ai][bj][m][n], 0, 0, 0); __builtin_amdgcn_s_setprio(0); } while (0)
; #define PG8_WAIT_V(n) asm volatile("s_waitcnt vmcnt(" #n ")" ::: "memory")
;     ...
;             const char* a1 = cA + (size_t)(t + 1) * kstep;
;             const char* a2 = last ? nA : cA + (size_t)(t + 2) * kstep; const char* b2 = last ? nB : cB + (size_t)(t + 2) * kstep;
;             const char* a3 = a2 + kstep; const char* b3 = b2 + kstep;
;             if (last && has_next) S.a_ready(nxt);
;             if (t == 0) E.pre_issue(pre, cur, tid, ui); else if (t == 2) E.pre_finish(pre, tid, ui);
;             if constexpr (SP2) {
;             PG8_LDB(B0, 0, 0); PG8_LDB(B1, 0, 1); PG8_SCHED; PG8_LDA(At, 0, 0); PG8_STAGE(PG8_SA(1, 1), a1 + hstep, voffA);
;             PG8_WAIT_V(8); PG8_WAIT_L(0); PG8_BAR; PG8_MMA(0, 0, At, B0); PG8_MMA(0, 1, At, B1); PG8_BAR; PG8_SCHED;
;             PG8_LDA(At, 0, 1); PG8_STAGE(PG8_SB(0, 0), b2, voffB); PG8_STAGE(PG8_SB(0, 1), b2 + hstep, voffB); PG8_STAGE(PG8_SA(0, 0), a2, voffA);
;             PG8_WAIT_V(8); PG8_WAIT_L(0); PG8_BAR; PG8_MMA(1, 0, At, B0); PG8_MMA(1, 1, At, B1); PG8_BAR; PG8_SCHED;
;             PG8_LDB(B0, 1, 0); PG8_LDB(B1, 1, 1); PG8_SCHED; PG8_LDA(At, 1, 0); PG8_STAGE(PG8_SA(0, 1), a2 + hstep, voffA);
;             PG8_WAIT_V(8); PG8_WAIT_L(0); PG8_BAR; PG8_MMA(0, 0, At, B0); PG8_MMA(0, 1, At, B1); PG8_BAR; PG8_SCHED;
.LBB0_753:
	s_add_u32 s48, s68, 0xfff80080
	s_addc_u32 s49, s69, -1
	s_add_i32 s61, 0, 0x10000
	s_cmp_eq_u32 s59, 28
	s_cselect_b32 s79, s53, s49
	s_cselect_b32 s78, s54, s48
	s_cselect_b32 s77, s25, s58
	s_cselect_b32 s76, s55, s56
	s_add_i32 s48, 0, 0x14000
	ds_read_b128 v[132:135], v251
	ds_read_b128 v[158:161], v251 offset:1024
	ds_read_b128 v[162:165], v251 offset:2048
	ds_read_b128 v[166:169], v251 offset:3072
	ds_read_b128 v[170:173], v251 offset:16384
	ds_read_b128 v[176:179], v251 offset:17408
	ds_read_b128 v[180:183], v251 offset:18432
	ds_read_b128 v[184:187], v251 offset:19456
	v_lshl_add_u64 v[232:233], s[68:69], 0, v[150:151]
	s_add_i32 m0, s1, 0xc000
	ds_read_b128 v[188:191], v175
	ds_read_b128 v[192:195], v175 offset:1024
	ds_read_b128 v[196:199], v175 offset:2048
	ds_read_b128 v[206:209], v175 offset:3072
	ds_read_b128 v[210:213], v175 offset:4096
	ds_read_b128 v[214:217], v175 offset:5120
	ds_read_b128 v[218:221], v175 offset:6144
	ds_read_b128 v[222:225], v175 offset:7168
	global_load_lds_dwordx4 v[232:233], off
	v_lshl_add_u64 v[232:233], s[68:69], 0, v[152:153]
	s_add_i32 m0, s1, 0xe000
	s_nop 0
	global_load_lds_dwordx4 v[232:233], off
	s_waitcnt vmcnt(8) lgkmcnt(0)
	s_setprio 1
	s_barrier
	v_mfma_f32_16x16x32_bf16 v[128:131], v[132:135], v[188:191], v[128:131]
	v_mfma_f32_16x16x32_bf16 v[124:127], v[162:165], v[188:191], v[124:127]
	v_mfma_f32_16x16x32_bf16 v[116:119], v[132:135], v[196:199], v[116:119]
	v_mfma_f32_16x16x32_bf16 v[108:111], v[162:165], v[196:199], v[108:111]
	v_mfma_f32_16x16x32_bf16 v[100:103], v[132:135], v[210:213], v[100:103]
	v_mfma_f32_16x16x32_bf16 v[92:95], v[162:165], v[210:213], v[92:95]
	v_mfma_f32_16x16x32_bf16 v[84:87], v[132:135], v[218:221], v[84:87]
	v_mfma_f32_16x16x32_bf16 v[76:79], v[162:165], v[218:221], v[76:79]
	v_mfma_f32_16x16x32_bf16 v[128:131], v[158:161], v[192:195], v[128:131]
	v_mfma_f32_16x16x32_bf16 v[124:127], v[166:169], v[192:195], v[124:127]
	v_mfma_f32_16x16x32_bf16 v[116:119], v[158:161], v[206:209], v[116:119]
	v_mfma_f32_16x16x32_bf16 v[108:111], v[166:169], v[206:209], v[108:111]
	v_mfma_f32_16x16x32_bf16 v[100:103], v[158:161], v[214:217], v[100:103]
	v_mfma_f32_16x16x32_bf16 v[92:95], v[166:169], v[214:217], v[92:95]
	v_mfma_f32_16x16x32_bf16 v[84:87], v[158:161], v[222:225], v[84:87]
	v_mfma_f32_16x16x32_bf16 v[76:79], v[166:169], v[222:225], v[76:79]
	v_mfma_f32_16x16x32_bf16 v[120:123], v[170:173], v[188:191], v[120:123]
	v_mfma_f32_16x16x32_bf16 v[112:115], v[180:183], v[188:191], v[112:115]
	v_mfma_f32_16x16x32_bf16 v[104:107], v[170:173], v[196:199], v[104:107]
	v_mfma_f32_16x16x32_bf16 v[96:99], v[180:183], v[196:199], v[96:99]
	v_mfma_f32_16x16x32_bf16 v[88:91], v[170:173], v[210:213], v[88:91]
	v_mfma_f32_16x16x32_bf16 v[80:83], v[180:183], v[210:213], v[80:83]
	v_mfma_f32_16x16x32_bf16 v[72:75], v[170:173], v[218:221], v[72:75]
	v_mfma_f32_16x16x32_bf16 v[68:71], v[180:183], v[218:221], v[68:71]
	v_mfma_f32_16x16x32_bf16 v[120:123], v[176:179], v[192:195], v[120:123]
	v_mfma_f32_16x16x32_bf16 v[112:115], v[184:187], v[192:195], v[112:115]
	v_mfma_f32_16x16x32_bf16 v[104:107], v[176:179], v[206:209], v[104:107]
	v_mfma_f32_16x16x32_bf16 v[96:99], v[184:187], v[206:209], v[96:99]
	v_mfma_f32_16x16x32_bf16 v[88:91], v[176:179], v[214:217], v[88:91]
	v_mfma_f32_16x16x32_bf16 v[80:83], v[184:187], v[214:217], v[80:83]
	v_mfma_f32_16x16x32_bf16 v[72:75], v[176:179], v[222:225], v[72:75]
	v_mfma_f32_16x16x32_bf16 v[68:71], v[184:187], v[222:225], v[68:71]
	s_barrier
	s_setprio 0
	s_add_i32 s49, s61, s0
	v_lshl_add_u64 v[232:233], s[76:77], 0, v[140:141]
	s_mov_b32 m0, s49
	ds_read_b128 v[188:191], v175 offset:16384
	ds_read_b128 v[192:195], v175 offset:17408
	ds_read_b128 v[196:199], v175 offset:18432
	ds_read_b128 v[206:209], v175 offset:19456
	ds_read_b128 v[210:213], v175 offset:20480
	ds_read_b128 v[214:217], v175 offset:21504
	ds_read_b128 v[218:221], v175 offset:22528
	ds_read_b128 v[222:225], v175 offset:23552
	global_load_lds_dwordx4 v[232:233], off
	s_add_i32 m0, s49, 0x2000
	s_add_u32 s82, s76, 0x80000
	v_lshl_add_u64 v[234:235], s[76:77], 0, v[136:137]
	s_addc_u32 s83, s77, 0
	s_add_i32 s48, s48, s0
	global_load_lds_dwordx4 v[234:235], off
	v_lshl_add_u64 v[236:237], s[82:83], 0, v[140:141]
	s_mov_b32 m0, s48
	v_lshl_add_u64 v[238:239], s[78:79], 0, v[138:139]
	global_load_lds_dwordx4 v[236:237], off
	v_lshl_add_u64 v[236:237], s[82:83], 0, v[136:137]
	s_add_i32 m0, s48, 0x2000
	s_nop 0
	global_load_lds_dwordx4 v[236:237], off
	v_lshl_add_u64 v[236:237], s[78:79], 0, v[142:143]
	s_mov_b32 m0, s1
	s_nop 0
	global_load_lds_dwordx4 v[236:237], off
	s_mov_b32 m0, s4
	s_nop 0
	global_load_lds_dwordx4 v[238:239], off
	s_waitcnt vmcnt(8) lgkmcnt(0)
	s_setprio 1
	s_barrier
; #define PG8_STAGE(bufoff, gbase, voff) do { _Pragma("unroll") for (int _i = 0; _i < 2; ++_i) \
;         __builtin_amdgcn_global_load_lds((const unsigned*)((const char*)(gbase) + (voff)[_i]), (PG8_LAS unsigned*)(lds + (bufoff) + ldsw + _i * 8192), 16, 0, 0); } while (0)
; #define PG8_LDA(dst, b, h) do { _Pragma("unroll") for (int m = 0; m < 4; ++m) _Pragma("unroll") for (int k = 0; k < 2; ++k) dst[m][k] = *(const PG8_LAS bf16x8*)(lds + PG8_SA(b, h) + aoff + m * 2048 + k * 1024); } while (0)
; #define PG8_LDB(dst, b, h) do { _Pragma("unroll") for (int n = 0; n < 2; ++n) _Pragma("unroll") for (int k = 0; k < 2; ++k) dst[n][k] = *(const PG8_LAS bf16x8*)(lds + PG8_SB(b, h) + boff + n * 2048 + k * 1024); } while (0)
; #define PG8_MMA(ai, bj, At, Bt) do { __builtin_amdgcn_s_setprio(1); _Pragma("unroll") for (int m = 0; m < 4; ++m) _Pragma("unroll") for (int n = 0; n < 2; ++n) _Pragma("unroll") for (int k = 0; k < 2; ++k) \
;         acc[ai][bj][m][n] = __builtin_amdgcn_mfma_f32_16x16x32_bf16(Bt[n][k], At[m][k], acc[ai][bj][m][n], 0, 0, 0); __builtin_amdgcn_s_setprio(0); } while (0)
; #define PG8_WAIT_V(n) asm volatile("s_waitcnt vmcnt(" #n ")" ::: "memory")
; #define PG8_WAIT_L(n) asm volatile("s_waitcnt lgkmcnt(" #n ")" ::: "memory")
; #define PG8_BAR __builtin_amdgcn_s_barrier()
; #define PG8_SCHED __builtin_amdgcn_sched_barrier(0)
;     ...
;             PG8_WAIT_V(8); PG8_WAIT_L(0); PG8_BAR; PG8_MMA(1, 0, At, B0); PG8_MMA(1, 1, At, B1); PG8_BAR; PG8_SCHED;
;             PG8_LDB(B0, 1, 0); PG8_LDB(B1, 1, 1); PG8_SCHED; PG8_LDA(At, 1, 0); PG8_STAGE(PG8_SA(0, 1), a2 + hstep, voffA);
;             PG8_WAIT_V(8); PG8_WAIT_L(0); PG8_BAR; PG8_MMA(0, 0, At, B0); PG8_MMA(0, 1, At, B1); PG8_BAR; PG8_SCHED;
;             PG8_LDA(At, 1, 1); PG8_STAGE(PG8_SB(1, 0), b3, voffB); PG8_STAGE(PG8_SB(1, 1), b3 + hstep, voffB); PG8_STAGE(PG8_SA(1, 0), a3, voffA);
;             PG8_WAIT_V(8); PG8_WAIT_L(0); PG8_BAR; PG8_MMA(1, 0, At, B0); PG8_MMA(1, 1, At, B1); PG8_BAR; PG8_SCHED;
	v_mfma_f32_16x16x32_bf16 v[64:67], v[132:135], v[188:191], v[64:67]
	v_mfma_f32_16x16x32_bf16 v[60:63], v[162:165], v[188:191], v[60:63]
	v_mfma_f32_16x16x32_bf16 v[52:55], v[132:135], v[196:199], v[52:55]
	v_mfma_f32_16x16x32_bf16 v[44:47], v[162:165], v[196:199], v[44:47]
	v_mfma_f32_16x16x32_bf16 v[36:39], v[132:135], v[210:213], v[36:39]
	v_mfma_f32_16x16x32_bf16 v[28:31], v[162:165], v[210:213], v[28:31]
	v_mfma_f32_16x16x32_bf16 v[20:23], v[132:135], v[218:221], v[20:23]
	v_mfma_f32_16x16x32_bf16 v[12:15], v[162:165], v[218:221], v[12:15]
	v_mfma_f32_16x16x32_bf16 v[64:67], v[158:161], v[192:195], v[64:67]
	v_mfma_f32_16x16x32_bf16 v[60:63], v[166:169], v[192:195], v[60:63]
	v_mfma_f32_16x16x32_bf16 v[52:55], v[158:161], v[206:209], v[52:55]
	v_mfma_f32_16x16x32_bf16 v[44:47], v[166:169], v[206:209], v[44:47]
	v_mfma_f32_16x16x32_bf16 v[36:39], v[158:161], v[214:217], v[36:39]
	v_mfma_f32_16x16x32_bf16 v[28:31], v[166:169], v[214:217], v[28:31]
	v_mfma_f32_16x16x32_bf16 v[20:23], v[158:161], v[222:225], v[20:23]
	v_mfma_f32_16x16x32_bf16 v[12:15], v[166:169], v[222:225], v[12:15]
	v_mfma_f32_16x16x32_bf16 v[56:59], v[170:173], v[188:191], v[56:59]
	v_mfma_f32_16x16x32_bf16 v[48:51], v[180:183], v[188:191], v[48:51]
	v_mfma_f32_16x16x32_bf16 v[40:43], v[170:173], v[196:199], v[40:43]
	v_mfma_f32_16x16x32_bf16 v[32:35], v[180:183], v[196:199], v[32:35]
	v_mfma_f32_16x16x32_bf16 v[24:27], v[170:173], v[210:213], v[24:27]
	v_mfma_f32_16x16x32_bf16 v[16:19], v[180:183], v[210:213], v[16:19]
	v_mfma_f32_16x16x32_bf16 v[8:11], v[170:173], v[218:221], v[8:11]
	v_mfma_f32_16x16x32_bf16 v[4:7], v[180:183], v[218:221], v[4:7]
	v_mfma_f32_16x16x32_bf16 v[56:59], v[176:179], v[192:195], v[56:59]
	v_mfma_f32_16x16x32_bf16 v[48:51], v[184:187], v[192:195], v[48:51]
	v_mfma_f32_16x16x32_bf16 v[40:43], v[176:179], v[206:209], v[40:43]
	v_mfma_f32_16x16x32_bf16 v[32:35], v[184:187], v[206:209], v[32:35]
	v_mfma_f32_16x16x32_bf16 v[24:27], v[176:179], v[214:217], v[24:27]
	v_mfma_f32_16x16x32_bf16 v[16:19], v[184:187], v[214:217], v[16:19]
	v_mfma_f32_16x16x32_bf16 v[8:11], v[176:179], v[222:225], v[8:11]
	v_mfma_f32_16x16x32_bf16 v[4:7], v[184:187], v[222:225], v[4:7]
	s_barrier
	s_setprio 0
	s_add_i32 s48, 0, 0x18000
	s_add_i32 s49, 0, 0x1c000
	ds_read_b128 v[132:135], v251 offset:32768
	ds_read_b128 v[158:161], v251 offset:33792
	ds_read_b128 v[162:165], v251 offset:34816
	ds_read_b128 v[166:169], v251 offset:35840
	ds_read_b128 v[170:173], v251 offset:49152
	ds_read_b128 v[176:179], v251 offset:50176
	ds_read_b128 v[180:183], v251 offset:51200
	ds_read_b128 v[184:187], v251 offset:52224
	s_add_u32 s78, s78, 0x80000
	s_addc_u32 s79, s79, 0
	s_mov_b32 m0, s5
	v_lshl_add_u64 v[240:241], s[78:79], 0, v[142:143]
	ds_read_b128 v[188:191], v175 offset:32768
	ds_read_b128 v[192:195], v175 offset:33792
	ds_read_b128 v[196:199], v175 offset:34816
	ds_read_b128 v[206:209], v175 offset:35840
	ds_read_b128 v[210:213], v175 offset:36864
	ds_read_b128 v[214:217], v175 offset:37888
	ds_read_b128 v[218:221], v175 offset:38912
	ds_read_b128 v[222:225], v175 offset:39936
	global_load_lds_dwordx4 v[240:241], off
	v_lshl_add_u64 v[240:241], s[78:79], 0, v[138:139]
	s_mov_b32 m0, s7
	s_nop 0
	global_load_lds_dwordx4 v[240:241], off
	s_waitcnt vmcnt(8) lgkmcnt(0)
	s_setprio 1
	s_barrier
	v_mfma_f32_16x16x32_bf16 v[128:131], v[132:135], v[188:191], v[128:131]
	v_mfma_f32_16x16x32_bf16 v[124:127], v[162:165], v[188:191], v[124:127]
	v_mfma_f32_16x16x32_bf16 v[116:119], v[132:135], v[196:199], v[116:119]
	v_mfma_f32_16x16x32_bf16 v[108:111], v[162:165], v[196:199], v[108:111]
	v_mfma_f32_16x16x32_bf16 v[100:103], v[132:135], v[210:213], v[100:103]
	v_mfma_f32_16x16x32_bf16 v[92:95], v[162:165], v[210:213], v[92:95]
	v_mfma_f32_16x16x32_bf16 v[84:87], v[132:135], v[218:221], v[84:87]
	v_mfma_f32_16x16x32_bf16 v[76:79], v[162:165], v[218:221], v[76:79]
	v_mfma_f32_16x16x32_bf16 v[128:131], v[158:161], v[192:195], v[128:131]
	v_mfma_f32_16x16x32_bf16 v[124:127], v[166:169], v[192:195], v[124:127]
	v_mfma_f32_16x16x32_bf16 v[116:119], v[158:161], v[206:209], v[116:119]
	v_mfma_f32_16x16x32_bf16 v[108:111], v[166:169], v[206:209], v[108:111]
	v_mfma_f32_16x16x32_bf16 v[100:103], v[158:161], v[214:217], v[100:103]
	v_mfma_f32_16x16x32_bf16 v[92:95], v[166:169], v[214:217], v[92:95]
	v_mfma_f32_16x16x32_bf16 v[84:87], v[158:161], v[222:225], v[84:87]
	v_mfma_f32_16x16x32_bf16 v[76:79], v[166:169], v[222:225], v[76:79]
	v_mfma_f32_16x16x32_bf16 v[120:123], v[170:173], v[188:191], v[120:123]
	v_mfma_f32_16x16x32_bf16 v[112:115], v[180:183], v[188:191], v[112:115]
	v_mfma_f32_16x16x32_bf16 v[104:107], v[170:173], v[196:199], v[104:107]
	v_mfma_f32_16x16x32_bf16 v[96:99], v[180:183], v[196:199], v[96:99]
	v_mfma_f32_16x16x32_bf16 v[88:91], v[170:173], v[210:213], v[88:91]
	v_mfma_f32_16x16x32_bf16 v[80:83], v[180:183], v[210:213], v[80:83]
	v_mfma_f32_16x16x32_bf16 v[72:75], v[170:173], v[218:221], v[72:75]
	v_mfma_f32_16x16x32_bf16 v[68:71], v[180:183], v[218:221], v[68:71]
	v_mfma_f32_16x16x32_bf16 v[120:123], v[176:179], v[192:195], v[120:123]
	v_mfma_f32_16x16x32_bf16 v[112:115], v[184:187], v[192:195], v[112:115]
	v_mfma_f32_16x16x32_bf16 v[104:107], v[176:179], v[206:209], v[104:107]
	v_mfma_f32_16x16x32_bf16 v[96:99], v[184:187], v[206:209], v[96:99]
	v_mfma_f32_16x16x32_bf16 v[88:91], v[176:179], v[214:217], v[88:91]
	v_mfma_f32_16x16x32_bf16 v[80:83], v[184:187], v[214:217], v[80:83]
	v_mfma_f32_16x16x32_bf16 v[72:75], v[176:179], v[222:225], v[72:75]
	v_mfma_f32_16x16x32_bf16 v[68:71], v[184:187], v[222:225], v[68:71]
	s_barrier
; #define PG8_STAGE(bufoff, gbase, voff) do { _Pragma("unroll") for (int _i = 0; _i < 2; ++_i) \
;         __builtin_amdgcn_global_load_lds((const unsigned*)((const char*)(gbase) + (voff)[_i]), (PG8_LAS unsigned*)(lds + (bufoff) + ldsw + _i * 8192), 16, 0, 0); } while (0)
; #define PG8_LDA(dst, b, h) do { _Pragma("unroll") for (int m = 0; m < 4; ++m) _Pragma("unroll") for (int k = 0; k < 2; ++k) dst[m][k] = *(const PG8_LAS bf16x8*)(lds + PG8_SA(b, h) + aoff + m * 2048 + k * 1024); } while (0)
; #define PG8_MMA(ai, bj, At, Bt) do { __builtin_amdgcn_s_setprio(1); _Pragma("unroll") for (int m = 0; m < 4; ++m) _Pragma("unroll") for (int n = 0; n < 2; ++n) _Pragma("unroll") for (int k = 0; k < 2; ++k) \
;         acc[ai][bj][m][n] = __builtin_amdgcn_mfma_f32_16x16x32_bf16(Bt[n][k], At[m][k], acc[ai][bj][m][n], 0, 0, 0); __builtin_amdgcn_s_setprio(0); } while (0)
; #define PG8_WAIT_V(n) asm volatile("s_waitcnt vmcnt(" #n ")" ::: "memory")
; #define PG8_WAIT_L(n) asm volatile("s_waitcnt lgkmcnt(" #n ")" ::: "memory")
; #define PG8_BAR __builtin_amdgcn_s_barrier()
; #define PG8_SCHED __builtin_amdgcn_sched_barrier(0)
;     ...
;         for (int t = 0; t < nt; t += 2) {
;     ...
;             PG8_LDA(At, 1, 1); PG8_STAGE(PG8_SB(1, 0), b3, voffB); PG8_STAGE(PG8_SB(1, 1), b3 + hstep, voffB); PG8_STAGE(PG8_SA(1, 0), a3, voffA);
;             PG8_WAIT_V(8); PG8_WAIT_L(0); PG8_BAR; PG8_MMA(1, 0, At, B0); PG8_MMA(1, 1, At, B1); PG8_BAR; PG8_SCHED;
	s_setprio 0
	s_add_i32 s48, s48, s0
	v_lshl_add_u64 v[232:233], v[232:233], 0, s[66:67]
	s_mov_b32 m0, s48
	ds_read_b128 v[188:191], v175 offset:49152
	ds_read_b128 v[192:195], v175 offset:50176
	ds_read_b128 v[196:199], v175 offset:51200
	ds_read_b128 v[206:209], v175 offset:52224
	ds_read_b128 v[210:213], v175 offset:53248
	ds_read_b128 v[214:217], v175 offset:54272
	ds_read_b128 v[218:221], v175 offset:55296
	ds_read_b128 v[222:225], v175 offset:56320
	global_load_lds_dwordx4 v[232:233], off
	s_add_i32 m0, s48, 0x2000
	s_add_u32 s76, s76, 0x80080
	v_lshl_add_u64 v[232:233], v[234:235], 0, s[66:67]
	s_addc_u32 s77, s77, 0
	s_add_i32 s48, s49, s0
	global_load_lds_dwordx4 v[232:233], off
	v_lshl_add_u64 v[232:233], s[76:77], 0, v[140:141]
	s_mov_b32 m0, s48
	s_nop 0
	global_load_lds_dwordx4 v[232:233], off
	v_lshl_add_u64 v[232:233], s[76:77], 0, v[136:137]
	s_add_i32 m0, s48, 0x2000
	s_nop 0
	global_load_lds_dwordx4 v[232:233], off
	v_lshl_add_u64 v[232:233], v[236:237], 0, s[66:67]
	s_mov_b32 m0, s21
	s_nop 0
	global_load_lds_dwordx4 v[232:233], off
	v_lshl_add_u64 v[232:233], v[238:239], 0, s[66:67]
	s_mov_b32 m0, s23
	s_nop 0
	global_load_lds_dwordx4 v[232:233], off
	s_waitcnt vmcnt(8) lgkmcnt(0)
	s_setprio 1
	s_barrier
	v_mfma_f32_16x16x32_bf16 v[64:67], v[132:135], v[188:191], v[64:67]
	v_mfma_f32_16x16x32_bf16 v[60:63], v[162:165], v[188:191], v[60:63]
	v_mfma_f32_16x16x32_bf16 v[52:55], v[132:135], v[196:199], v[52:55]
	v_mfma_f32_16x16x32_bf16 v[44:47], v[162:165], v[196:199], v[44:47]
	v_mfma_f32_16x16x32_bf16 v[36:39], v[132:135], v[210:213], v[36:39]
	v_mfma_f32_16x16x32_bf16 v[28:31], v[162:165], v[210:213], v[28:31]
	v_mfma_f32_16x16x32_bf16 v[20:23], v[132:135], v[218:221], v[20:23]
	v_mfma_f32_16x16x32_bf16 v[12:15], v[162:165], v[218:221], v[12:15]
	v_mfma_f32_16x16x32_bf16 v[64:67], v[158:161], v[192:195], v[64:67]
	v_mfma_f32_16x16x32_bf16 v[60:63], v[166:169], v[192:195], v[60:63]
	v_mfma_f32_16x16x32_bf16 v[52:55], v[158:161], v[206:209], v[52:55]
	v_mfma_f32_16x16x32_bf16 v[44:47], v[166:169], v[206:209], v[44:47]
	v_mfma_f32_16x16x32_bf16 v[36:39], v[158:161], v[214:217], v[36:39]
	v_mfma_f32_16x16x32_bf16 v[28:31], v[166:169], v[214:217], v[28:31]
	v_mfma_f32_16x16x32_bf16 v[20:23], v[158:161], v[222:225], v[20:23]
	v_mfma_f32_16x16x32_bf16 v[12:15], v[166:169], v[222:225], v[12:15]
	v_mfma_f32_16x16x32_bf16 v[56:59], v[170:173], v[188:191], v[56:59]
	v_mfma_f32_16x16x32_bf16 v[48:51], v[180:183], v[188:191], v[48:51]
	v_mfma_f32_16x16x32_bf16 v[40:43], v[170:173], v[196:199], v[40:43]
	v_mfma_f32_16x16x32_bf16 v[32:35], v[180:183], v[196:199], v[32:35]
	v_mfma_f32_16x16x32_bf16 v[24:27], v[170:173], v[210:213], v[24:27]
	v_mfma_f32_16x16x32_bf16 v[16:19], v[180:183], v[210:213], v[16:19]
	v_mfma_f32_16x16x32_bf16 v[8:11], v[170:173], v[218:221], v[8:11]
	v_mfma_f32_16x16x32_bf16 v[4:7], v[180:183], v[218:221], v[4:7]
	v_mfma_f32_16x16x32_bf16 v[56:59], v[176:179], v[192:195], v[56:59]
	v_mfma_f32_16x16x32_bf16 v[48:51], v[184:187], v[192:195], v[48:51]
	v_mfma_f32_16x16x32_bf16 v[40:43], v[176:179], v[206:209], v[40:43]
	v_mfma_f32_16x16x32_bf16 v[32:35], v[184:187], v[206:209], v[32:35]
	v_mfma_f32_16x16x32_bf16 v[24:27], v[176:179], v[214:217], v[24:27]
	v_mfma_f32_16x16x32_bf16 v[16:19], v[184:187], v[214:217], v[16:19]
	v_mfma_f32_16x16x32_bf16 v[8:11], v[176:179], v[222:225], v[8:11]
	v_mfma_f32_16x16x32_bf16 v[4:7], v[184:187], v[222:225], v[4:7]
	s_barrier
	s_setprio 0
	s_add_i32 s59, s59, 2
	s_add_u32 s68, s68, 0x100
	s_addc_u32 s69, s69, 0
	s_add_u32 s56, s56, 0x100
	s_addc_u32 s58, s58, 0
	s_cmp_gt_u32 s59, 29
	s_cbranch_scc0 .LBB0_753
	s_and_b64 vcc, exec, s[12:13]
	s_cbranch_vccz .LBB0_756
	s_barrier

.LBB0_998:
	s_add_u32 s48, s68, 0xfff80080
	s_addc_u32 s49, s69, -1
	s_add_i32 s81, 0, 0x10000
	s_cmp_eq_u32 s79, 28
	s_cselect_b32 s77, s51, s49
	s_cselect_b32 s76, s59, s48
	s_cselect_b32 s71, s25, s78
	s_cselect_b32 s70, s73, s75
	s_add_i32 s48, 0, 0x14000
	ds_read_b128 v[108:111], v251
	ds_read_b128 v[112:115], v251 offset:1024
	ds_read_b128 v[128:131], v251 offset:2048
	ds_read_b128 v[136:139], v251 offset:3072
	ds_read_b128 v[148:151], v251 offset:16384
	ds_read_b128 v[152:155], v251 offset:17408
	ds_read_b128 v[156:159], v251 offset:18432
	ds_read_b128 v[160:163], v251 offset:19456
	v_lshl_add_u64 v[198:199], s[68:69], 0, v[196:197]
	s_add_i32 m0, s6, 0xc000
	ds_read_b128 v[164:167], v234
	ds_read_b128 v[168:171], v234 offset:1024
	ds_read_b128 v[172:175], v234 offset:2048
	ds_read_b128 v[176:179], v234 offset:3072
	ds_read_b128 v[180:183], v234 offset:4096
	ds_read_b128 v[184:187], v234 offset:5120
	ds_read_b128 v[206:209], v234 offset:6144
	ds_read_b128 v[210:213], v234 offset:7168
	global_load_lds_dwordx4 v[198:199], off
	v_lshl_add_u64 v[198:199], s[68:69], 0, v[194:195]
	s_add_i32 m0, s6, 0xe000
	s_nop 0
	global_load_lds_dwordx4 v[198:199], off
	s_waitcnt vmcnt(8) lgkmcnt(0)
	s_setprio 1
	s_barrier
	v_mfma_f32_16x16x32_bf16 v[144:147], v[108:111], v[164:167], v[144:147]
	v_mfma_f32_16x16x32_bf16 v[140:143], v[128:131], v[164:167], v[140:143]
	v_mfma_f32_16x16x32_bf16 v[120:123], v[108:111], v[172:175], v[120:123]
	v_mfma_f32_16x16x32_bf16 v[116:119], v[128:131], v[172:175], v[116:119]
	v_mfma_f32_16x16x32_bf16 v[96:99], v[108:111], v[180:183], v[96:99]
	v_mfma_f32_16x16x32_bf16 v[92:95], v[128:131], v[180:183], v[92:95]
	v_mfma_f32_16x16x32_bf16 v[80:83], v[108:111], v[206:209], v[80:83]
	v_mfma_f32_16x16x32_bf16 v[76:79], v[128:131], v[206:209], v[76:79]
	v_mfma_f32_16x16x32_bf16 v[144:147], v[112:115], v[168:171], v[144:147]
	v_mfma_f32_16x16x32_bf16 v[140:143], v[136:139], v[168:171], v[140:143]
	v_mfma_f32_16x16x32_bf16 v[120:123], v[112:115], v[176:179], v[120:123]
	v_mfma_f32_16x16x32_bf16 v[116:119], v[136:139], v[176:179], v[116:119]
	v_mfma_f32_16x16x32_bf16 v[96:99], v[112:115], v[184:187], v[96:99]
	v_mfma_f32_16x16x32_bf16 v[92:95], v[136:139], v[184:187], v[92:95]
	v_mfma_f32_16x16x32_bf16 v[80:83], v[112:115], v[210:213], v[80:83]
	v_mfma_f32_16x16x32_bf16 v[76:79], v[136:139], v[210:213], v[76:79]
	v_mfma_f32_16x16x32_bf16 v[132:135], v[148:151], v[164:167], v[132:135]
	v_mfma_f32_16x16x32_bf16 v[124:127], v[156:159], v[164:167], v[124:127]
	v_mfma_f32_16x16x32_bf16 v[104:107], v[148:151], v[172:175], v[104:107]
	v_mfma_f32_16x16x32_bf16 v[100:103], v[156:159], v[172:175], v[100:103]
	v_mfma_f32_16x16x32_bf16 v[88:91], v[148:151], v[180:183], v[88:91]
	v_mfma_f32_16x16x32_bf16 v[84:87], v[156:159], v[180:183], v[84:87]
	v_mfma_f32_16x16x32_bf16 v[72:75], v[148:151], v[206:209], v[72:75]
	v_mfma_f32_16x16x32_bf16 v[68:71], v[156:159], v[206:209], v[68:71]
	v_mfma_f32_16x16x32_bf16 v[132:135], v[152:155], v[168:171], v[132:135]
	v_mfma_f32_16x16x32_bf16 v[124:127], v[160:163], v[168:171], v[124:127]
	v_mfma_f32_16x16x32_bf16 v[104:107], v[152:155], v[176:179], v[104:107]
	v_mfma_f32_16x16x32_bf16 v[100:103], v[160:163], v[176:179], v[100:103]
	v_mfma_f32_16x16x32_bf16 v[88:91], v[152:155], v[184:187], v[88:91]
	v_mfma_f32_16x16x32_bf16 v[84:87], v[160:163], v[184:187], v[84:87]
	v_mfma_f32_16x16x32_bf16 v[72:75], v[152:155], v[210:213], v[72:75]
	v_mfma_f32_16x16x32_bf16 v[68:71], v[160:163], v[210:213], v[68:71]
	s_barrier
	s_setprio 0
	s_add_i32 s49, s81, s5
	v_lshl_add_u64 v[198:199], s[70:71], 0, v[200:201]
	s_mov_b32 m0, s49
	ds_read_b128 v[164:167], v234 offset:16384
	ds_read_b128 v[168:171], v234 offset:17408
	ds_read_b128 v[172:175], v234 offset:18432
	ds_read_b128 v[176:179], v234 offset:19456
	ds_read_b128 v[180:183], v234 offset:20480
	ds_read_b128 v[184:187], v234 offset:21504
	ds_read_b128 v[206:209], v234 offset:22528
	ds_read_b128 v[210:213], v234 offset:23552
	global_load_lds_dwordx4 v[198:199], off
	s_add_i32 m0, s49, 0x2000
	s_add_u32 s84, s70, 0x80000
	v_lshl_add_u64 v[214:215], s[70:71], 0, v[188:189]
	s_addc_u32 s85, s71, 0
	s_add_i32 s48, s48, s5
	global_load_lds_dwordx4 v[214:215], off
	v_lshl_add_u64 v[216:217], s[84:85], 0, v[200:201]
	s_mov_b32 m0, s48
	v_lshl_add_u64 v[218:219], s[76:77], 0, v[190:191]
	global_load_lds_dwordx4 v[216:217], off
	v_lshl_add_u64 v[216:217], s[84:85], 0, v[188:189]
	s_add_i32 m0, s48, 0x2000
	s_nop 0
	global_load_lds_dwordx4 v[216:217], off
	v_lshl_add_u64 v[216:217], s[76:77], 0, v[192:193]
	s_mov_b32 m0, s6
	s_nop 0
	global_load_lds_dwordx4 v[216:217], off
	s_mov_b32 m0, s20
	s_nop 0
	global_load_lds_dwordx4 v[218:219], off
	s_waitcnt vmcnt(8) lgkmcnt(0)
	s_setprio 1
	s_barrier
	v_mfma_f32_16x16x32_bf16 v[64:67], v[108:111], v[164:167], v[64:67]
	v_mfma_f32_16x16x32_bf16 v[60:63], v[128:131], v[164:167], v[60:63]
	v_mfma_f32_16x16x32_bf16 v[48:51], v[108:111], v[172:175], v[48:51]
	v_mfma_f32_16x16x32_bf16 v[44:47], v[128:131], v[172:175], v[44:47]
	v_mfma_f32_16x16x32_bf16 v[32:35], v[108:111], v[180:183], v[32:35]
	v_mfma_f32_16x16x32_bf16 v[28:31], v[128:131], v[180:183], v[28:31]
	v_mfma_f32_16x16x32_bf16 v[16:19], v[108:111], v[206:209], v[16:19]
	v_mfma_f32_16x16x32_bf16 v[12:15], v[128:131], v[206:209], v[12:15]
	v_mfma_f32_16x16x32_bf16 v[64:67], v[112:115], v[168:171], v[64:67]
	v_mfma_f32_16x16x32_bf16 v[60:63], v[136:139], v[168:171], v[60:63]
	v_mfma_f32_16x16x32_bf16 v[48:51], v[112:115], v[176:179], v[48:51]
	v_mfma_f32_16x16x32_bf16 v[44:47], v[136:139], v[176:179], v[44:47]
	v_mfma_f32_16x16x32_bf16 v[32:35], v[112:115], v[184:187], v[32:35]
	v_mfma_f32_16x16x32_bf16 v[28:31], v[136:139], v[184:187], v[28:31]
	v_mfma_f32_16x16x32_bf16 v[16:19], v[112:115], v[210:213], v[16:19]
	v_mfma_f32_16x16x32_bf16 v[12:15], v[136:139], v[210:213], v[12:15]
	v_mfma_f32_16x16x32_bf16 v[56:59], v[148:151], v[164:167], v[56:59]
	v_mfma_f32_16x16x32_bf16 v[52:55], v[156:159], v[164:167], v[52:55]
	v_mfma_f32_16x16x32_bf16 v[40:43], v[148:151], v[172:175], v[40:43]
	v_mfma_f32_16x16x32_bf16 v[36:39], v[156:159], v[172:175], v[36:39]
	v_mfma_f32_16x16x32_bf16 v[24:27], v[148:151], v[180:183], v[24:27]
	v_mfma_f32_16x16x32_bf16 v[20:23], v[156:159], v[180:183], v[20:23]
	v_mfma_f32_16x16x32_bf16 v[8:11], v[148:151], v[206:209], v[8:11]
	v_mfma_f32_16x16x32_bf16 v[4:7], v[156:159], v[206:209], v[4:7]
	v_mfma_f32_16x16x32_bf16 v[56:59], v[152:155], v[168:171], v[56:59]
	v_mfma_f32_16x16x32_bf16 v[52:55], v[160:163], v[168:171], v[52:55]
	v_mfma_f32_16x16x32_bf16 v[40:43], v[152:155], v[176:179], v[40:43]
	v_mfma_f32_16x16x32_bf16 v[36:39], v[160:163], v[176:179], v[36:39]
	v_mfma_f32_16x16x32_bf16 v[24:27], v[152:155], v[184:187], v[24:27]
	v_mfma_f32_16x16x32_bf16 v[20:23], v[160:163], v[184:187], v[20:23]
	v_mfma_f32_16x16x32_bf16 v[8:11], v[152:155], v[210:213], v[8:11]
	v_mfma_f32_16x16x32_bf16 v[4:7], v[160:163], v[210:213], v[4:7]
	s_barrier
	s_setprio 0
	s_add_i32 s48, 0, 0x18000
	s_add_i32 s49, 0, 0x1c000
	ds_read_b128 v[108:111], v251 offset:32768
	ds_read_b128 v[112:115], v251 offset:33792
	ds_read_b128 v[128:131], v251 offset:34816
	ds_read_b128 v[136:139], v251 offset:35840
	ds_read_b128 v[148:151], v251 offset:49152
	ds_read_b128 v[152:155], v251 offset:50176
	ds_read_b128 v[156:159], v251 offset:51200
	ds_read_b128 v[160:163], v251 offset:52224
	s_add_u32 s76, s76, 0x80000
	s_addc_u32 s77, s77, 0
	s_mov_b32 m0, s21
	v_lshl_add_u64 v[220:221], s[76:77], 0, v[192:193]
	ds_read_b128 v[164:167], v234 offset:32768
	ds_read_b128 v[168:171], v234 offset:33792
	ds_read_b128 v[172:175], v234 offset:34816
	ds_read_b128 v[176:179], v234 offset:35840
	ds_read_b128 v[180:183], v234 offset:36864
	ds_read_b128 v[184:187], v234 offset:37888
	ds_read_b128 v[206:209], v234 offset:38912
	ds_read_b128 v[210:213], v234 offset:39936
	global_load_lds_dwordx4 v[220:221], off
	v_lshl_add_u64 v[220:221], s[76:77], 0, v[190:191]
	s_mov_b32 m0, s23
	s_nop 0
	global_load_lds_dwordx4 v[220:221], off
	s_waitcnt vmcnt(8) lgkmcnt(0)
	s_setprio 1
	s_barrier
	v_mfma_f32_16x16x32_bf16 v[144:147], v[108:111], v[164:167], v[144:147]
	v_mfma_f32_16x16x32_bf16 v[140:143], v[128:131], v[164:167], v[140:143]
	v_mfma_f32_16x16x32_bf16 v[120:123], v[108:111], v[172:175], v[120:123]
	v_mfma_f32_16x16x32_bf16 v[116:119], v[128:131], v[172:175], v[116:119]
	v_mfma_f32_16x16x32_bf16 v[96:99], v[108:111], v[180:183], v[96:99]
	v_mfma_f32_16x16x32_bf16 v[92:95], v[128:131], v[180:183], v[92:95]
	v_mfma_f32_16x16x32_bf16 v[80:83], v[108:111], v[206:209], v[80:83]
	v_mfma_f32_16x16x32_bf16 v[76:79], v[128:131], v[206:209], v[76:79]
	v_mfma_f32_16x16x32_bf16 v[144:147], v[112:115], v[168:171], v[144:147]
	v_mfma_f32_16x16x32_bf16 v[140:143], v[136:139], v[168:171], v[140:143]
	v_mfma_f32_16x16x32_bf16 v[120:123], v[112:115], v[176:179], v[120:123]
	v_mfma_f32_16x16x32_bf16 v[116:119], v[136:139], v[176:179], v[116:119]
	v_mfma_f32_16x16x32_bf16 v[96:99], v[112:115], v[184:187], v[96:99]
	v_mfma_f32_16x16x32_bf16 v[92:95], v[136:139], v[184:187], v[92:95]
	v_mfma_f32_16x16x32_bf16 v[80:83], v[112:115], v[210:213], v[80:83]
	v_mfma_f32_16x16x32_bf16 v[76:79], v[136:139], v[210:213], v[76:79]
	v_mfma_f32_16x16x32_bf16 v[132:135], v[148:151], v[164:167], v[132:135]
	v_mfma_f32_16x16x32_bf16 v[124:127], v[156:159], v[164:167], v[124:127]
	v_mfma_f32_16x16x32_bf16 v[104:107], v[148:151], v[172:175], v[104:107]
	v_mfma_f32_16x16x32_bf16 v[100:103], v[156:159], v[172:175], v[100:103]
	v_mfma_f32_16x16x32_bf16 v[88:91], v[148:151], v[180:183], v[88:91]
	v_mfma_f32_16x16x32_bf16 v[84:87], v[156:159], v[180:183], v[84:87]
	v_mfma_f32_16x16x32_bf16 v[72:75], v[148:151], v[206:209], v[72:75]
	v_mfma_f32_16x16x32_bf16 v[68:71], v[156:159], v[206:209], v[68:71]
	v_mfma_f32_16x16x32_bf16 v[132:135], v[152:155], v[168:171], v[132:135]
	v_mfma_f32_16x16x32_bf16 v[124:127], v[160:163], v[168:171], v[124:127]
	v_mfma_f32_16x16x32_bf16 v[104:107], v[152:155], v[176:179], v[104:107]
	v_mfma_f32_16x16x32_bf16 v[100:103], v[160:163], v[176:179], v[100:103]
	v_mfma_f32_16x16x32_bf16 v[88:91], v[152:155], v[184:187], v[88:91]
	v_mfma_f32_16x16x32_bf16 v[84:87], v[160:163], v[184:187], v[84:87]
	v_mfma_f32_16x16x32_bf16 v[72:75], v[152:155], v[210:213], v[72:75]
	v_mfma_f32_16x16x32_bf16 v[68:71], v[160:163], v[210:213], v[68:71]
	s_barrier
	s_setprio 0
	s_add_i32 s48, s48, s5
	v_lshl_add_u64 v[198:199], v[198:199], 0, s[66:67]
	s_mov_b32 m0, s48
	ds_read_b128 v[164:167], v234 offset:49152
	ds_read_b128 v[168:171], v234 offset:50176
	ds_read_b128 v[172:175], v234 offset:51200
	ds_read_b128 v[176:179], v234 offset:52224
	ds_read_b128 v[180:183], v234 offset:53248
	ds_read_b128 v[184:187], v234 offset:54272
	ds_read_b128 v[206:209], v234 offset:55296
	ds_read_b128 v[210:213], v234 offset:56320
	global_load_lds_dwordx4 v[198:199], off
	s_add_i32 m0, s48, 0x2000
	s_add_u32 s70, s70, 0x80080
	v_lshl_add_u64 v[198:199], v[214:215], 0, s[66:67]
	s_addc_u32 s71, s71, 0
	s_add_i32 s48, s49, s5
	global_load_lds_dwordx4 v[198:199], off
	v_lshl_add_u64 v[198:199], s[70:71], 0, v[200:201]
	s_mov_b32 m0, s48
	s_nop 0
	global_load_lds_dwordx4 v[198:199], off
	v_lshl_add_u64 v[198:199], s[70:71], 0, v[188:189]
	s_add_i32 m0, s48, 0x2000
	s_nop 0
	global_load_lds_dwordx4 v[198:199], off
	v_lshl_add_u64 v[198:199], v[216:217], 0, s[66:67]
	s_mov_b32 m0, s54
	s_nop 0
	global_load_lds_dwordx4 v[198:199], off
	v_lshl_add_u64 v[198:199], v[218:219], 0, s[66:67]
	s_mov_b32 m0, s55
	s_nop 0
	global_load_lds_dwordx4 v[198:199], off
	s_waitcnt vmcnt(8) lgkmcnt(0)
	s_setprio 1
	s_barrier
	v_mfma_f32_16x16x32_bf16 v[64:67], v[108:111], v[164:167], v[64:67]
	v_mfma_f32_16x16x32_bf16 v[60:63], v[128:131], v[164:167], v[60:63]
	v_mfma_f32_16x16x32_bf16 v[48:51], v[108:111], v[172:175], v[48:51]
	v_mfma_f32_16x16x32_bf16 v[44:47], v[128:131], v[172:175], v[44:47]
	v_mfma_f32_16x16x32_bf16 v[32:35], v[108:111], v[180:183], v[32:35]
	v_mfma_f32_16x16x32_bf16 v[28:31], v[128:131], v[180:183], v[28:31]
	v_mfma_f32_16x16x32_bf16 v[16:19], v[108:111], v[206:209], v[16:19]
	v_mfma_f32_16x16x32_bf16 v[12:15], v[128:131], v[206:209], v[12:15]
	v_mfma_f32_16x16x32_bf16 v[64:67], v[112:115], v[168:171], v[64:67]
	v_mfma_f32_16x16x32_bf16 v[60:63], v[136:139], v[168:171], v[60:63]
	v_mfma_f32_16x16x32_bf16 v[48:51], v[112:115], v[176:179], v[48:51]
	v_mfma_f32_16x16x32_bf16 v[44:47], v[136:139], v[176:179], v[44:47]
	v_mfma_f32_16x16x32_bf16 v[32:35], v[112:115], v[184:187], v[32:35]
	v_mfma_f32_16x16x32_bf16 v[28:31], v[136:139], v[184:187], v[28:31]
	v_mfma_f32_16x16x32_bf16 v[16:19], v[112:115], v[210:213], v[16:19]
	v_mfma_f32_16x16x32_bf16 v[12:15], v[136:139], v[210:213], v[12:15]
	v_mfma_f32_16x16x32_bf16 v[56:59], v[148:151], v[164:167], v[56:59]
	v_mfma_f32_16x16x32_bf16 v[52:55], v[156:159], v[164:167], v[52:55]
	v_mfma_f32_16x16x32_bf16 v[40:43], v[148:151], v[172:175], v[40:43]
	v_mfma_f32_16x16x32_bf16 v[36:39], v[156:159], v[172:175], v[36:39]
	v_mfma_f32_16x16x32_bf16 v[24:27], v[148:151], v[180:183], v[24:27]
	v_mfma_f32_16x16x32_bf16 v[20:23], v[156:159], v[180:183], v[20:23]
	v_mfma_f32_16x16x32_bf16 v[8:11], v[148:151], v[206:209], v[8:11]
	v_mfma_f32_16x16x32_bf16 v[4:7], v[156:159], v[206:209], v[4:7]
	v_mfma_f32_16x16x32_bf16 v[56:59], v[152:155], v[168:171], v[56:59]
	v_mfma_f32_16x16x32_bf16 v[52:55], v[160:163], v[168:171], v[52:55]
	v_mfma_f32_16x16x32_bf16 v[40:43], v[152:155], v[176:179], v[40:43]
	v_mfma_f32_16x16x32_bf16 v[36:39], v[160:163], v[176:179], v[36:39]
	v_mfma_f32_16x16x32_bf16 v[24:27], v[152:155], v[184:187], v[24:27]
	v_mfma_f32_16x16x32_bf16 v[20:23], v[160:163], v[184:187], v[20:23]
	v_mfma_f32_16x16x32_bf16 v[8:11], v[152:155], v[210:213], v[8:11]
	v_mfma_f32_16x16x32_bf16 v[4:7], v[160:163], v[210:213], v[4:7]
	s_barrier
	s_setprio 0
	s_add_i32 s79, s79, 2
	s_add_u32 s75, s75, 0x100
	s_addc_u32 s78, s78, 0
	s_add_u32 s68, s68, 0x100
	s_addc_u32 s69, s69, 0
	s_cmp_gt_u32 s79, 29
	s_cbranch_scc0 .LBB0_998
	s_and_b64 vcc, exec, s[14:15]
	s_cbranch_vccz .LBB0_1001
	s_barrier

.LBB0_1086:
	s_add_u32 s10, s8, 0xfff80080
	s_addc_u32 s11, s9, -1
	s_add_i32 s48, 0, 0x10000
	s_cmp_eq_u32 s97, 28
	s_cselect_b32 s13, s69, s11
	s_cselect_b32 s12, s76, s10
	s_cselect_b32 s11, s77, s89
	s_cselect_b32 s10, s82, s83
	s_add_i32 vcc_lo, 0, 0x14000
	ds_read_b128 v[106:109], v251
	ds_read_b128 v[110:113], v251 offset:1024
	ds_read_b128 v[114:117], v251 offset:2048
	ds_read_b128 v[118:121], v251 offset:3072
	ds_read_b128 v[122:125], v251 offset:16384
	ds_read_b128 v[126:129], v251 offset:17408
	ds_read_b128 v[130:133], v251 offset:18432
	ds_read_b128 v[134:137], v251 offset:19456
	v_lshl_add_u64 v[100:101], s[8:9], 0, v[190:191]
	s_add_i32 m0, s1, 0xc000
	ds_read_b128 v[166:169], v222
	ds_read_b128 v[170:173], v222 offset:1024
	ds_read_b128 v[174:177], v222 offset:2048
	ds_read_b128 v[178:181], v222 offset:3072
	ds_read_b128 v[194:197], v222 offset:4096
	ds_read_b128 v[206:209], v222 offset:5120
	ds_read_b128 v[210:213], v222 offset:6144
	ds_read_b128 v[214:217], v222 offset:7168
	global_load_lds_dwordx4 v[100:101], off
	v_lshl_add_u64 v[100:101], s[8:9], 0, v[192:193]
	s_add_i32 m0, s1, 0xe000
	s_nop 0
	global_load_lds_dwordx4 v[100:101], off
	s_waitcnt vmcnt(8) lgkmcnt(0)
	s_setprio 1
	s_barrier
	v_mfma_f32_16x16x32_bf16 v[4:7], v[106:109], v[166:169], v[4:7]
	v_mfma_f32_16x16x32_bf16 v[72:75], v[114:117], v[166:169], v[72:75]
	v_mfma_f32_16x16x32_bf16 v[162:165], v[106:109], v[174:177], v[162:165]
	v_mfma_f32_16x16x32_bf16 v[60:63], v[114:117], v[174:177], v[60:63]
	v_mfma_f32_16x16x32_bf16 v[158:161], v[106:109], v[194:197], v[158:161]
	v_mfma_f32_16x16x32_bf16 v[56:59], v[114:117], v[194:197], v[56:59]
	v_mfma_f32_16x16x32_bf16 v[96:99], v[106:109], v[210:213], v[96:99]
	v_mfma_f32_16x16x32_bf16 v[76:79], v[114:117], v[210:213], v[76:79]
	v_mfma_f32_16x16x32_bf16 v[4:7], v[110:113], v[170:173], v[4:7]
	v_mfma_f32_16x16x32_bf16 v[72:75], v[118:121], v[170:173], v[72:75]
	v_mfma_f32_16x16x32_bf16 v[162:165], v[110:113], v[178:181], v[162:165]
	v_mfma_f32_16x16x32_bf16 v[60:63], v[118:121], v[178:181], v[60:63]
	v_mfma_f32_16x16x32_bf16 v[158:161], v[110:113], v[206:209], v[158:161]
	v_mfma_f32_16x16x32_bf16 v[56:59], v[118:121], v[206:209], v[56:59]
	v_mfma_f32_16x16x32_bf16 v[96:99], v[110:113], v[214:217], v[96:99]
	v_mfma_f32_16x16x32_bf16 v[76:79], v[118:121], v[214:217], v[76:79]
	v_mfma_f32_16x16x32_bf16 v[8:11], v[122:125], v[166:169], v[8:11]
	v_mfma_f32_16x16x32_bf16 v[64:67], v[130:133], v[166:169], v[64:67]
	v_mfma_f32_16x16x32_bf16 v[154:157], v[122:125], v[174:177], v[154:157]
	v_mfma_f32_16x16x32_bf16 v[52:55], v[130:133], v[174:177], v[52:55]
	v_mfma_f32_16x16x32_bf16 v[150:153], v[122:125], v[194:197], v[150:153]
	v_mfma_f32_16x16x32_bf16 v[48:51], v[130:133], v[194:197], v[48:51]
	v_mfma_f32_16x16x32_bf16 v[92:95], v[122:125], v[210:213], v[92:95]
	v_mfma_f32_16x16x32_bf16 v[68:71], v[130:133], v[210:213], v[68:71]
	v_mfma_f32_16x16x32_bf16 v[8:11], v[126:129], v[170:173], v[8:11]
	v_mfma_f32_16x16x32_bf16 v[64:67], v[134:137], v[170:173], v[64:67]
	v_mfma_f32_16x16x32_bf16 v[154:157], v[126:129], v[178:181], v[154:157]
	v_mfma_f32_16x16x32_bf16 v[52:55], v[134:137], v[178:181], v[52:55]
	v_mfma_f32_16x16x32_bf16 v[150:153], v[126:129], v[206:209], v[150:153]
	v_mfma_f32_16x16x32_bf16 v[48:51], v[134:137], v[206:209], v[48:51]
	v_mfma_f32_16x16x32_bf16 v[92:95], v[126:129], v[214:217], v[92:95]
	v_mfma_f32_16x16x32_bf16 v[68:71], v[134:137], v[214:217], v[68:71]
	s_barrier
	s_setprio 0
	s_add_i32 s48, s48, s0
	v_lshl_add_u64 v[198:199], s[10:11], 0, v[186:187]
	s_mov_b32 m0, s48
	ds_read_b128 v[166:169], v222 offset:16384
	ds_read_b128 v[170:173], v222 offset:17408
	ds_read_b128 v[174:177], v222 offset:18432
	ds_read_b128 v[178:181], v222 offset:19456
	ds_read_b128 v[194:197], v222 offset:20480
	ds_read_b128 v[206:209], v222 offset:21504
	ds_read_b128 v[210:213], v222 offset:22528
	ds_read_b128 v[214:217], v222 offset:23552
	global_load_lds_dwordx4 v[198:199], off
	s_add_i32 m0, s48, 0x2000
	s_add_u32 s48, s10, 0x80000
	v_lshl_add_u64 v[218:219], s[10:11], 0, v[182:183]
	s_addc_u32 s49, s11, 0
	s_add_i32 vcc_lo, vcc_lo, s0
	global_load_lds_dwordx4 v[218:219], off
	v_lshl_add_u64 v[100:101], s[48:49], 0, v[186:187]
	s_mov_b32 m0, vcc_lo
	v_lshl_add_u64 v[224:225], s[12:13], 0, v[188:189]
	global_load_lds_dwordx4 v[100:101], off
	v_lshl_add_u64 v[100:101], s[48:49], 0, v[182:183]
	s_add_i32 m0, vcc_lo, 0x2000
	v_lshl_add_u64 v[232:233], s[12:13], 0, v[184:185]
	global_load_lds_dwordx4 v[100:101], off
	s_mov_b32 m0, s1
	s_nop 0
	global_load_lds_dwordx4 v[224:225], off
	s_mov_b32 m0, s4
	s_nop 0
	global_load_lds_dwordx4 v[232:233], off
	s_waitcnt vmcnt(8) lgkmcnt(0)
	s_setprio 1
	s_barrier
	v_mfma_f32_16x16x32_bf16 v[146:149], v[106:109], v[166:169], v[146:149]
	v_mfma_f32_16x16x32_bf16 v[44:47], v[114:117], v[166:169], v[44:47]
	v_mfma_f32_16x16x32_bf16 v[142:145], v[106:109], v[174:177], v[142:145]
	v_mfma_f32_16x16x32_bf16 v[40:43], v[114:117], v[174:177], v[40:43]
	v_mfma_f32_16x16x32_bf16 v[138:141], v[106:109], v[194:197], v[138:141]
	v_mfma_f32_16x16x32_bf16 v[36:39], v[114:117], v[194:197], v[36:39]
	v_mfma_f32_16x16x32_bf16 v[80:83], v[106:109], v[210:213], v[80:83]
	v_mfma_f32_16x16x32_bf16 v[20:23], v[114:117], v[210:213], v[20:23]
	v_mfma_f32_16x16x32_bf16 v[146:149], v[110:113], v[170:173], v[146:149]
	v_mfma_f32_16x16x32_bf16 v[44:47], v[118:121], v[170:173], v[44:47]
	v_mfma_f32_16x16x32_bf16 v[142:145], v[110:113], v[178:181], v[142:145]
	v_mfma_f32_16x16x32_bf16 v[40:43], v[118:121], v[178:181], v[40:43]
	v_mfma_f32_16x16x32_bf16 v[138:141], v[110:113], v[206:209], v[138:141]
	v_mfma_f32_16x16x32_bf16 v[36:39], v[118:121], v[206:209], v[36:39]
	v_mfma_f32_16x16x32_bf16 v[80:83], v[110:113], v[214:217], v[80:83]
	v_mfma_f32_16x16x32_bf16 v[20:23], v[118:121], v[214:217], v[20:23]
	v_mfma_f32_16x16x32_bf16 v[100:103], v[122:125], v[166:169], v[102:105]
	v_mfma_f32_16x16x32_bf16 v[32:35], v[130:133], v[166:169], v[32:35]
	v_mfma_f32_16x16x32_bf16 v[88:91], v[122:125], v[174:177], v[88:91]
	v_mfma_f32_16x16x32_bf16 v[28:31], v[130:133], v[174:177], v[28:31]
	v_mfma_f32_16x16x32_bf16 v[84:87], v[122:125], v[194:197], v[84:87]
	v_mfma_f32_16x16x32_bf16 v[24:27], v[130:133], v[194:197], v[24:27]
	v_mfma_f32_16x16x32_bf16 v[16:19], v[122:125], v[210:213], v[16:19]
	v_mfma_f32_16x16x32_bf16 v[12:15], v[130:133], v[210:213], v[12:15]
	v_mfma_f32_16x16x32_bf16 v[100:103], v[126:129], v[170:173], v[100:103]
	v_mfma_f32_16x16x32_bf16 v[32:35], v[134:137], v[170:173], v[32:35]
	v_mfma_f32_16x16x32_bf16 v[88:91], v[126:129], v[178:181], v[88:91]
	v_mfma_f32_16x16x32_bf16 v[28:31], v[134:137], v[178:181], v[28:31]
	v_mfma_f32_16x16x32_bf16 v[84:87], v[126:129], v[206:209], v[84:87]
	v_mfma_f32_16x16x32_bf16 v[24:27], v[134:137], v[206:209], v[24:27]
	v_mfma_f32_16x16x32_bf16 v[16:19], v[126:129], v[214:217], v[16:19]
	v_mfma_f32_16x16x32_bf16 v[12:15], v[134:137], v[214:217], v[12:15]
	s_barrier
	s_setprio 0
	s_add_i32 s48, 0, 0x18000
	s_add_i32 s49, 0, 0x1c000
	ds_read_b128 v[104:107], v251 offset:32768
	ds_read_b128 v[108:111], v251 offset:33792
	ds_read_b128 v[112:115], v251 offset:34816
	ds_read_b128 v[116:119], v251 offset:35840
	ds_read_b128 v[120:123], v251 offset:49152
	ds_read_b128 v[124:127], v251 offset:50176
	ds_read_b128 v[128:131], v251 offset:51200
	ds_read_b128 v[132:135], v251 offset:52224
	s_add_u32 s12, s12, 0x80000
	s_addc_u32 s13, s13, 0
	s_mov_b32 m0, s5
	v_lshl_add_u64 v[136:137], s[12:13], 0, v[188:189]
	ds_read_b128 v[166:169], v222 offset:32768
	ds_read_b128 v[170:173], v222 offset:33792
	ds_read_b128 v[174:177], v222 offset:34816
	ds_read_b128 v[178:181], v222 offset:35840
	ds_read_b128 v[194:197], v222 offset:36864
	ds_read_b128 v[206:209], v222 offset:37888
	ds_read_b128 v[210:213], v222 offset:38912
	ds_read_b128 v[214:217], v222 offset:39936
	global_load_lds_dwordx4 v[136:137], off
	v_lshl_add_u64 v[136:137], s[12:13], 0, v[184:185]
	s_mov_b32 m0, s44
	s_nop 0
	global_load_lds_dwordx4 v[136:137], off
	s_waitcnt vmcnt(8) lgkmcnt(0)
	s_setprio 1
	s_barrier
	v_mfma_f32_16x16x32_bf16 v[4:7], v[104:107], v[166:169], v[4:7]
	v_mfma_f32_16x16x32_bf16 v[72:75], v[112:115], v[166:169], v[72:75]
	v_mfma_f32_16x16x32_bf16 v[162:165], v[104:107], v[174:177], v[162:165]
	v_mfma_f32_16x16x32_bf16 v[60:63], v[112:115], v[174:177], v[60:63]
	v_mfma_f32_16x16x32_bf16 v[158:161], v[104:107], v[194:197], v[158:161]
	v_mfma_f32_16x16x32_bf16 v[56:59], v[112:115], v[194:197], v[56:59]
	v_mfma_f32_16x16x32_bf16 v[96:99], v[104:107], v[210:213], v[96:99]
	v_mfma_f32_16x16x32_bf16 v[76:79], v[112:115], v[210:213], v[76:79]
	v_mfma_f32_16x16x32_bf16 v[4:7], v[108:111], v[170:173], v[4:7]
	v_mfma_f32_16x16x32_bf16 v[72:75], v[116:119], v[170:173], v[72:75]
	v_mfma_f32_16x16x32_bf16 v[162:165], v[108:111], v[178:181], v[162:165]
	v_mfma_f32_16x16x32_bf16 v[60:63], v[116:119], v[178:181], v[60:63]
	v_mfma_f32_16x16x32_bf16 v[158:161], v[108:111], v[206:209], v[158:161]
	v_mfma_f32_16x16x32_bf16 v[56:59], v[116:119], v[206:209], v[56:59]
	v_mfma_f32_16x16x32_bf16 v[96:99], v[108:111], v[214:217], v[96:99]
	v_mfma_f32_16x16x32_bf16 v[76:79], v[116:119], v[214:217], v[76:79]
	v_mfma_f32_16x16x32_bf16 v[8:11], v[120:123], v[166:169], v[8:11]
	v_mfma_f32_16x16x32_bf16 v[64:67], v[128:131], v[166:169], v[64:67]
	v_mfma_f32_16x16x32_bf16 v[154:157], v[120:123], v[174:177], v[154:157]
	v_mfma_f32_16x16x32_bf16 v[52:55], v[128:131], v[174:177], v[52:55]
	v_mfma_f32_16x16x32_bf16 v[150:153], v[120:123], v[194:197], v[150:153]
	v_mfma_f32_16x16x32_bf16 v[48:51], v[128:131], v[194:197], v[48:51]
	v_mfma_f32_16x16x32_bf16 v[92:95], v[120:123], v[210:213], v[92:95]
	v_mfma_f32_16x16x32_bf16 v[68:71], v[128:131], v[210:213], v[68:71]
	v_mfma_f32_16x16x32_bf16 v[8:11], v[124:127], v[170:173], v[8:11]
	v_mfma_f32_16x16x32_bf16 v[64:67], v[132:135], v[170:173], v[64:67]
	v_mfma_f32_16x16x32_bf16 v[154:157], v[124:127], v[178:181], v[154:157]
	v_mfma_f32_16x16x32_bf16 v[52:55], v[132:135], v[178:181], v[52:55]
	v_mfma_f32_16x16x32_bf16 v[150:153], v[124:127], v[206:209], v[150:153]
	v_mfma_f32_16x16x32_bf16 v[48:51], v[132:135], v[206:209], v[48:51]
	v_mfma_f32_16x16x32_bf16 v[92:95], v[124:127], v[214:217], v[92:95]
	v_mfma_f32_16x16x32_bf16 v[68:71], v[132:135], v[214:217], v[68:71]
	s_barrier
	s_setprio 0
	s_add_i32 s12, s48, s0
	v_lshl_add_u64 v[136:137], v[198:199], 0, s[66:67]
	s_mov_b32 m0, s12
	ds_read_b128 v[166:169], v222 offset:49152
	ds_read_b128 v[170:173], v222 offset:50176
	ds_read_b128 v[174:177], v222 offset:51200
	ds_read_b128 v[178:181], v222 offset:52224
	ds_read_b128 v[194:197], v222 offset:53248
	ds_read_b128 v[206:209], v222 offset:54272
	ds_read_b128 v[210:213], v222 offset:55296
	ds_read_b128 v[214:217], v222 offset:56320
	global_load_lds_dwordx4 v[136:137], off
	s_add_i32 m0, s12, 0x2000
	s_add_u32 s10, s10, 0x80080
	v_lshl_add_u64 v[136:137], v[218:219], 0, s[66:67]
	s_addc_u32 s11, s11, 0
	s_add_i32 s12, s49, s0
	global_load_lds_dwordx4 v[136:137], off
	v_lshl_add_u64 v[136:137], s[10:11], 0, v[186:187]
	s_mov_b32 m0, s12
	s_nop 0
	global_load_lds_dwordx4 v[136:137], off
	v_lshl_add_u64 v[136:137], s[10:11], 0, v[182:183]
	s_add_i32 m0, s12, 0x2000
	s_nop 0
	global_load_lds_dwordx4 v[136:137], off
	v_lshl_add_u64 v[136:137], v[224:225], 0, s[66:67]
	s_mov_b32 m0, s42
	s_nop 0
	global_load_lds_dwordx4 v[136:137], off
	v_lshl_add_u64 v[136:137], v[232:233], 0, s[66:67]
	s_mov_b32 m0, s55
	s_nop 0
	global_load_lds_dwordx4 v[136:137], off
	s_waitcnt vmcnt(8) lgkmcnt(0)
	s_setprio 1
	s_barrier
	v_mfma_f32_16x16x32_bf16 v[146:149], v[104:107], v[166:169], v[146:149]
	v_mfma_f32_16x16x32_bf16 v[44:47], v[112:115], v[166:169], v[44:47]
	v_mfma_f32_16x16x32_bf16 v[142:145], v[104:107], v[174:177], v[142:145]
	v_mfma_f32_16x16x32_bf16 v[40:43], v[112:115], v[174:177], v[40:43]
	v_mfma_f32_16x16x32_bf16 v[136:139], v[104:107], v[194:197], v[138:141]
	v_mfma_f32_16x16x32_bf16 v[36:39], v[112:115], v[194:197], v[36:39]
	v_mfma_f32_16x16x32_bf16 v[80:83], v[104:107], v[210:213], v[80:83]
	v_mfma_f32_16x16x32_bf16 v[20:23], v[112:115], v[210:213], v[20:23]
	v_mfma_f32_16x16x32_bf16 v[146:149], v[108:111], v[170:173], v[146:149]
	v_mfma_f32_16x16x32_bf16 v[44:47], v[116:119], v[170:173], v[44:47]
	v_mfma_f32_16x16x32_bf16 v[142:145], v[108:111], v[178:181], v[142:145]
	v_mfma_f32_16x16x32_bf16 v[40:43], v[116:119], v[178:181], v[40:43]
	v_mfma_f32_16x16x32_bf16 v[138:141], v[108:111], v[206:209], v[136:139]
	v_mfma_f32_16x16x32_bf16 v[36:39], v[116:119], v[206:209], v[36:39]
	v_mfma_f32_16x16x32_bf16 v[80:83], v[108:111], v[214:217], v[80:83]
	v_mfma_f32_16x16x32_bf16 v[20:23], v[116:119], v[214:217], v[20:23]
	v_mfma_f32_16x16x32_bf16 v[100:103], v[120:123], v[166:169], v[100:103]
	v_mfma_f32_16x16x32_bf16 v[32:35], v[128:131], v[166:169], v[32:35]
	v_mfma_f32_16x16x32_bf16 v[88:91], v[120:123], v[174:177], v[88:91]
	v_mfma_f32_16x16x32_bf16 v[28:31], v[128:131], v[174:177], v[28:31]
	v_mfma_f32_16x16x32_bf16 v[84:87], v[120:123], v[194:197], v[84:87]
	v_mfma_f32_16x16x32_bf16 v[24:27], v[128:131], v[194:197], v[24:27]
	v_mfma_f32_16x16x32_bf16 v[16:19], v[120:123], v[210:213], v[16:19]
	v_mfma_f32_16x16x32_bf16 v[12:15], v[128:131], v[210:213], v[12:15]
	v_mfma_f32_16x16x32_bf16 v[102:105], v[124:127], v[170:173], v[100:103]
	v_mfma_f32_16x16x32_bf16 v[32:35], v[132:135], v[170:173], v[32:35]
	v_mfma_f32_16x16x32_bf16 v[88:91], v[124:127], v[178:181], v[88:91]
	v_mfma_f32_16x16x32_bf16 v[28:31], v[132:135], v[178:181], v[28:31]
	v_mfma_f32_16x16x32_bf16 v[84:87], v[124:127], v[206:209], v[84:87]
	v_mfma_f32_16x16x32_bf16 v[24:27], v[132:135], v[206:209], v[24:27]
	v_mfma_f32_16x16x32_bf16 v[16:19], v[124:127], v[214:217], v[16:19]
	v_mfma_f32_16x16x32_bf16 v[12:15], v[132:135], v[214:217], v[12:15]
	s_barrier
	s_setprio 0
	s_add_i32 s97, s97, 2
	s_add_u32 s8, s8, 0x100
	s_addc_u32 s9, s9, 0
	s_add_u32 s83, s83, 0x100
	s_addc_u32 s89, s89, 0
	s_cmp_gt_u32 s97, 29
	s_cbranch_scc0 .LBB0_1086
	s_and_b64 vcc, exec, s[70:71]
	s_cbranch_vccz .LBB0_1089
	s_barrier

.LBB0_1212:
	s_add_u32 s62, s60, 0x100
	s_addc_u32 s63, s61, 0
	s_add_i32 s48, 0, 0x10000
	s_cmpk_eq_i32 s79, 0x54
	s_cselect_b32 s71, s9, s63
	s_cselect_b32 s70, s8, s62
	s_cselect_b32 s69, s25, s78
	s_cselect_b32 s68, s24, s77
	s_add_i32 s81, 0, 0x14000
	ds_read_b128 v[108:111], v251
	ds_read_b128 v[112:115], v251 offset:1024
	ds_read_b128 v[128:131], v251 offset:2048
	ds_read_b128 v[136:139], v251 offset:3072
	ds_read_b128 v[148:151], v251 offset:16384
	ds_read_b128 v[152:155], v251 offset:17408
	ds_read_b128 v[156:159], v251 offset:18432
	ds_read_b128 v[160:163], v251 offset:19456
	v_lshl_add_u64 v[198:199], s[60:61], 0, v[196:197]
	s_add_i32 m0, s5, 0xc000
	ds_read_b128 v[164:167], v234
	ds_read_b128 v[168:171], v234 offset:1024
	ds_read_b128 v[172:175], v234 offset:2048
	ds_read_b128 v[176:179], v234 offset:3072
	ds_read_b128 v[180:183], v234 offset:4096
	ds_read_b128 v[184:187], v234 offset:5120
	ds_read_b128 v[206:209], v234 offset:6144
	ds_read_b128 v[210:213], v234 offset:7168
	global_load_lds_dwordx4 v[198:199], off
	v_lshl_add_u64 v[198:199], s[60:61], 0, v[194:195]
	s_add_i32 m0, s5, 0xe000
	s_nop 0
	global_load_lds_dwordx4 v[198:199], off
	s_waitcnt vmcnt(8) lgkmcnt(0)
	s_setprio 1
	s_barrier
	v_mfma_f32_16x16x32_bf16 v[144:147], v[108:111], v[164:167], v[144:147]
	v_mfma_f32_16x16x32_bf16 v[140:143], v[128:131], v[164:167], v[140:143]
	v_mfma_f32_16x16x32_bf16 v[120:123], v[108:111], v[172:175], v[120:123]
	v_mfma_f32_16x16x32_bf16 v[116:119], v[128:131], v[172:175], v[116:119]
	v_mfma_f32_16x16x32_bf16 v[96:99], v[108:111], v[180:183], v[96:99]
	v_mfma_f32_16x16x32_bf16 v[92:95], v[128:131], v[180:183], v[92:95]
	v_mfma_f32_16x16x32_bf16 v[80:83], v[108:111], v[206:209], v[80:83]
	v_mfma_f32_16x16x32_bf16 v[76:79], v[128:131], v[206:209], v[76:79]
	v_mfma_f32_16x16x32_bf16 v[144:147], v[112:115], v[168:171], v[144:147]
	v_mfma_f32_16x16x32_bf16 v[140:143], v[136:139], v[168:171], v[140:143]
	v_mfma_f32_16x16x32_bf16 v[120:123], v[112:115], v[176:179], v[120:123]
	v_mfma_f32_16x16x32_bf16 v[116:119], v[136:139], v[176:179], v[116:119]
	v_mfma_f32_16x16x32_bf16 v[96:99], v[112:115], v[184:187], v[96:99]
	v_mfma_f32_16x16x32_bf16 v[92:95], v[136:139], v[184:187], v[92:95]
	v_mfma_f32_16x16x32_bf16 v[80:83], v[112:115], v[210:213], v[80:83]
	v_mfma_f32_16x16x32_bf16 v[76:79], v[136:139], v[210:213], v[76:79]
	v_mfma_f32_16x16x32_bf16 v[132:135], v[148:151], v[164:167], v[132:135]
	v_mfma_f32_16x16x32_bf16 v[124:127], v[156:159], v[164:167], v[124:127]
	v_mfma_f32_16x16x32_bf16 v[104:107], v[148:151], v[172:175], v[104:107]
	v_mfma_f32_16x16x32_bf16 v[100:103], v[156:159], v[172:175], v[100:103]
	v_mfma_f32_16x16x32_bf16 v[88:91], v[148:151], v[180:183], v[88:91]
	v_mfma_f32_16x16x32_bf16 v[84:87], v[156:159], v[180:183], v[84:87]
	v_mfma_f32_16x16x32_bf16 v[72:75], v[148:151], v[206:209], v[72:75]
	v_mfma_f32_16x16x32_bf16 v[68:71], v[156:159], v[206:209], v[68:71]
	v_mfma_f32_16x16x32_bf16 v[132:135], v[152:155], v[168:171], v[132:135]
	v_mfma_f32_16x16x32_bf16 v[124:127], v[160:163], v[168:171], v[124:127]
	v_mfma_f32_16x16x32_bf16 v[104:107], v[152:155], v[176:179], v[104:107]
	v_mfma_f32_16x16x32_bf16 v[100:103], v[160:163], v[176:179], v[100:103]
	v_mfma_f32_16x16x32_bf16 v[88:91], v[152:155], v[184:187], v[88:91]
	v_mfma_f32_16x16x32_bf16 v[84:87], v[160:163], v[184:187], v[84:87]
	v_mfma_f32_16x16x32_bf16 v[72:75], v[152:155], v[210:213], v[72:75]
	v_mfma_f32_16x16x32_bf16 v[68:71], v[160:163], v[210:213], v[68:71]
	s_barrier
	s_setprio 0
	s_add_i32 s48, s48, s4
	v_lshl_add_u64 v[198:199], s[68:69], 0, v[200:201]
	s_mov_b32 m0, s48
	ds_read_b128 v[164:167], v234 offset:16384
	ds_read_b128 v[168:171], v234 offset:17408
	ds_read_b128 v[172:175], v234 offset:18432
	ds_read_b128 v[176:179], v234 offset:19456
	ds_read_b128 v[180:183], v234 offset:20480
	ds_read_b128 v[184:187], v234 offset:21504
	ds_read_b128 v[206:209], v234 offset:22528
	ds_read_b128 v[210:213], v234 offset:23552
	global_load_lds_dwordx4 v[198:199], off
	s_add_i32 m0, s48, 0x2000
	s_add_u32 s48, s68, 0x160000
	v_lshl_add_u64 v[214:215], s[68:69], 0, v[188:189]
	s_addc_u32 s49, s69, 0
	s_add_i32 s60, s81, s4
	global_load_lds_dwordx4 v[214:215], off
	v_lshl_add_u64 v[216:217], s[48:49], 0, v[200:201]
	s_mov_b32 m0, s60
	v_lshl_add_u64 v[218:219], s[70:71], 0, v[190:191]
	global_load_lds_dwordx4 v[216:217], off
	v_lshl_add_u64 v[216:217], s[48:49], 0, v[188:189]
	s_add_i32 m0, s60, 0x2000
	s_nop 0
	global_load_lds_dwordx4 v[216:217], off
	v_lshl_add_u64 v[216:217], s[70:71], 0, v[192:193]
	s_mov_b32 m0, s5
	s_nop 0
	global_load_lds_dwordx4 v[216:217], off
	s_mov_b32 m0, s20
	s_nop 0
	global_load_lds_dwordx4 v[218:219], off
	s_waitcnt vmcnt(8) lgkmcnt(0)
	s_setprio 1
	s_barrier
	v_mfma_f32_16x16x32_bf16 v[64:67], v[108:111], v[164:167], v[64:67]
	v_mfma_f32_16x16x32_bf16 v[60:63], v[128:131], v[164:167], v[60:63]
	v_mfma_f32_16x16x32_bf16 v[48:51], v[108:111], v[172:175], v[48:51]
	v_mfma_f32_16x16x32_bf16 v[44:47], v[128:131], v[172:175], v[44:47]
	v_mfma_f32_16x16x32_bf16 v[32:35], v[108:111], v[180:183], v[32:35]
	v_mfma_f32_16x16x32_bf16 v[28:31], v[128:131], v[180:183], v[28:31]
	v_mfma_f32_16x16x32_bf16 v[16:19], v[108:111], v[206:209], v[16:19]
	v_mfma_f32_16x16x32_bf16 v[12:15], v[128:131], v[206:209], v[12:15]
	v_mfma_f32_16x16x32_bf16 v[64:67], v[112:115], v[168:171], v[64:67]
	v_mfma_f32_16x16x32_bf16 v[60:63], v[136:139], v[168:171], v[60:63]
	v_mfma_f32_16x16x32_bf16 v[48:51], v[112:115], v[176:179], v[48:51]
	v_mfma_f32_16x16x32_bf16 v[44:47], v[136:139], v[176:179], v[44:47]
	v_mfma_f32_16x16x32_bf16 v[32:35], v[112:115], v[184:187], v[32:35]
	v_mfma_f32_16x16x32_bf16 v[28:31], v[136:139], v[184:187], v[28:31]
	v_mfma_f32_16x16x32_bf16 v[16:19], v[112:115], v[210:213], v[16:19]
	v_mfma_f32_16x16x32_bf16 v[12:15], v[136:139], v[210:213], v[12:15]
	v_mfma_f32_16x16x32_bf16 v[56:59], v[148:151], v[164:167], v[56:59]
	v_mfma_f32_16x16x32_bf16 v[52:55], v[156:159], v[164:167], v[52:55]
	v_mfma_f32_16x16x32_bf16 v[40:43], v[148:151], v[172:175], v[40:43]
	v_mfma_f32_16x16x32_bf16 v[36:39], v[156:159], v[172:175], v[36:39]
	v_mfma_f32_16x16x32_bf16 v[24:27], v[148:151], v[180:183], v[24:27]
	v_mfma_f32_16x16x32_bf16 v[20:23], v[156:159], v[180:183], v[20:23]
	v_mfma_f32_16x16x32_bf16 v[8:11], v[148:151], v[206:209], v[8:11]
	v_mfma_f32_16x16x32_bf16 v[4:7], v[156:159], v[206:209], v[4:7]
	v_mfma_f32_16x16x32_bf16 v[56:59], v[152:155], v[168:171], v[56:59]
	v_mfma_f32_16x16x32_bf16 v[52:55], v[160:163], v[168:171], v[52:55]
	v_mfma_f32_16x16x32_bf16 v[40:43], v[152:155], v[176:179], v[40:43]
	v_mfma_f32_16x16x32_bf16 v[36:39], v[160:163], v[176:179], v[36:39]
	v_mfma_f32_16x16x32_bf16 v[24:27], v[152:155], v[184:187], v[24:27]
	v_mfma_f32_16x16x32_bf16 v[20:23], v[160:163], v[184:187], v[20:23]
	v_mfma_f32_16x16x32_bf16 v[8:11], v[152:155], v[210:213], v[8:11]
	v_mfma_f32_16x16x32_bf16 v[4:7], v[160:163], v[210:213], v[4:7]
	s_barrier
	s_setprio 0
	s_add_i32 s60, 0, 0x18000
	s_add_i32 s61, 0, 0x1c000
	ds_read_b128 v[108:111], v251 offset:32768
	ds_read_b128 v[112:115], v251 offset:33792
	ds_read_b128 v[128:131], v251 offset:34816
	ds_read_b128 v[136:139], v251 offset:35840
	ds_read_b128 v[148:151], v251 offset:49152
	ds_read_b128 v[152:155], v251 offset:50176
	ds_read_b128 v[156:159], v251 offset:51200
	ds_read_b128 v[160:163], v251 offset:52224
	s_add_u32 s48, s70, 0x160000
	s_addc_u32 s49, s71, 0
	s_mov_b32 m0, s21
	v_lshl_add_u64 v[220:221], s[48:49], 0, v[192:193]
	ds_read_b128 v[164:167], v234 offset:32768
	ds_read_b128 v[168:171], v234 offset:33792
	ds_read_b128 v[172:175], v234 offset:34816
	ds_read_b128 v[176:179], v234 offset:35840
	ds_read_b128 v[180:183], v234 offset:36864
	ds_read_b128 v[184:187], v234 offset:37888
	ds_read_b128 v[206:209], v234 offset:38912
	ds_read_b128 v[210:213], v234 offset:39936
	global_load_lds_dwordx4 v[220:221], off
	v_lshl_add_u64 v[220:221], s[48:49], 0, v[190:191]
	s_mov_b32 m0, s23
	s_nop 0
	global_load_lds_dwordx4 v[220:221], off
	s_waitcnt vmcnt(8) lgkmcnt(0)
	s_setprio 1
	s_barrier
	v_mfma_f32_16x16x32_bf16 v[144:147], v[108:111], v[164:167], v[144:147]
	v_mfma_f32_16x16x32_bf16 v[140:143], v[128:131], v[164:167], v[140:143]
	v_mfma_f32_16x16x32_bf16 v[120:123], v[108:111], v[172:175], v[120:123]
	v_mfma_f32_16x16x32_bf16 v[116:119], v[128:131], v[172:175], v[116:119]
	v_mfma_f32_16x16x32_bf16 v[96:99], v[108:111], v[180:183], v[96:99]
	v_mfma_f32_16x16x32_bf16 v[92:95], v[128:131], v[180:183], v[92:95]
	v_mfma_f32_16x16x32_bf16 v[80:83], v[108:111], v[206:209], v[80:83]
	v_mfma_f32_16x16x32_bf16 v[76:79], v[128:131], v[206:209], v[76:79]
	v_mfma_f32_16x16x32_bf16 v[144:147], v[112:115], v[168:171], v[144:147]
	v_mfma_f32_16x16x32_bf16 v[140:143], v[136:139], v[168:171], v[140:143]
	v_mfma_f32_16x16x32_bf16 v[120:123], v[112:115], v[176:179], v[120:123]
	v_mfma_f32_16x16x32_bf16 v[116:119], v[136:139], v[176:179], v[116:119]
	v_mfma_f32_16x16x32_bf16 v[96:99], v[112:115], v[184:187], v[96:99]
	v_mfma_f32_16x16x32_bf16 v[92:95], v[136:139], v[184:187], v[92:95]
	v_mfma_f32_16x16x32_bf16 v[80:83], v[112:115], v[210:213], v[80:83]
	v_mfma_f32_16x16x32_bf16 v[76:79], v[136:139], v[210:213], v[76:79]
	v_mfma_f32_16x16x32_bf16 v[132:135], v[148:151], v[164:167], v[132:135]
	v_mfma_f32_16x16x32_bf16 v[124:127], v[156:159], v[164:167], v[124:127]
	v_mfma_f32_16x16x32_bf16 v[104:107], v[148:151], v[172:175], v[104:107]
	v_mfma_f32_16x16x32_bf16 v[100:103], v[156:159], v[172:175], v[100:103]
	v_mfma_f32_16x16x32_bf16 v[88:91], v[148:151], v[180:183], v[88:91]
	v_mfma_f32_16x16x32_bf16 v[84:87], v[156:159], v[180:183], v[84:87]
	v_mfma_f32_16x16x32_bf16 v[72:75], v[148:151], v[206:209], v[72:75]
	v_mfma_f32_16x16x32_bf16 v[68:71], v[156:159], v[206:209], v[68:71]
	v_mfma_f32_16x16x32_bf16 v[132:135], v[152:155], v[168:171], v[132:135]
	v_mfma_f32_16x16x32_bf16 v[124:127], v[160:163], v[168:171], v[124:127]
	v_mfma_f32_16x16x32_bf16 v[104:107], v[152:155], v[176:179], v[104:107]
	v_mfma_f32_16x16x32_bf16 v[100:103], v[160:163], v[176:179], v[100:103]
	v_mfma_f32_16x16x32_bf16 v[88:91], v[152:155], v[184:187], v[88:91]
	v_mfma_f32_16x16x32_bf16 v[84:87], v[160:163], v[184:187], v[84:87]
	v_mfma_f32_16x16x32_bf16 v[72:75], v[152:155], v[210:213], v[72:75]
	v_mfma_f32_16x16x32_bf16 v[68:71], v[160:163], v[210:213], v[68:71]
	s_barrier
	s_setprio 0
	s_add_i32 s48, s60, s4
	v_lshl_add_u64 v[198:199], v[198:199], 0, s[66:67]
	s_mov_b32 m0, s48
	ds_read_b128 v[164:167], v234 offset:49152
	ds_read_b128 v[168:171], v234 offset:50176
	ds_read_b128 v[172:175], v234 offset:51200
	ds_read_b128 v[176:179], v234 offset:52224
	ds_read_b128 v[180:183], v234 offset:53248
	ds_read_b128 v[184:187], v234 offset:54272
	ds_read_b128 v[206:209], v234 offset:55296
	ds_read_b128 v[210:213], v234 offset:56320
	global_load_lds_dwordx4 v[198:199], off
	s_add_i32 m0, s48, 0x2000
	s_add_u32 s48, s68, 0x160080
	v_lshl_add_u64 v[198:199], v[214:215], 0, s[66:67]
	s_addc_u32 s49, s69, 0
	s_add_i32 s60, s61, s4
	global_load_lds_dwordx4 v[198:199], off
	v_lshl_add_u64 v[198:199], s[48:49], 0, v[200:201]
	s_mov_b32 m0, s60
	s_nop 0
	global_load_lds_dwordx4 v[198:199], off
	v_lshl_add_u64 v[198:199], s[48:49], 0, v[188:189]
	s_add_i32 m0, s60, 0x2000
	s_nop 0
	global_load_lds_dwordx4 v[198:199], off
	v_lshl_add_u64 v[198:199], v[216:217], 0, s[66:67]
	s_mov_b32 m0, s54
	s_nop 0
	global_load_lds_dwordx4 v[198:199], off
	v_lshl_add_u64 v[198:199], v[218:219], 0, s[66:67]
	s_mov_b32 m0, s55
	s_nop 0
	global_load_lds_dwordx4 v[198:199], off
	s_waitcnt vmcnt(8) lgkmcnt(0)
	s_setprio 1
	s_barrier
	v_mfma_f32_16x16x32_bf16 v[64:67], v[108:111], v[164:167], v[64:67]
	v_mfma_f32_16x16x32_bf16 v[60:63], v[128:131], v[164:167], v[60:63]
	v_mfma_f32_16x16x32_bf16 v[48:51], v[108:111], v[172:175], v[48:51]
	v_mfma_f32_16x16x32_bf16 v[44:47], v[128:131], v[172:175], v[44:47]
	v_mfma_f32_16x16x32_bf16 v[32:35], v[108:111], v[180:183], v[32:35]
	v_mfma_f32_16x16x32_bf16 v[28:31], v[128:131], v[180:183], v[28:31]
	v_mfma_f32_16x16x32_bf16 v[16:19], v[108:111], v[206:209], v[16:19]
	v_mfma_f32_16x16x32_bf16 v[12:15], v[128:131], v[206:209], v[12:15]
	v_mfma_f32_16x16x32_bf16 v[64:67], v[112:115], v[168:171], v[64:67]
	v_mfma_f32_16x16x32_bf16 v[60:63], v[136:139], v[168:171], v[60:63]
	v_mfma_f32_16x16x32_bf16 v[48:51], v[112:115], v[176:179], v[48:51]
	v_mfma_f32_16x16x32_bf16 v[44:47], v[136:139], v[176:179], v[44:47]
	v_mfma_f32_16x16x32_bf16 v[32:35], v[112:115], v[184:187], v[32:35]
	v_mfma_f32_16x16x32_bf16 v[28:31], v[136:139], v[184:187], v[28:31]
	v_mfma_f32_16x16x32_bf16 v[16:19], v[112:115], v[210:213], v[16:19]
	v_mfma_f32_16x16x32_bf16 v[12:15], v[136:139], v[210:213], v[12:15]
	v_mfma_f32_16x16x32_bf16 v[56:59], v[148:151], v[164:167], v[56:59]
	v_mfma_f32_16x16x32_bf16 v[52:55], v[156:159], v[164:167], v[52:55]
	v_mfma_f32_16x16x32_bf16 v[40:43], v[148:151], v[172:175], v[40:43]
	v_mfma_f32_16x16x32_bf16 v[36:39], v[156:159], v[172:175], v[36:39]
	v_mfma_f32_16x16x32_bf16 v[24:27], v[148:151], v[180:183], v[24:27]
	v_mfma_f32_16x16x32_bf16 v[20:23], v[156:159], v[180:183], v[20:23]
	v_mfma_f32_16x16x32_bf16 v[8:11], v[148:151], v[206:209], v[8:11]
	v_mfma_f32_16x16x32_bf16 v[4:7], v[156:159], v[206:209], v[4:7]
	v_mfma_f32_16x16x32_bf16 v[56:59], v[152:155], v[168:171], v[56:59]
	v_mfma_f32_16x16x32_bf16 v[52:55], v[160:163], v[168:171], v[52:55]
	v_mfma_f32_16x16x32_bf16 v[40:43], v[152:155], v[176:179], v[40:43]
	v_mfma_f32_16x16x32_bf16 v[36:39], v[160:163], v[176:179], v[36:39]
	v_mfma_f32_16x16x32_bf16 v[24:27], v[152:155], v[184:187], v[24:27]
	v_mfma_f32_16x16x32_bf16 v[20:23], v[160:163], v[184:187], v[20:23]
	v_mfma_f32_16x16x32_bf16 v[8:11], v[152:155], v[210:213], v[8:11]
	v_mfma_f32_16x16x32_bf16 v[4:7], v[160:163], v[210:213], v[4:7]
	s_barrier
	s_setprio 0
	s_add_i32 s79, s79, 2
	s_add_u32 s77, s77, 0x100
	s_addc_u32 s78, s78, 0
	s_cmpk_gt_u32 s79, 0x55
	s_mov_b64 s[60:61], s[62:63]
	s_cbranch_scc0 .LBB0_1212
	s_and_b64 vcc, exec, s[12:13]
	s_cbranch_vccz .LBB0_1215
	s_barrier

.LBB0_1254:
	s_add_u32 s60, s50, 0x100
	s_addc_u32 s61, s51, 0
	s_add_i32 s48, 0, 0x10000
	s_cmpk_eq_i32 s77, 0x54
	s_cselect_b32 s69, s7, s61
	s_cselect_b32 s68, s6, s60
	s_cselect_b32 s63, s25, s76
	s_cselect_b32 s62, s24, s75
	s_add_i32 s78, 0, 0x14000
	ds_read_b128 v[108:111], v251
	ds_read_b128 v[112:115], v251 offset:1024
	ds_read_b128 v[128:131], v251 offset:2048
	ds_read_b128 v[136:139], v251 offset:3072
	ds_read_b128 v[148:151], v251 offset:16384
	ds_read_b128 v[152:155], v251 offset:17408
	ds_read_b128 v[156:159], v251 offset:18432
	ds_read_b128 v[160:163], v251 offset:19456
	v_lshl_add_u64 v[198:199], s[50:51], 0, v[196:197]
	s_add_i32 m0, s21, 0xc000
	ds_read_b128 v[164:167], v234
	ds_read_b128 v[168:171], v234 offset:1024
	ds_read_b128 v[172:175], v234 offset:2048
	ds_read_b128 v[176:179], v234 offset:3072
	ds_read_b128 v[180:183], v234 offset:4096
	ds_read_b128 v[184:187], v234 offset:5120
	ds_read_b128 v[206:209], v234 offset:6144
	ds_read_b128 v[210:213], v234 offset:7168
	global_load_lds_dwordx4 v[198:199], off
	v_lshl_add_u64 v[198:199], s[50:51], 0, v[194:195]
	s_add_i32 m0, s21, 0xe000
	s_nop 0
	global_load_lds_dwordx4 v[198:199], off
	s_waitcnt vmcnt(8) lgkmcnt(0)
	s_setprio 1
	s_barrier
	v_mfma_f32_16x16x32_bf16 v[144:147], v[108:111], v[164:167], v[144:147]
	v_mfma_f32_16x16x32_bf16 v[140:143], v[128:131], v[164:167], v[140:143]
	v_mfma_f32_16x16x32_bf16 v[120:123], v[108:111], v[172:175], v[120:123]
	v_mfma_f32_16x16x32_bf16 v[116:119], v[128:131], v[172:175], v[116:119]
	v_mfma_f32_16x16x32_bf16 v[96:99], v[108:111], v[180:183], v[96:99]
	v_mfma_f32_16x16x32_bf16 v[92:95], v[128:131], v[180:183], v[92:95]
	v_mfma_f32_16x16x32_bf16 v[80:83], v[108:111], v[206:209], v[80:83]
	v_mfma_f32_16x16x32_bf16 v[76:79], v[128:131], v[206:209], v[76:79]
	v_mfma_f32_16x16x32_bf16 v[144:147], v[112:115], v[168:171], v[144:147]
	v_mfma_f32_16x16x32_bf16 v[140:143], v[136:139], v[168:171], v[140:143]
	v_mfma_f32_16x16x32_bf16 v[120:123], v[112:115], v[176:179], v[120:123]
	v_mfma_f32_16x16x32_bf16 v[116:119], v[136:139], v[176:179], v[116:119]
	v_mfma_f32_16x16x32_bf16 v[96:99], v[112:115], v[184:187], v[96:99]
	v_mfma_f32_16x16x32_bf16 v[92:95], v[136:139], v[184:187], v[92:95]
	v_mfma_f32_16x16x32_bf16 v[80:83], v[112:115], v[210:213], v[80:83]
	v_mfma_f32_16x16x32_bf16 v[76:79], v[136:139], v[210:213], v[76:79]
	v_mfma_f32_16x16x32_bf16 v[132:135], v[148:151], v[164:167], v[132:135]
	v_mfma_f32_16x16x32_bf16 v[124:127], v[156:159], v[164:167], v[124:127]
	v_mfma_f32_16x16x32_bf16 v[104:107], v[148:151], v[172:175], v[104:107]
	v_mfma_f32_16x16x32_bf16 v[100:103], v[156:159], v[172:175], v[100:103]
	v_mfma_f32_16x16x32_bf16 v[88:91], v[148:151], v[180:183], v[88:91]
	v_mfma_f32_16x16x32_bf16 v[84:87], v[156:159], v[180:183], v[84:87]
	v_mfma_f32_16x16x32_bf16 v[72:75], v[148:151], v[206:209], v[72:75]
	v_mfma_f32_16x16x32_bf16 v[68:71], v[156:159], v[206:209], v[68:71]
	v_mfma_f32_16x16x32_bf16 v[132:135], v[152:155], v[168:171], v[132:135]
	v_mfma_f32_16x16x32_bf16 v[124:127], v[160:163], v[168:171], v[124:127]
	v_mfma_f32_16x16x32_bf16 v[104:107], v[152:155], v[176:179], v[104:107]
	v_mfma_f32_16x16x32_bf16 v[100:103], v[160:163], v[176:179], v[100:103]
	v_mfma_f32_16x16x32_bf16 v[88:91], v[152:155], v[184:187], v[88:91]
	v_mfma_f32_16x16x32_bf16 v[84:87], v[160:163], v[184:187], v[84:87]
	v_mfma_f32_16x16x32_bf16 v[72:75], v[152:155], v[210:213], v[72:75]
	v_mfma_f32_16x16x32_bf16 v[68:71], v[160:163], v[210:213], v[68:71]
	s_barrier
	s_setprio 0
	s_add_i32 s48, s48, s20
	v_lshl_add_u64 v[198:199], s[62:63], 0, v[200:201]
	s_mov_b32 m0, s48
	ds_read_b128 v[164:167], v234 offset:16384
	ds_read_b128 v[168:171], v234 offset:17408
	ds_read_b128 v[172:175], v234 offset:18432
	ds_read_b128 v[176:179], v234 offset:19456
	ds_read_b128 v[180:183], v234 offset:20480
	ds_read_b128 v[184:187], v234 offset:21504
	ds_read_b128 v[206:209], v234 offset:22528
	ds_read_b128 v[210:213], v234 offset:23552
	global_load_lds_dwordx4 v[198:199], off
	s_add_i32 m0, s48, 0x2000
	s_add_u32 s48, s62, 0x160000
	v_lshl_add_u64 v[214:215], s[62:63], 0, v[188:189]
	s_addc_u32 s49, s63, 0
	s_add_i32 s50, s78, s20
	global_load_lds_dwordx4 v[214:215], off
	v_lshl_add_u64 v[216:217], s[48:49], 0, v[200:201]
	s_mov_b32 m0, s50
	v_lshl_add_u64 v[218:219], s[68:69], 0, v[190:191]
	global_load_lds_dwordx4 v[216:217], off
	v_lshl_add_u64 v[216:217], s[48:49], 0, v[188:189]
	s_add_i32 m0, s50, 0x2000
	s_nop 0
	global_load_lds_dwordx4 v[216:217], off
	v_lshl_add_u64 v[216:217], s[68:69], 0, v[192:193]
	s_mov_b32 m0, s21
	s_nop 0
	global_load_lds_dwordx4 v[216:217], off
	s_mov_b32 m0, s23
	s_nop 0
	global_load_lds_dwordx4 v[218:219], off
	s_waitcnt vmcnt(8) lgkmcnt(0)
	s_setprio 1
	s_barrier
	v_mfma_f32_16x16x32_bf16 v[64:67], v[108:111], v[164:167], v[64:67]
	v_mfma_f32_16x16x32_bf16 v[60:63], v[128:131], v[164:167], v[60:63]
	v_mfma_f32_16x16x32_bf16 v[48:51], v[108:111], v[172:175], v[48:51]
	v_mfma_f32_16x16x32_bf16 v[44:47], v[128:131], v[172:175], v[44:47]
	v_mfma_f32_16x16x32_bf16 v[32:35], v[108:111], v[180:183], v[32:35]
	v_mfma_f32_16x16x32_bf16 v[28:31], v[128:131], v[180:183], v[28:31]
	v_mfma_f32_16x16x32_bf16 v[16:19], v[108:111], v[206:209], v[16:19]
	v_mfma_f32_16x16x32_bf16 v[12:15], v[128:131], v[206:209], v[12:15]
	v_mfma_f32_16x16x32_bf16 v[64:67], v[112:115], v[168:171], v[64:67]
	v_mfma_f32_16x16x32_bf16 v[60:63], v[136:139], v[168:171], v[60:63]
	v_mfma_f32_16x16x32_bf16 v[48:51], v[112:115], v[176:179], v[48:51]
	v_mfma_f32_16x16x32_bf16 v[44:47], v[136:139], v[176:179], v[44:47]
	v_mfma_f32_16x16x32_bf16 v[32:35], v[112:115], v[184:187], v[32:35]
	v_mfma_f32_16x16x32_bf16 v[28:31], v[136:139], v[184:187], v[28:31]
	v_mfma_f32_16x16x32_bf16 v[16:19], v[112:115], v[210:213], v[16:19]
	v_mfma_f32_16x16x32_bf16 v[12:15], v[136:139], v[210:213], v[12:15]
	v_mfma_f32_16x16x32_bf16 v[56:59], v[148:151], v[164:167], v[56:59]
	v_mfma_f32_16x16x32_bf16 v[52:55], v[156:159], v[164:167], v[52:55]
	v_mfma_f32_16x16x32_bf16 v[40:43], v[148:151], v[172:175], v[40:43]
	v_mfma_f32_16x16x32_bf16 v[36:39], v[156:159], v[172:175], v[36:39]
	v_mfma_f32_16x16x32_bf16 v[24:27], v[148:151], v[180:183], v[24:27]
	v_mfma_f32_16x16x32_bf16 v[20:23], v[156:159], v[180:183], v[20:23]
	v_mfma_f32_16x16x32_bf16 v[8:11], v[148:151], v[206:209], v[8:11]
	v_mfma_f32_16x16x32_bf16 v[4:7], v[156:159], v[206:209], v[4:7]
	v_mfma_f32_16x16x32_bf16 v[56:59], v[152:155], v[168:171], v[56:59]
	v_mfma_f32_16x16x32_bf16 v[52:55], v[160:163], v[168:171], v[52:55]
	v_mfma_f32_16x16x32_bf16 v[40:43], v[152:155], v[176:179], v[40:43]
	v_mfma_f32_16x16x32_bf16 v[36:39], v[160:163], v[176:179], v[36:39]
	v_mfma_f32_16x16x32_bf16 v[24:27], v[152:155], v[184:187], v[24:27]
	v_mfma_f32_16x16x32_bf16 v[20:23], v[160:163], v[184:187], v[20:23]
	v_mfma_f32_16x16x32_bf16 v[8:11], v[152:155], v[210:213], v[8:11]
	v_mfma_f32_16x16x32_bf16 v[4:7], v[160:163], v[210:213], v[4:7]
	s_barrier
	s_setprio 0
	s_add_i32 s50, 0, 0x18000
	s_add_i32 s51, 0, 0x1c000
	ds_read_b128 v[108:111], v251 offset:32768
	ds_read_b128 v[112:115], v251 offset:33792
	ds_read_b128 v[128:131], v251 offset:34816
	ds_read_b128 v[136:139], v251 offset:35840
	ds_read_b128 v[148:151], v251 offset:49152
	ds_read_b128 v[152:155], v251 offset:50176
	ds_read_b128 v[156:159], v251 offset:51200
	ds_read_b128 v[160:163], v251 offset:52224
	s_add_u32 s48, s68, 0x160000
	s_addc_u32 s49, s69, 0
	s_mov_b32 m0, s42
	v_lshl_add_u64 v[220:221], s[48:49], 0, v[192:193]
	ds_read_b128 v[164:167], v234 offset:32768
	ds_read_b128 v[168:171], v234 offset:33792
	ds_read_b128 v[172:175], v234 offset:34816
	ds_read_b128 v[176:179], v234 offset:35840
	ds_read_b128 v[180:183], v234 offset:36864
	ds_read_b128 v[184:187], v234 offset:37888
	ds_read_b128 v[206:209], v234 offset:38912
	ds_read_b128 v[210:213], v234 offset:39936
	global_load_lds_dwordx4 v[220:221], off
	v_lshl_add_u64 v[220:221], s[48:49], 0, v[190:191]
	s_mov_b32 m0, s52
	s_nop 0
	global_load_lds_dwordx4 v[220:221], off
	s_waitcnt vmcnt(8) lgkmcnt(0)
	s_setprio 1
	s_barrier
	v_mfma_f32_16x16x32_bf16 v[144:147], v[108:111], v[164:167], v[144:147]
	v_mfma_f32_16x16x32_bf16 v[140:143], v[128:131], v[164:167], v[140:143]
	v_mfma_f32_16x16x32_bf16 v[120:123], v[108:111], v[172:175], v[120:123]
	v_mfma_f32_16x16x32_bf16 v[116:119], v[128:131], v[172:175], v[116:119]
	v_mfma_f32_16x16x32_bf16 v[96:99], v[108:111], v[180:183], v[96:99]
	v_mfma_f32_16x16x32_bf16 v[92:95], v[128:131], v[180:183], v[92:95]
	v_mfma_f32_16x16x32_bf16 v[80:83], v[108:111], v[206:209], v[80:83]
	v_mfma_f32_16x16x32_bf16 v[76:79], v[128:131], v[206:209], v[76:79]
	v_mfma_f32_16x16x32_bf16 v[144:147], v[112:115], v[168:171], v[144:147]
	v_mfma_f32_16x16x32_bf16 v[140:143], v[136:139], v[168:171], v[140:143]
	v_mfma_f32_16x16x32_bf16 v[120:123], v[112:115], v[176:179], v[120:123]
	v_mfma_f32_16x16x32_bf16 v[116:119], v[136:139], v[176:179], v[116:119]
	v_mfma_f32_16x16x32_bf16 v[96:99], v[112:115], v[184:187], v[96:99]
	v_mfma_f32_16x16x32_bf16 v[92:95], v[136:139], v[184:187], v[92:95]
	v_mfma_f32_16x16x32_bf16 v[80:83], v[112:115], v[210:213], v[80:83]
	v_mfma_f32_16x16x32_bf16 v[76:79], v[136:139], v[210:213], v[76:79]
	v_mfma_f32_16x16x32_bf16 v[132:135], v[148:151], v[164:167], v[132:135]
	v_mfma_f32_16x16x32_bf16 v[124:127], v[156:159], v[164:167], v[124:127]
	v_mfma_f32_16x16x32_bf16 v[104:107], v[148:151], v[172:175], v[104:107]
	v_mfma_f32_16x16x32_bf16 v[100:103], v[156:159], v[172:175], v[100:103]
	v_mfma_f32_16x16x32_bf16 v[88:91], v[148:151], v[180:183], v[88:91]
	v_mfma_f32_16x16x32_bf16 v[84:87], v[156:159], v[180:183], v[84:87]
	v_mfma_f32_16x16x32_bf16 v[72:75], v[148:151], v[206:209], v[72:75]
	v_mfma_f32_16x16x32_bf16 v[68:71], v[156:159], v[206:209], v[68:71]
	v_mfma_f32_16x16x32_bf16 v[132:135], v[152:155], v[168:171], v[132:135]
	v_mfma_f32_16x16x32_bf16 v[124:127], v[160:163], v[168:171], v[124:127]
	v_mfma_f32_16x16x32_bf16 v[104:107], v[152:155], v[176:179], v[104:107]
	v_mfma_f32_16x16x32_bf16 v[100:103], v[160:163], v[176:179], v[100:103]
	v_mfma_f32_16x16x32_bf16 v[88:91], v[152:155], v[184:187], v[88:91]
	v_mfma_f32_16x16x32_bf16 v[84:87], v[160:163], v[184:187], v[84:87]
	v_mfma_f32_16x16x32_bf16 v[72:75], v[152:155], v[210:213], v[72:75]
	v_mfma_f32_16x16x32_bf16 v[68:71], v[160:163], v[210:213], v[68:71]
	s_barrier
	s_setprio 0
	s_add_i32 s48, s50, s20
	v_lshl_add_u64 v[198:199], v[198:199], 0, s[66:67]
	s_mov_b32 m0, s48
	ds_read_b128 v[164:167], v234 offset:49152
	ds_read_b128 v[168:171], v234 offset:50176
	ds_read_b128 v[172:175], v234 offset:51200
	ds_read_b128 v[176:179], v234 offset:52224
	ds_read_b128 v[180:183], v234 offset:53248
	ds_read_b128 v[184:187], v234 offset:54272
	ds_read_b128 v[206:209], v234 offset:55296
	ds_read_b128 v[210:213], v234 offset:56320
	global_load_lds_dwordx4 v[198:199], off
	s_add_i32 m0, s48, 0x2000
	s_add_u32 s48, s62, 0x160080
	v_lshl_add_u64 v[198:199], v[214:215], 0, s[66:67]
	s_addc_u32 s49, s63, 0
	s_add_i32 s50, s51, s20
	global_load_lds_dwordx4 v[198:199], off
	v_lshl_add_u64 v[198:199], s[48:49], 0, v[200:201]
	s_mov_b32 m0, s50
	s_nop 0
	global_load_lds_dwordx4 v[198:199], off
	v_lshl_add_u64 v[198:199], s[48:49], 0, v[188:189]
	s_add_i32 m0, s50, 0x2000
	s_nop 0
	global_load_lds_dwordx4 v[198:199], off
	v_lshl_add_u64 v[198:199], v[216:217], 0, s[66:67]
	s_mov_b32 m0, s56
	s_nop 0
	global_load_lds_dwordx4 v[198:199], off
	v_lshl_add_u64 v[198:199], v[218:219], 0, s[66:67]
	s_mov_b32 m0, s58
	s_nop 0
	global_load_lds_dwordx4 v[198:199], off
	s_waitcnt vmcnt(8) lgkmcnt(0)
	s_setprio 1
	s_barrier
	v_mfma_f32_16x16x32_bf16 v[64:67], v[108:111], v[164:167], v[64:67]
	v_mfma_f32_16x16x32_bf16 v[60:63], v[128:131], v[164:167], v[60:63]
	v_mfma_f32_16x16x32_bf16 v[48:51], v[108:111], v[172:175], v[48:51]
	v_mfma_f32_16x16x32_bf16 v[44:47], v[128:131], v[172:175], v[44:47]
	v_mfma_f32_16x16x32_bf16 v[32:35], v[108:111], v[180:183], v[32:35]
	v_mfma_f32_16x16x32_bf16 v[28:31], v[128:131], v[180:183], v[28:31]
	v_mfma_f32_16x16x32_bf16 v[16:19], v[108:111], v[206:209], v[16:19]
	v_mfma_f32_16x16x32_bf16 v[12:15], v[128:131], v[206:209], v[12:15]
	v_mfma_f32_16x16x32_bf16 v[64:67], v[112:115], v[168:171], v[64:67]
	v_mfma_f32_16x16x32_bf16 v[60:63], v[136:139], v[168:171], v[60:63]
	v_mfma_f32_16x16x32_bf16 v[48:51], v[112:115], v[176:179], v[48:51]
	v_mfma_f32_16x16x32_bf16 v[44:47], v[136:139], v[176:179], v[44:47]
	v_mfma_f32_16x16x32_bf16 v[32:35], v[112:115], v[184:187], v[32:35]
	v_mfma_f32_16x16x32_bf16 v[28:31], v[136:139], v[184:187], v[28:31]
	v_mfma_f32_16x16x32_bf16 v[16:19], v[112:115], v[210:213], v[16:19]
	v_mfma_f32_16x16x32_bf16 v[12:15], v[136:139], v[210:213], v[12:15]
	v_mfma_f32_16x16x32_bf16 v[56:59], v[148:151], v[164:167], v[56:59]
	v_mfma_f32_16x16x32_bf16 v[52:55], v[156:159], v[164:167], v[52:55]
	v_mfma_f32_16x16x32_bf16 v[40:43], v[148:151], v[172:175], v[40:43]
	v_mfma_f32_16x16x32_bf16 v[36:39], v[156:159], v[172:175], v[36:39]
	v_mfma_f32_16x16x32_bf16 v[24:27], v[148:151], v[180:183], v[24:27]
	v_mfma_f32_16x16x32_bf16 v[20:23], v[156:159], v[180:183], v[20:23]
	v_mfma_f32_16x16x32_bf16 v[8:11], v[148:151], v[206:209], v[8:11]
	v_mfma_f32_16x16x32_bf16 v[4:7], v[156:159], v[206:209], v[4:7]
	v_mfma_f32_16x16x32_bf16 v[56:59], v[152:155], v[168:171], v[56:59]
	v_mfma_f32_16x16x32_bf16 v[52:55], v[160:163], v[168:171], v[52:55]
	v_mfma_f32_16x16x32_bf16 v[40:43], v[152:155], v[176:179], v[40:43]
	v_mfma_f32_16x16x32_bf16 v[36:39], v[160:163], v[176:179], v[36:39]
	v_mfma_f32_16x16x32_bf16 v[24:27], v[152:155], v[184:187], v[24:27]
	v_mfma_f32_16x16x32_bf16 v[20:23], v[160:163], v[184:187], v[20:23]
	v_mfma_f32_16x16x32_bf16 v[8:11], v[152:155], v[210:213], v[8:11]
	v_mfma_f32_16x16x32_bf16 v[4:7], v[160:163], v[210:213], v[4:7]
	s_barrier
	s_setprio 0
	s_add_i32 s77, s77, 2
	s_add_u32 s75, s75, 0x100
	s_addc_u32 s76, s76, 0
	s_cmpk_gt_u32 s77, 0x55
	s_mov_b64 s[50:51], s[60:61]
	s_cbranch_scc0 .LBB0_1254
	s_and_b64 vcc, exec, s[12:13]
	s_cbranch_vccz .LBB0_1257
	s_barrier
